# v12 + GEMM load segments issue the LDS-DMA group before the fragment ds_reads (earliest prefetch issue)
# baseline (speedup 1.0000x reference)
; #define PG8_STAGE(bufoff, gbase, voff) do { _Pragma("unroll") for (int _i = 0; _i < 2; ++_i) \
;         __builtin_amdgcn_global_load_lds((const unsigned*)((const char*)(gbase) + (voff)[_i]), (LAS unsigned*)(lds + (bufoff) + ldsw + _i * 8192), 16, 0, 0); } while (0)
; #define PG8_LDA(dst, b, h) do { _Pragma("unroll") for (int m = 0; m < 4; ++m) _Pragma("unroll") for (int k = 0; k < 2; ++k) dst[m][k] = *(const LAS bf16x8*)(lds + PG8_SA(b, h) + aoff + m * 2048 + k * 1024); } while (0)
; #define PG8_LDB(dst, b, h) do { _Pragma("unroll") for (int n = 0; n < 2; ++n) _Pragma("unroll") for (int k = 0; k < 2; ++k) dst[n][k] = *(const LAS bf16x8*)(lds + PG8_SB(b, h) + boff + n * 2048 + k * 1024); } while (0)
; #define PG8_MMA(ai, bj, At, Bt) do { __builtin_amdgcn_s_setprio(1); _Pragma("unroll") for (int m = 0; m < 4; ++m) _Pragma("unroll") for (int n = 0; n < 2; ++n) _Pragma("unroll") for (int k = 0; k < 2; ++k) \
;         acc[ai][bj][m][n] = __builtin_amdgcn_mfma_f32_16x16x32_bf16(Bt[n][k], At[m][k], acc[ai][bj][m][n], 0, 0, 0); __builtin_amdgcn_s_setprio(0); } while (0)
; #define PG8_WAIT_V(n) asm volatile("s_waitcnt vmcnt(" #n ")" ::: "memory")
; #define PG8_WAIT_L(n) asm volatile("s_waitcnt lgkmcnt(" #n ")" ::: "memory")
; #define PG8_BAR __builtin_amdgcn_s_barrier()
; template <class Epi, class Sched, int LDA, int LDB, bool ALIGN_EPI = true>
; __device__ __forceinline__ void gemm_phase(LAS unsigned char* lds, const Gemm g, const Sched& S, const Epi& E, int wave) {
;     ...
;         for (int t = 0; t < nt; t += 2) {
;             const bool last = (t == nt - 2);
;             const char* a1 = cA + (size_t)(t + 1) * kstep;
;             const char* a2 = last ? nA : cA + (size_t)(t + 2) * kstep; const char* b2 = last ? nB : cB + (size_t)(t + 2) * kstep;
;             const char* a3 = a2 + kstep; const char* b3 = b2 + kstep;
;             PG8_LDB(B0, 0, 0); PG8_LDB(B1, 0, 1); PG8_SCHED; PG8_LDA(At, 0, 0); PG8_STAGE(PG8_SA(1, 1), a1 + hstepA, voffA);
;             PG8_WAIT_V(8); PG8_WAIT_L(0); PG8_BAR; PG8_MMA(0, 0, At, B0); PG8_MMA(0, 1, At, B1); PG8_BAR; PG8_SCHED;
;             PG8_LDA(At, 0, 1); PG8_STAGE(PG8_SB(0, 0), b2, voffB); PG8_STAGE(PG8_SB(0, 1), b2 + hstepB, voffB); PG8_STAGE(PG8_SA(0, 0), a2, voffA);
;             PG8_WAIT_V(8); PG8_WAIT_L(0); PG8_BAR; PG8_MMA(1, 0, At, B0); PG8_MMA(1, 1, At, B1); PG8_BAR; PG8_SCHED;
.LBB0_485:
	s_add_u32 s24, s18, 0x100
	s_addc_u32 s25, s19, 0
	s_add_i32 s54, 0, 0x10000
	s_cmp_eq_u32 s53, 28
	s_cselect_b32 s35, s3, s25
	s_cselect_b32 s34, s2, s24
	s_cselect_b32 s29, s1, s45
	s_cselect_b32 s28, s17, s44
	s_add_i32 s55, 0, 0x14000
	v_lshl_add_u64 v[140:141], s[18:19], 0, v[136:137]
	s_add_i32 m0, s38, 0xc000
	s_nop 0
	global_load_lds_dwordx4 v[140:141], off
	v_lshl_add_u64 v[140:141], s[18:19], 0, v[138:139]
	s_add_i32 m0, s38, 0xe000
	s_nop 0
	global_load_lds_dwordx4 v[140:141], off
	v_add_u32_e32 v140, s54, v143
	ds_read_b128 v[146:149], v140
	ds_read_b128 v[150:153], v140 offset:1024
	ds_read_b128 v[154:157], v140 offset:2048
	ds_read_b128 v[158:161], v140 offset:3072
	v_add_u32_e32 v140, s55, v143
	ds_read_b128 v[162:165], v140
	ds_read_b128 v[166:169], v140 offset:1024
	ds_read_b128 v[170:173], v140 offset:2048
	ds_read_b128 v[180:183], v140 offset:3072
	ds_read_b128 v[184:187], v145
	ds_read_b128 v[188:191], v145 offset:1024
	ds_read_b128 v[192:195], v145 offset:2048
	ds_read_b128 v[196:199], v145 offset:3072
	ds_read_b128 v[200:203], v145 offset:4096
	ds_read_b128 v[204:207], v145 offset:5120
	ds_read_b128 v[208:211], v145 offset:6144
	ds_read_b128 v[212:215], v145 offset:7168
	s_waitcnt vmcnt(8)
	s_waitcnt lgkmcnt(0)
	s_setprio 1
	s_barrier
	v_mfma_f32_16x16x32_bf16 v[126:129], v[146:149], v[184:187], v[126:129]
	v_mfma_f32_16x16x32_bf16 v[118:121], v[154:157], v[184:187], v[118:121]
	v_mfma_f32_16x16x32_bf16 v[110:113], v[146:149], v[192:195], v[110:113]
	v_mfma_f32_16x16x32_bf16 v[102:105], v[154:157], v[192:195], v[102:105]
	v_mfma_f32_16x16x32_bf16 v[94:97], v[146:149], v[200:203], v[94:97]
	v_mfma_f32_16x16x32_bf16 v[86:89], v[154:157], v[200:203], v[86:89]
	v_mfma_f32_16x16x32_bf16 v[78:81], v[146:149], v[208:211], v[78:81]
	v_mfma_f32_16x16x32_bf16 v[70:73], v[154:157], v[208:211], v[70:73]
	v_mfma_f32_16x16x32_bf16 v[126:129], v[150:153], v[188:191], v[126:129]
	v_mfma_f32_16x16x32_bf16 v[118:121], v[158:161], v[188:191], v[118:121]
	v_mfma_f32_16x16x32_bf16 v[110:113], v[150:153], v[196:199], v[110:113]
	v_mfma_f32_16x16x32_bf16 v[102:105], v[158:161], v[196:199], v[102:105]
	v_mfma_f32_16x16x32_bf16 v[94:97], v[150:153], v[204:207], v[94:97]
	v_mfma_f32_16x16x32_bf16 v[86:89], v[158:161], v[204:207], v[86:89]
	v_mfma_f32_16x16x32_bf16 v[78:81], v[150:153], v[212:215], v[78:81]
	v_mfma_f32_16x16x32_bf16 v[70:73], v[158:161], v[212:215], v[70:73]
	v_mfma_f32_16x16x32_bf16 v[122:125], v[162:165], v[184:187], v[122:125]
	v_mfma_f32_16x16x32_bf16 v[114:117], v[170:173], v[184:187], v[114:117]
	v_mfma_f32_16x16x32_bf16 v[106:109], v[162:165], v[192:195], v[106:109]
	v_mfma_f32_16x16x32_bf16 v[98:101], v[170:173], v[192:195], v[98:101]
	v_mfma_f32_16x16x32_bf16 v[90:93], v[162:165], v[200:203], v[90:93]
	v_mfma_f32_16x16x32_bf16 v[82:85], v[170:173], v[200:203], v[82:85]
	v_mfma_f32_16x16x32_bf16 v[74:77], v[162:165], v[208:211], v[74:77]
	v_mfma_f32_16x16x32_bf16 v[66:69], v[170:173], v[208:211], v[66:69]
	v_mfma_f32_16x16x32_bf16 v[122:125], v[166:169], v[188:191], v[122:125]
	v_mfma_f32_16x16x32_bf16 v[114:117], v[180:183], v[188:191], v[114:117]
	v_mfma_f32_16x16x32_bf16 v[106:109], v[166:169], v[196:199], v[106:109]
	v_mfma_f32_16x16x32_bf16 v[98:101], v[180:183], v[196:199], v[98:101]
	v_mfma_f32_16x16x32_bf16 v[90:93], v[166:169], v[204:207], v[90:93]
	v_mfma_f32_16x16x32_bf16 v[82:85], v[180:183], v[204:207], v[82:85]
	v_mfma_f32_16x16x32_bf16 v[74:77], v[166:169], v[212:215], v[74:77]
	v_mfma_f32_16x16x32_bf16 v[66:69], v[180:183], v[212:215], v[66:69]
	s_barrier
	s_setprio 0
	s_add_i32 s18, s54, s5
	v_lshl_add_u64 v[140:141], s[28:29], 0, v[0:1]
	s_mov_b32 m0, s18
	s_nop 0
	global_load_lds_dwordx4 v[140:141], off
	s_add_i32 m0, s18, 0x2000
	s_add_u32 s18, s28, 0x80000
	v_lshl_add_u64 v[174:175], s[28:29], 0, v[130:131]
	s_addc_u32 s19, s29, 0
	s_add_i32 s54, s55, s5
	global_load_lds_dwordx4 v[174:175], off
	v_lshl_add_u64 v[216:217], s[18:19], 0, v[0:1]
	s_mov_b32 m0, s54
	v_lshl_add_u64 v[218:219], s[34:35], 0, v[132:133]
	global_load_lds_dwordx4 v[216:217], off
	v_lshl_add_u64 v[216:217], s[18:19], 0, v[130:131]
	s_add_i32 m0, s54, 0x2000
	s_nop 0
	global_load_lds_dwordx4 v[216:217], off
	v_lshl_add_u64 v[216:217], s[34:35], 0, v[134:135]
	s_mov_b32 m0, s38
	s_nop 0
	global_load_lds_dwordx4 v[216:217], off
	s_mov_b32 m0, s39
	s_nop 0
	global_load_lds_dwordx4 v[218:219], off
	ds_read_b128 v[184:187], v145 offset:16384
	ds_read_b128 v[188:191], v145 offset:17408
	ds_read_b128 v[192:195], v145 offset:18432
	ds_read_b128 v[196:199], v145 offset:19456
	ds_read_b128 v[200:203], v145 offset:20480
	ds_read_b128 v[204:207], v145 offset:21504
	ds_read_b128 v[208:211], v145 offset:22528
	ds_read_b128 v[212:215], v145 offset:23552
	s_waitcnt vmcnt(8)
	s_waitcnt lgkmcnt(0)
	s_setprio 1
	s_barrier
; #define PG8_STAGE(bufoff, gbase, voff) do { _Pragma("unroll") for (int _i = 0; _i < 2; ++_i) \
;         __builtin_amdgcn_global_load_lds((const unsigned*)((const char*)(gbase) + (voff)[_i]), (LAS unsigned*)(lds + (bufoff) + ldsw + _i * 8192), 16, 0, 0); } while (0)
; #define PG8_LDA(dst, b, h) do { _Pragma("unroll") for (int m = 0; m < 4; ++m) _Pragma("unroll") for (int k = 0; k < 2; ++k) dst[m][k] = *(const LAS bf16x8*)(lds + PG8_SA(b, h) + aoff + m * 2048 + k * 1024); } while (0)
; #define PG8_LDB(dst, b, h) do { _Pragma("unroll") for (int n = 0; n < 2; ++n) _Pragma("unroll") for (int k = 0; k < 2; ++k) dst[n][k] = *(const LAS bf16x8*)(lds + PG8_SB(b, h) + boff + n * 2048 + k * 1024); } while (0)
; #define PG8_MMA(ai, bj, At, Bt) do { __builtin_amdgcn_s_setprio(1); _Pragma("unroll") for (int m = 0; m < 4; ++m) _Pragma("unroll") for (int n = 0; n < 2; ++n) _Pragma("unroll") for (int k = 0; k < 2; ++k) \
;         acc[ai][bj][m][n] = __builtin_amdgcn_mfma_f32_16x16x32_bf16(Bt[n][k], At[m][k], acc[ai][bj][m][n], 0, 0, 0); __builtin_amdgcn_s_setprio(0); } while (0)
; #define PG8_WAIT_V(n) asm volatile("s_waitcnt vmcnt(" #n ")" ::: "memory")
; #define PG8_WAIT_L(n) asm volatile("s_waitcnt lgkmcnt(" #n ")" ::: "memory")
; #define PG8_BAR __builtin_amdgcn_s_barrier()
; #define PG8_SCHED __builtin_amdgcn_sched_barrier(0)
; template <class Epi, class Sched, int LDA, int LDB, bool ALIGN_EPI = true>
; __device__ __forceinline__ void gemm_phase(LAS unsigned char* lds, const Gemm g, const Sched& S, const Epi& E, int wave) {
;     ...
;             PG8_WAIT_V(8); PG8_WAIT_L(0); PG8_BAR; PG8_MMA(1, 0, At, B0); PG8_MMA(1, 1, At, B1); PG8_BAR; PG8_SCHED;
;             PG8_LDB(B0, 1, 0); PG8_LDB(B1, 1, 1); PG8_SCHED; PG8_LDA(At, 1, 0); PG8_STAGE(PG8_SA(0, 1), a2 + hstepA, voffA);
;             PG8_WAIT_V(8); PG8_WAIT_L(0); PG8_BAR; PG8_MMA(0, 0, At, B0); PG8_MMA(0, 1, At, B1); PG8_BAR; PG8_SCHED;
	v_mfma_f32_16x16x32_bf16 v[62:65], v[146:149], v[184:187], v[62:65]
	v_mfma_f32_16x16x32_bf16 v[54:57], v[154:157], v[184:187], v[54:57]
	v_mfma_f32_16x16x32_bf16 v[46:49], v[146:149], v[192:195], v[46:49]
	v_mfma_f32_16x16x32_bf16 v[38:41], v[154:157], v[192:195], v[38:41]
	v_mfma_f32_16x16x32_bf16 v[30:33], v[146:149], v[200:203], v[30:33]
	v_mfma_f32_16x16x32_bf16 v[22:25], v[154:157], v[200:203], v[22:25]
	v_mfma_f32_16x16x32_bf16 v[14:17], v[146:149], v[208:211], v[14:17]
	v_mfma_f32_16x16x32_bf16 v[6:9], v[154:157], v[208:211], v[6:9]
	v_mfma_f32_16x16x32_bf16 v[62:65], v[150:153], v[188:191], v[62:65]
	v_mfma_f32_16x16x32_bf16 v[54:57], v[158:161], v[188:191], v[54:57]
	v_mfma_f32_16x16x32_bf16 v[46:49], v[150:153], v[196:199], v[46:49]
	v_mfma_f32_16x16x32_bf16 v[38:41], v[158:161], v[196:199], v[38:41]
	v_mfma_f32_16x16x32_bf16 v[30:33], v[150:153], v[204:207], v[30:33]
	v_mfma_f32_16x16x32_bf16 v[22:25], v[158:161], v[204:207], v[22:25]
	v_mfma_f32_16x16x32_bf16 v[14:17], v[150:153], v[212:215], v[14:17]
	v_mfma_f32_16x16x32_bf16 v[6:9], v[158:161], v[212:215], v[6:9]
	v_mfma_f32_16x16x32_bf16 v[58:61], v[162:165], v[184:187], v[58:61]
	v_mfma_f32_16x16x32_bf16 v[50:53], v[170:173], v[184:187], v[50:53]
	v_mfma_f32_16x16x32_bf16 v[42:45], v[162:165], v[192:195], v[42:45]
	v_mfma_f32_16x16x32_bf16 v[34:37], v[170:173], v[192:195], v[34:37]
	v_mfma_f32_16x16x32_bf16 v[26:29], v[162:165], v[200:203], v[26:29]
	v_mfma_f32_16x16x32_bf16 v[18:21], v[170:173], v[200:203], v[18:21]
	v_mfma_f32_16x16x32_bf16 v[10:13], v[162:165], v[208:211], v[10:13]
	v_mfma_f32_16x16x32_bf16 v[2:5], v[170:173], v[208:211], v[2:5]
	v_mfma_f32_16x16x32_bf16 v[58:61], v[166:169], v[188:191], v[58:61]
	v_mfma_f32_16x16x32_bf16 v[50:53], v[180:183], v[188:191], v[50:53]
	v_mfma_f32_16x16x32_bf16 v[42:45], v[166:169], v[196:199], v[42:45]
	v_mfma_f32_16x16x32_bf16 v[34:37], v[180:183], v[196:199], v[34:37]
	v_mfma_f32_16x16x32_bf16 v[26:29], v[166:169], v[204:207], v[26:29]
	v_mfma_f32_16x16x32_bf16 v[18:21], v[180:183], v[204:207], v[18:21]
	v_mfma_f32_16x16x32_bf16 v[10:13], v[166:169], v[212:215], v[10:13]
	v_mfma_f32_16x16x32_bf16 v[2:5], v[180:183], v[212:215], v[2:5]
	s_barrier
	s_setprio 0
	s_add_i32 s54, 0, 0x18000
	s_add_i32 s55, 0, 0x1c000
	s_add_u32 s18, s34, 0x84000
	s_addc_u32 s19, s35, 0
	s_mov_b32 m0, s46
	v_lshl_add_u64 v[220:221], s[18:19], 0, v[134:135]
	global_load_lds_dwordx4 v[220:221], off
	v_lshl_add_u64 v[220:221], s[18:19], 0, v[132:133]
	s_mov_b32 m0, s47
	s_nop 0
	global_load_lds_dwordx4 v[220:221], off
	v_add_u32_e32 v158, s54, v143
	v_add_u32_e32 v180, s55, v143
	ds_read_b128 v[146:149], v158
	ds_read_b128 v[150:153], v158 offset:1024
	ds_read_b128 v[154:157], v158 offset:2048
	ds_read_b128 v[158:161], v158 offset:3072
	ds_read_b128 v[162:165], v180
	ds_read_b128 v[166:169], v180 offset:1024
	ds_read_b128 v[170:173], v180 offset:2048
	ds_read_b128 v[180:183], v180 offset:3072
	ds_read_b128 v[184:187], v145 offset:32768
	ds_read_b128 v[188:191], v145 offset:33792
	ds_read_b128 v[192:195], v145 offset:34816
	ds_read_b128 v[196:199], v145 offset:35840
	ds_read_b128 v[200:203], v145 offset:36864
	ds_read_b128 v[204:207], v145 offset:37888
	ds_read_b128 v[208:211], v145 offset:38912
	ds_read_b128 v[212:215], v145 offset:39936
	s_waitcnt vmcnt(8)
	s_waitcnt lgkmcnt(0)
	s_setprio 1
	s_barrier
	v_mfma_f32_16x16x32_bf16 v[126:129], v[146:149], v[184:187], v[126:129]
	v_mfma_f32_16x16x32_bf16 v[118:121], v[154:157], v[184:187], v[118:121]
	v_mfma_f32_16x16x32_bf16 v[110:113], v[146:149], v[192:195], v[110:113]
	v_mfma_f32_16x16x32_bf16 v[102:105], v[154:157], v[192:195], v[102:105]
	v_mfma_f32_16x16x32_bf16 v[94:97], v[146:149], v[200:203], v[94:97]
	v_mfma_f32_16x16x32_bf16 v[86:89], v[154:157], v[200:203], v[86:89]
	v_mfma_f32_16x16x32_bf16 v[78:81], v[146:149], v[208:211], v[78:81]
	v_mfma_f32_16x16x32_bf16 v[70:73], v[154:157], v[208:211], v[70:73]
	v_mfma_f32_16x16x32_bf16 v[126:129], v[150:153], v[188:191], v[126:129]
	v_mfma_f32_16x16x32_bf16 v[118:121], v[158:161], v[188:191], v[118:121]
	v_mfma_f32_16x16x32_bf16 v[110:113], v[150:153], v[196:199], v[110:113]
	v_mfma_f32_16x16x32_bf16 v[102:105], v[158:161], v[196:199], v[102:105]
	v_mfma_f32_16x16x32_bf16 v[94:97], v[150:153], v[204:207], v[94:97]
	v_mfma_f32_16x16x32_bf16 v[86:89], v[158:161], v[204:207], v[86:89]
	v_mfma_f32_16x16x32_bf16 v[78:81], v[150:153], v[212:215], v[78:81]
	v_mfma_f32_16x16x32_bf16 v[70:73], v[158:161], v[212:215], v[70:73]
	v_mfma_f32_16x16x32_bf16 v[122:125], v[162:165], v[184:187], v[122:125]
	v_mfma_f32_16x16x32_bf16 v[114:117], v[170:173], v[184:187], v[114:117]
	v_mfma_f32_16x16x32_bf16 v[106:109], v[162:165], v[192:195], v[106:109]
	v_mfma_f32_16x16x32_bf16 v[98:101], v[170:173], v[192:195], v[98:101]
	v_mfma_f32_16x16x32_bf16 v[90:93], v[162:165], v[200:203], v[90:93]
	v_mfma_f32_16x16x32_bf16 v[82:85], v[170:173], v[200:203], v[82:85]
	v_mfma_f32_16x16x32_bf16 v[74:77], v[162:165], v[208:211], v[74:77]
	v_mfma_f32_16x16x32_bf16 v[66:69], v[170:173], v[208:211], v[66:69]
	v_mfma_f32_16x16x32_bf16 v[122:125], v[166:169], v[188:191], v[122:125]
	v_mfma_f32_16x16x32_bf16 v[114:117], v[180:183], v[188:191], v[114:117]
	v_mfma_f32_16x16x32_bf16 v[106:109], v[166:169], v[196:199], v[106:109]
	v_mfma_f32_16x16x32_bf16 v[98:101], v[180:183], v[196:199], v[98:101]
	v_mfma_f32_16x16x32_bf16 v[90:93], v[166:169], v[204:207], v[90:93]
	v_mfma_f32_16x16x32_bf16 v[82:85], v[180:183], v[204:207], v[82:85]
	v_mfma_f32_16x16x32_bf16 v[74:77], v[166:169], v[212:215], v[74:77]
	v_mfma_f32_16x16x32_bf16 v[66:69], v[180:183], v[212:215], v[66:69]
	s_barrier
; #define PG8_STAGE(bufoff, gbase, voff) do { _Pragma("unroll") for (int _i = 0; _i < 2; ++_i) \
;         __builtin_amdgcn_global_load_lds((const unsigned*)((const char*)(gbase) + (voff)[_i]), (LAS unsigned*)(lds + (bufoff) + ldsw + _i * 8192), 16, 0, 0); } while (0)
; #define PG8_LDA(dst, b, h) do { _Pragma("unroll") for (int m = 0; m < 4; ++m) _Pragma("unroll") for (int k = 0; k < 2; ++k) dst[m][k] = *(const LAS bf16x8*)(lds + PG8_SA(b, h) + aoff + m * 2048 + k * 1024); } while (0)
; #define PG8_MMA(ai, bj, At, Bt) do { __builtin_amdgcn_s_setprio(1); _Pragma("unroll") for (int m = 0; m < 4; ++m) _Pragma("unroll") for (int n = 0; n < 2; ++n) _Pragma("unroll") for (int k = 0; k < 2; ++k) \
;         acc[ai][bj][m][n] = __builtin_amdgcn_mfma_f32_16x16x32_bf16(Bt[n][k], At[m][k], acc[ai][bj][m][n], 0, 0, 0); __builtin_amdgcn_s_setprio(0); } while (0)
; #define PG8_WAIT_V(n) asm volatile("s_waitcnt vmcnt(" #n ")" ::: "memory")
; #define PG8_WAIT_L(n) asm volatile("s_waitcnt lgkmcnt(" #n ")" ::: "memory")
; #define PG8_BAR __builtin_amdgcn_s_barrier()
; #define PG8_SCHED __builtin_amdgcn_sched_barrier(0)
; template <class Epi, class Sched, int LDA, int LDB, bool ALIGN_EPI = true>
; __device__ __forceinline__ void gemm_phase(LAS unsigned char* lds, const Gemm g, const Sched& S, const Epi& E, int wave) {
;     ...
;             PG8_LDA(At, 1, 1); PG8_STAGE(PG8_SB(1, 0), b3, voffB); PG8_STAGE(PG8_SB(1, 1), b3 + hstepB, voffB); PG8_STAGE(PG8_SA(1, 0), a3, voffA);
;             PG8_WAIT_V(8); PG8_WAIT_L(0); PG8_BAR; PG8_MMA(1, 0, At, B0); PG8_MMA(1, 1, At, B1); PG8_BAR; PG8_SCHED;
;         }
	s_setprio 0
	s_add_i32 s18, s54, s5
	v_lshl_add_u64 v[140:141], v[140:141], 0, s[6:7]
	s_mov_b32 m0, s18
	s_nop 0
	global_load_lds_dwordx4 v[140:141], off
	s_add_i32 m0, s18, 0x2000
	s_add_u32 s18, s28, 0x80080
	v_lshl_add_u64 v[140:141], v[174:175], 0, s[6:7]
	s_addc_u32 s19, s29, 0
	s_add_i32 s28, s55, s5
	global_load_lds_dwordx4 v[140:141], off
	v_lshl_add_u64 v[140:141], s[18:19], 0, v[0:1]
	s_mov_b32 m0, s28
	s_nop 0
	global_load_lds_dwordx4 v[140:141], off
	v_lshl_add_u64 v[140:141], s[18:19], 0, v[130:131]
	s_add_i32 m0, s28, 0x2000
	s_nop 0
	global_load_lds_dwordx4 v[140:141], off
	v_lshl_add_u64 v[140:141], v[216:217], 0, s[6:7]
	s_mov_b32 m0, s48
	s_nop 0
	global_load_lds_dwordx4 v[140:141], off
	v_lshl_add_u64 v[140:141], v[218:219], 0, s[6:7]
	s_mov_b32 m0, s49
	s_nop 0
	global_load_lds_dwordx4 v[140:141], off
	ds_read_b128 v[184:187], v145 offset:49152
	ds_read_b128 v[188:191], v145 offset:50176
	ds_read_b128 v[192:195], v145 offset:51200
	ds_read_b128 v[196:199], v145 offset:52224
	ds_read_b128 v[200:203], v145 offset:53248
	ds_read_b128 v[204:207], v145 offset:54272
	ds_read_b128 v[208:211], v145 offset:55296
	ds_read_b128 v[212:215], v145 offset:56320
	s_waitcnt vmcnt(8)
	s_waitcnt lgkmcnt(0)
	s_setprio 1
	s_barrier
	v_mfma_f32_16x16x32_bf16 v[62:65], v[146:149], v[184:187], v[62:65]
	v_mfma_f32_16x16x32_bf16 v[54:57], v[154:157], v[184:187], v[54:57]
	v_mfma_f32_16x16x32_bf16 v[46:49], v[146:149], v[192:195], v[46:49]
	v_mfma_f32_16x16x32_bf16 v[38:41], v[154:157], v[192:195], v[38:41]
	v_mfma_f32_16x16x32_bf16 v[30:33], v[146:149], v[200:203], v[30:33]
	v_mfma_f32_16x16x32_bf16 v[22:25], v[154:157], v[200:203], v[22:25]
	v_mfma_f32_16x16x32_bf16 v[14:17], v[146:149], v[208:211], v[14:17]
	v_mfma_f32_16x16x32_bf16 v[6:9], v[154:157], v[208:211], v[6:9]
	v_mfma_f32_16x16x32_bf16 v[62:65], v[150:153], v[188:191], v[62:65]
	v_mfma_f32_16x16x32_bf16 v[54:57], v[158:161], v[188:191], v[54:57]
	v_mfma_f32_16x16x32_bf16 v[46:49], v[150:153], v[196:199], v[46:49]
	v_mfma_f32_16x16x32_bf16 v[38:41], v[158:161], v[196:199], v[38:41]
	v_mfma_f32_16x16x32_bf16 v[30:33], v[150:153], v[204:207], v[30:33]
	v_mfma_f32_16x16x32_bf16 v[22:25], v[158:161], v[204:207], v[22:25]
	v_mfma_f32_16x16x32_bf16 v[14:17], v[150:153], v[212:215], v[14:17]
	v_mfma_f32_16x16x32_bf16 v[6:9], v[158:161], v[212:215], v[6:9]
	v_mfma_f32_16x16x32_bf16 v[58:61], v[162:165], v[184:187], v[58:61]
	v_mfma_f32_16x16x32_bf16 v[50:53], v[170:173], v[184:187], v[50:53]
	v_mfma_f32_16x16x32_bf16 v[42:45], v[162:165], v[192:195], v[42:45]
	v_mfma_f32_16x16x32_bf16 v[34:37], v[170:173], v[192:195], v[34:37]
	v_mfma_f32_16x16x32_bf16 v[26:29], v[162:165], v[200:203], v[26:29]
	v_mfma_f32_16x16x32_bf16 v[18:21], v[170:173], v[200:203], v[18:21]
	v_mfma_f32_16x16x32_bf16 v[10:13], v[162:165], v[208:211], v[10:13]
	v_mfma_f32_16x16x32_bf16 v[2:5], v[170:173], v[208:211], v[2:5]
	v_mfma_f32_16x16x32_bf16 v[58:61], v[166:169], v[188:191], v[58:61]
	v_mfma_f32_16x16x32_bf16 v[50:53], v[180:183], v[188:191], v[50:53]
	v_mfma_f32_16x16x32_bf16 v[42:45], v[166:169], v[196:199], v[42:45]
	v_mfma_f32_16x16x32_bf16 v[34:37], v[180:183], v[196:199], v[34:37]
	v_mfma_f32_16x16x32_bf16 v[26:29], v[166:169], v[204:207], v[26:29]
	v_mfma_f32_16x16x32_bf16 v[18:21], v[180:183], v[204:207], v[18:21]
	v_mfma_f32_16x16x32_bf16 v[10:13], v[166:169], v[212:215], v[10:13]
	v_mfma_f32_16x16x32_bf16 v[2:5], v[180:183], v[212:215], v[2:5]
	s_barrier
	s_setprio 0
	s_add_i32 s53, s53, 2
	s_add_u32 s44, s44, 0x100
	s_addc_u32 s45, s45, 0
	s_cmp_gt_u32 s53, 29
	s_mov_b64 s[18:19], s[24:25]
	s_cbranch_scc0 .LBB0_485
	v_readlane_b32 s6, v252, 14
	v_readlane_b32 s7, v252, 15
	s_and_b64 vcc, exec, s[6:7]
	s_cbranch_vccz .LBB0_488
	s_barrier

; #define PG8_STAGE(bufoff, gbase, voff) do { _Pragma("unroll") for (int _i = 0; _i < 2; ++_i) \
;         __builtin_amdgcn_global_load_lds((const unsigned*)((const char*)(gbase) + (voff)[_i]), (LAS unsigned*)(lds + (bufoff) + ldsw + _i * 8192), 16, 0, 0); } while (0)
; #define PG8_LDA(dst, b, h) do { _Pragma("unroll") for (int m = 0; m < 4; ++m) _Pragma("unroll") for (int k = 0; k < 2; ++k) dst[m][k] = *(const LAS bf16x8*)(lds + PG8_SA(b, h) + aoff + m * 2048 + k * 1024); } while (0)
; #define PG8_LDB(dst, b, h) do { _Pragma("unroll") for (int n = 0; n < 2; ++n) _Pragma("unroll") for (int k = 0; k < 2; ++k) dst[n][k] = *(const LAS bf16x8*)(lds + PG8_SB(b, h) + boff + n * 2048 + k * 1024); } while (0)
; #define PG8_MMA(ai, bj, At, Bt) do { __builtin_amdgcn_s_setprio(1); _Pragma("unroll") for (int m = 0; m < 4; ++m) _Pragma("unroll") for (int n = 0; n < 2; ++n) _Pragma("unroll") for (int k = 0; k < 2; ++k) \
;         acc[ai][bj][m][n] = __builtin_amdgcn_mfma_f32_16x16x32_bf16(Bt[n][k], At[m][k], acc[ai][bj][m][n], 0, 0, 0); __builtin_amdgcn_s_setprio(0); } while (0)
; #define PG8_WAIT_V(n) asm volatile("s_waitcnt vmcnt(" #n ")" ::: "memory")
; #define PG8_WAIT_L(n) asm volatile("s_waitcnt lgkmcnt(" #n ")" ::: "memory")
; #define PG8_BAR __builtin_amdgcn_s_barrier()
; template <class Epi, class Sched, int LDA, int LDB, bool ALIGN_EPI = true>
; __device__ __forceinline__ void gemm_phase(LAS unsigned char* lds, const Gemm g, const Sched& S, const Epi& E, int wave) {
;     ...
;         for (int t = 0; t < nt; t += 2) {
;             const bool last = (t == nt - 2);
;             const char* a1 = cA + (size_t)(t + 1) * kstep;
;             const char* a2 = last ? nA : cA + (size_t)(t + 2) * kstep; const char* b2 = last ? nB : cB + (size_t)(t + 2) * kstep;
;             const char* a3 = a2 + kstep; const char* b3 = b2 + kstep;
;             PG8_LDB(B0, 0, 0); PG8_LDB(B1, 0, 1); PG8_SCHED; PG8_LDA(At, 0, 0); PG8_STAGE(PG8_SA(1, 1), a1 + hstepA, voffA);
;             PG8_WAIT_V(8); PG8_WAIT_L(0); PG8_BAR; PG8_MMA(0, 0, At, B0); PG8_MMA(0, 1, At, B1); PG8_BAR; PG8_SCHED;
;             PG8_LDA(At, 0, 1); PG8_STAGE(PG8_SB(0, 0), b2, voffB); PG8_STAGE(PG8_SB(0, 1), b2 + hstepB, voffB); PG8_STAGE(PG8_SA(0, 0), a2, voffA);
;             PG8_WAIT_V(8); PG8_WAIT_L(0); PG8_BAR; PG8_MMA(1, 0, At, B0); PG8_MMA(1, 1, At, B1); PG8_BAR; PG8_SCHED;
.LBB0_1893:
	s_add_i32 s79, s46, 2
	s_add_u32 s38, s36, 0x100
	s_addc_u32 s39, s37, 0
	s_add_i32 s82, 0, 0x10000
	s_cmp_eq_u32 s25, s46
	s_cselect_b32 s49, s29, s39
	s_cselect_b32 s48, s28, s38
	s_cselect_b32 s47, s35, s78
	s_cselect_b32 s46, s34, s77
	s_add_i32 s85, 0, 0x14000
	v_lshl_add_u64 v[208:209], s[36:37], 0, v[144:145]
	s_add_i32 m0, s50, 0xc000
	s_nop 0
	global_load_lds_dwordx4 v[208:209], off
	v_lshl_add_u64 v[208:209], s[36:37], 0, v[146:147]
	s_add_i32 m0, s50, 0xe000
	s_nop 0
	global_load_lds_dwordx4 v[208:209], off
	v_add_u32_e32 v152, s82, v249
	v_add_u32_e32 v168, s85, v249
	ds_read_b128 v[130:133], v152
	ds_read_b128 v[134:137], v152 offset:1024
	ds_read_b128 v[148:151], v152 offset:2048
	ds_read_b128 v[152:155], v152 offset:3072
	ds_read_b128 v[156:159], v168
	ds_read_b128 v[160:163], v168 offset:1024
	ds_read_b128 v[164:167], v168 offset:2048
	ds_read_b128 v[168:171], v168 offset:3072
	ds_read_b128 v[172:175], v236
	ds_read_b128 v[180:183], v236 offset:1024
	ds_read_b128 v[184:187], v236 offset:2048
	ds_read_b128 v[188:191], v236 offset:3072
	ds_read_b128 v[192:195], v236 offset:4096
	ds_read_b128 v[196:199], v236 offset:5120
	ds_read_b128 v[200:203], v236 offset:6144
	ds_read_b128 v[204:207], v236 offset:7168
	s_waitcnt vmcnt(8)
	s_waitcnt lgkmcnt(0)
	s_setprio 1
	s_barrier
	v_mfma_f32_16x16x32_bf16 v[126:129], v[130:133], v[172:175], v[126:129]
	v_mfma_f32_16x16x32_bf16 v[122:125], v[148:151], v[172:175], v[122:125]
	v_mfma_f32_16x16x32_bf16 v[110:113], v[130:133], v[184:187], v[110:113]
	v_mfma_f32_16x16x32_bf16 v[106:109], v[148:151], v[184:187], v[106:109]
	v_mfma_f32_16x16x32_bf16 v[94:97], v[130:133], v[192:195], v[94:97]
	v_mfma_f32_16x16x32_bf16 v[90:93], v[148:151], v[192:195], v[90:93]
	v_mfma_f32_16x16x32_bf16 v[78:81], v[130:133], v[200:203], v[78:81]
	v_mfma_f32_16x16x32_bf16 v[74:77], v[148:151], v[200:203], v[74:77]
	v_mfma_f32_16x16x32_bf16 v[126:129], v[134:137], v[180:183], v[126:129]
	v_mfma_f32_16x16x32_bf16 v[122:125], v[152:155], v[180:183], v[122:125]
	v_mfma_f32_16x16x32_bf16 v[110:113], v[134:137], v[188:191], v[110:113]
	v_mfma_f32_16x16x32_bf16 v[106:109], v[152:155], v[188:191], v[106:109]
	v_mfma_f32_16x16x32_bf16 v[94:97], v[134:137], v[196:199], v[94:97]
	v_mfma_f32_16x16x32_bf16 v[90:93], v[152:155], v[196:199], v[90:93]
	v_mfma_f32_16x16x32_bf16 v[78:81], v[134:137], v[204:207], v[78:81]
	v_mfma_f32_16x16x32_bf16 v[74:77], v[152:155], v[204:207], v[74:77]
	v_mfma_f32_16x16x32_bf16 v[118:121], v[156:159], v[172:175], v[118:121]
	v_mfma_f32_16x16x32_bf16 v[114:117], v[164:167], v[172:175], v[114:117]
	v_mfma_f32_16x16x32_bf16 v[102:105], v[156:159], v[184:187], v[102:105]
	v_mfma_f32_16x16x32_bf16 v[98:101], v[164:167], v[184:187], v[98:101]
	v_mfma_f32_16x16x32_bf16 v[86:89], v[156:159], v[192:195], v[86:89]
	v_mfma_f32_16x16x32_bf16 v[82:85], v[164:167], v[192:195], v[82:85]
	v_mfma_f32_16x16x32_bf16 v[70:73], v[156:159], v[200:203], v[70:73]
	v_mfma_f32_16x16x32_bf16 v[66:69], v[164:167], v[200:203], v[66:69]
	v_mfma_f32_16x16x32_bf16 v[118:121], v[160:163], v[180:183], v[118:121]
	v_mfma_f32_16x16x32_bf16 v[114:117], v[168:171], v[180:183], v[114:117]
	v_mfma_f32_16x16x32_bf16 v[102:105], v[160:163], v[188:191], v[102:105]
	v_mfma_f32_16x16x32_bf16 v[98:101], v[168:171], v[188:191], v[98:101]
	v_mfma_f32_16x16x32_bf16 v[86:89], v[160:163], v[196:199], v[86:89]
	v_mfma_f32_16x16x32_bf16 v[82:85], v[168:171], v[196:199], v[82:85]
	v_mfma_f32_16x16x32_bf16 v[70:73], v[160:163], v[204:207], v[70:73]
	v_mfma_f32_16x16x32_bf16 v[66:69], v[168:171], v[204:207], v[66:69]
	s_barrier
	s_setprio 0
	s_add_i32 s36, s82, s2
	v_lshl_add_u64 v[208:209], s[46:47], 0, v[0:1]
	s_mov_b32 m0, s36
	s_nop 0
	global_load_lds_dwordx4 v[208:209], off
	s_add_i32 m0, s36, 0x2000
	s_add_u32 s36, s46, 0x160000
	v_lshl_add_u64 v[210:211], s[46:47], 0, v[142:143]
	s_addc_u32 s37, s47, 0
	s_add_i32 s82, s85, s2
	global_load_lds_dwordx4 v[210:211], off
	v_lshl_add_u64 v[212:213], s[36:37], 0, v[0:1]
	s_mov_b32 m0, s82
	v_lshl_add_u64 v[214:215], s[48:49], 0, v[140:141]
	global_load_lds_dwordx4 v[212:213], off
	v_lshl_add_u64 v[212:213], s[36:37], 0, v[142:143]
	s_add_i32 m0, s82, 0x2000
	s_nop 0
	global_load_lds_dwordx4 v[212:213], off
	v_lshl_add_u64 v[212:213], s[48:49], 0, v[138:139]
	s_mov_b32 m0, s50
	s_nop 0
	global_load_lds_dwordx4 v[212:213], off
	s_mov_b32 m0, s51
	s_nop 0
	global_load_lds_dwordx4 v[214:215], off
	ds_read_b128 v[172:175], v236 offset:16384
	ds_read_b128 v[180:183], v236 offset:17408
	ds_read_b128 v[184:187], v236 offset:18432
	ds_read_b128 v[188:191], v236 offset:19456
	ds_read_b128 v[192:195], v236 offset:20480
	ds_read_b128 v[196:199], v236 offset:21504
	ds_read_b128 v[200:203], v236 offset:22528
	ds_read_b128 v[204:207], v236 offset:23552
	s_waitcnt vmcnt(8)
	s_waitcnt lgkmcnt(0)
	s_setprio 1
	s_barrier
; #define PG8_STAGE(bufoff, gbase, voff) do { _Pragma("unroll") for (int _i = 0; _i < 2; ++_i) \
;         __builtin_amdgcn_global_load_lds((const unsigned*)((const char*)(gbase) + (voff)[_i]), (LAS unsigned*)(lds + (bufoff) + ldsw + _i * 8192), 16, 0, 0); } while (0)
; #define PG8_LDA(dst, b, h) do { _Pragma("unroll") for (int m = 0; m < 4; ++m) _Pragma("unroll") for (int k = 0; k < 2; ++k) dst[m][k] = *(const LAS bf16x8*)(lds + PG8_SA(b, h) + aoff + m * 2048 + k * 1024); } while (0)
; #define PG8_LDB(dst, b, h) do { _Pragma("unroll") for (int n = 0; n < 2; ++n) _Pragma("unroll") for (int k = 0; k < 2; ++k) dst[n][k] = *(const LAS bf16x8*)(lds + PG8_SB(b, h) + boff + n * 2048 + k * 1024); } while (0)
; #define PG8_MMA(ai, bj, At, Bt) do { __builtin_amdgcn_s_setprio(1); _Pragma("unroll") for (int m = 0; m < 4; ++m) _Pragma("unroll") for (int n = 0; n < 2; ++n) _Pragma("unroll") for (int k = 0; k < 2; ++k) \
;         acc[ai][bj][m][n] = __builtin_amdgcn_mfma_f32_16x16x32_bf16(Bt[n][k], At[m][k], acc[ai][bj][m][n], 0, 0, 0); __builtin_amdgcn_s_setprio(0); } while (0)
; #define PG8_WAIT_V(n) asm volatile("s_waitcnt vmcnt(" #n ")" ::: "memory")
; #define PG8_WAIT_L(n) asm volatile("s_waitcnt lgkmcnt(" #n ")" ::: "memory")
; #define PG8_BAR __builtin_amdgcn_s_barrier()
; #define PG8_SCHED __builtin_amdgcn_sched_barrier(0)
; template <class Epi, class Sched, int LDA, int LDB, bool ALIGN_EPI = true>
; __device__ __forceinline__ void gemm_phase(LAS unsigned char* lds, const Gemm g, const Sched& S, const Epi& E, int wave) {
;     ...
;             PG8_WAIT_V(8); PG8_WAIT_L(0); PG8_BAR; PG8_MMA(1, 0, At, B0); PG8_MMA(1, 1, At, B1); PG8_BAR; PG8_SCHED;
;             PG8_LDB(B0, 1, 0); PG8_LDB(B1, 1, 1); PG8_SCHED; PG8_LDA(At, 1, 0); PG8_STAGE(PG8_SA(0, 1), a2 + hstepA, voffA);
;             PG8_WAIT_V(8); PG8_WAIT_L(0); PG8_BAR; PG8_MMA(0, 0, At, B0); PG8_MMA(0, 1, At, B1); PG8_BAR; PG8_SCHED;
	v_mfma_f32_16x16x32_bf16 v[62:65], v[130:133], v[172:175], v[62:65]
	v_mfma_f32_16x16x32_bf16 v[58:61], v[148:151], v[172:175], v[58:61]
	v_mfma_f32_16x16x32_bf16 v[46:49], v[130:133], v[184:187], v[46:49]
	v_mfma_f32_16x16x32_bf16 v[42:45], v[148:151], v[184:187], v[42:45]
	v_mfma_f32_16x16x32_bf16 v[30:33], v[130:133], v[192:195], v[30:33]
	v_mfma_f32_16x16x32_bf16 v[26:29], v[148:151], v[192:195], v[26:29]
	v_mfma_f32_16x16x32_bf16 v[14:17], v[130:133], v[200:203], v[14:17]
	v_mfma_f32_16x16x32_bf16 v[10:13], v[148:151], v[200:203], v[10:13]
	v_mfma_f32_16x16x32_bf16 v[62:65], v[134:137], v[180:183], v[62:65]
	v_mfma_f32_16x16x32_bf16 v[58:61], v[152:155], v[180:183], v[58:61]
	v_mfma_f32_16x16x32_bf16 v[46:49], v[134:137], v[188:191], v[46:49]
	v_mfma_f32_16x16x32_bf16 v[42:45], v[152:155], v[188:191], v[42:45]
	v_mfma_f32_16x16x32_bf16 v[30:33], v[134:137], v[196:199], v[30:33]
	v_mfma_f32_16x16x32_bf16 v[26:29], v[152:155], v[196:199], v[26:29]
	v_mfma_f32_16x16x32_bf16 v[14:17], v[134:137], v[204:207], v[14:17]
	v_mfma_f32_16x16x32_bf16 v[10:13], v[152:155], v[204:207], v[10:13]
	v_mfma_f32_16x16x32_bf16 v[54:57], v[156:159], v[172:175], v[54:57]
	v_mfma_f32_16x16x32_bf16 v[50:53], v[164:167], v[172:175], v[50:53]
	v_mfma_f32_16x16x32_bf16 v[38:41], v[156:159], v[184:187], v[38:41]
	v_mfma_f32_16x16x32_bf16 v[34:37], v[164:167], v[184:187], v[34:37]
	v_mfma_f32_16x16x32_bf16 v[22:25], v[156:159], v[192:195], v[22:25]
	v_mfma_f32_16x16x32_bf16 v[18:21], v[164:167], v[192:195], v[18:21]
	v_mfma_f32_16x16x32_bf16 v[6:9], v[156:159], v[200:203], v[6:9]
	v_mfma_f32_16x16x32_bf16 v[2:5], v[164:167], v[200:203], v[2:5]
	v_mfma_f32_16x16x32_bf16 v[54:57], v[160:163], v[180:183], v[54:57]
	v_mfma_f32_16x16x32_bf16 v[50:53], v[168:171], v[180:183], v[50:53]
	v_mfma_f32_16x16x32_bf16 v[38:41], v[160:163], v[188:191], v[38:41]
	v_mfma_f32_16x16x32_bf16 v[34:37], v[168:171], v[188:191], v[34:37]
	v_mfma_f32_16x16x32_bf16 v[22:25], v[160:163], v[196:199], v[22:25]
	v_mfma_f32_16x16x32_bf16 v[18:21], v[168:171], v[196:199], v[18:21]
	v_mfma_f32_16x16x32_bf16 v[6:9], v[160:163], v[204:207], v[6:9]
	v_mfma_f32_16x16x32_bf16 v[2:5], v[168:171], v[204:207], v[2:5]
	s_barrier
	s_setprio 0
	s_add_i32 s82, 0, 0x18000
	s_add_i32 s85, 0, 0x1c000
	s_add_u32 s36, s48, 0x160000
	s_addc_u32 s37, s49, 0
	s_mov_b32 m0, s52
	v_lshl_add_u64 v[216:217], s[36:37], 0, v[138:139]
	global_load_lds_dwordx4 v[216:217], off
	v_lshl_add_u64 v[216:217], s[36:37], 0, v[140:141]
	s_mov_b32 m0, s53
	s_nop 0
	global_load_lds_dwordx4 v[216:217], off
	v_add_u32_e32 v152, s82, v249
	v_add_u32_e32 v168, s85, v249
	ds_read_b128 v[130:133], v152
	ds_read_b128 v[134:137], v152 offset:1024
	ds_read_b128 v[148:151], v152 offset:2048
	ds_read_b128 v[152:155], v152 offset:3072
	ds_read_b128 v[156:159], v168
	ds_read_b128 v[160:163], v168 offset:1024
	ds_read_b128 v[164:167], v168 offset:2048
	ds_read_b128 v[168:171], v168 offset:3072
	ds_read_b128 v[172:175], v236 offset:32768
	ds_read_b128 v[180:183], v236 offset:33792
	ds_read_b128 v[184:187], v236 offset:34816
	ds_read_b128 v[188:191], v236 offset:35840
	ds_read_b128 v[192:195], v236 offset:36864
	ds_read_b128 v[196:199], v236 offset:37888
	ds_read_b128 v[200:203], v236 offset:38912
	ds_read_b128 v[204:207], v236 offset:39936
	s_waitcnt vmcnt(8)
	s_waitcnt lgkmcnt(0)
	s_setprio 1
	s_barrier
	v_mfma_f32_16x16x32_bf16 v[126:129], v[130:133], v[172:175], v[126:129]
	v_mfma_f32_16x16x32_bf16 v[122:125], v[148:151], v[172:175], v[122:125]
	v_mfma_f32_16x16x32_bf16 v[110:113], v[130:133], v[184:187], v[110:113]
	v_mfma_f32_16x16x32_bf16 v[106:109], v[148:151], v[184:187], v[106:109]
	v_mfma_f32_16x16x32_bf16 v[94:97], v[130:133], v[192:195], v[94:97]
	v_mfma_f32_16x16x32_bf16 v[90:93], v[148:151], v[192:195], v[90:93]
	v_mfma_f32_16x16x32_bf16 v[78:81], v[130:133], v[200:203], v[78:81]
	v_mfma_f32_16x16x32_bf16 v[74:77], v[148:151], v[200:203], v[74:77]
	v_mfma_f32_16x16x32_bf16 v[126:129], v[134:137], v[180:183], v[126:129]
	v_mfma_f32_16x16x32_bf16 v[122:125], v[152:155], v[180:183], v[122:125]
	v_mfma_f32_16x16x32_bf16 v[110:113], v[134:137], v[188:191], v[110:113]
	v_mfma_f32_16x16x32_bf16 v[106:109], v[152:155], v[188:191], v[106:109]
	v_mfma_f32_16x16x32_bf16 v[94:97], v[134:137], v[196:199], v[94:97]
	v_mfma_f32_16x16x32_bf16 v[90:93], v[152:155], v[196:199], v[90:93]
	v_mfma_f32_16x16x32_bf16 v[78:81], v[134:137], v[204:207], v[78:81]
	v_mfma_f32_16x16x32_bf16 v[74:77], v[152:155], v[204:207], v[74:77]
	v_mfma_f32_16x16x32_bf16 v[118:121], v[156:159], v[172:175], v[118:121]
	v_mfma_f32_16x16x32_bf16 v[114:117], v[164:167], v[172:175], v[114:117]
	v_mfma_f32_16x16x32_bf16 v[102:105], v[156:159], v[184:187], v[102:105]
	v_mfma_f32_16x16x32_bf16 v[98:101], v[164:167], v[184:187], v[98:101]
	v_mfma_f32_16x16x32_bf16 v[86:89], v[156:159], v[192:195], v[86:89]
	v_mfma_f32_16x16x32_bf16 v[82:85], v[164:167], v[192:195], v[82:85]
	v_mfma_f32_16x16x32_bf16 v[70:73], v[156:159], v[200:203], v[70:73]
	v_mfma_f32_16x16x32_bf16 v[66:69], v[164:167], v[200:203], v[66:69]
	v_mfma_f32_16x16x32_bf16 v[118:121], v[160:163], v[180:183], v[118:121]
	v_mfma_f32_16x16x32_bf16 v[114:117], v[168:171], v[180:183], v[114:117]
	v_mfma_f32_16x16x32_bf16 v[102:105], v[160:163], v[188:191], v[102:105]
	v_mfma_f32_16x16x32_bf16 v[98:101], v[168:171], v[188:191], v[98:101]
	v_mfma_f32_16x16x32_bf16 v[86:89], v[160:163], v[196:199], v[86:89]
	v_mfma_f32_16x16x32_bf16 v[82:85], v[168:171], v[196:199], v[82:85]
	v_mfma_f32_16x16x32_bf16 v[70:73], v[160:163], v[204:207], v[70:73]
	v_mfma_f32_16x16x32_bf16 v[66:69], v[168:171], v[204:207], v[66:69]
	s_barrier
; #define PG8_STAGE(bufoff, gbase, voff) do { _Pragma("unroll") for (int _i = 0; _i < 2; ++_i) \
;         __builtin_amdgcn_global_load_lds((const unsigned*)((const char*)(gbase) + (voff)[_i]), (LAS unsigned*)(lds + (bufoff) + ldsw + _i * 8192), 16, 0, 0); } while (0)
; #define PG8_LDA(dst, b, h) do { _Pragma("unroll") for (int m = 0; m < 4; ++m) _Pragma("unroll") for (int k = 0; k < 2; ++k) dst[m][k] = *(const LAS bf16x8*)(lds + PG8_SA(b, h) + aoff + m * 2048 + k * 1024); } while (0)
; #define PG8_MMA(ai, bj, At, Bt) do { __builtin_amdgcn_s_setprio(1); _Pragma("unroll") for (int m = 0; m < 4; ++m) _Pragma("unroll") for (int n = 0; n < 2; ++n) _Pragma("unroll") for (int k = 0; k < 2; ++k) \
;         acc[ai][bj][m][n] = __builtin_amdgcn_mfma_f32_16x16x32_bf16(Bt[n][k], At[m][k], acc[ai][bj][m][n], 0, 0, 0); __builtin_amdgcn_s_setprio(0); } while (0)
; #define PG8_WAIT_V(n) asm volatile("s_waitcnt vmcnt(" #n ")" ::: "memory")
; #define PG8_WAIT_L(n) asm volatile("s_waitcnt lgkmcnt(" #n ")" ::: "memory")
; #define PG8_BAR __builtin_amdgcn_s_barrier()
; #define PG8_SCHED __builtin_amdgcn_sched_barrier(0)
; template <class Epi, class Sched, int LDA, int LDB, bool ALIGN_EPI = true>
; __device__ __forceinline__ void gemm_phase(LAS unsigned char* lds, const Gemm g, const Sched& S, const Epi& E, int wave) {
;     ...
;             PG8_LDA(At, 1, 1); PG8_STAGE(PG8_SB(1, 0), b3, voffB); PG8_STAGE(PG8_SB(1, 1), b3 + hstepB, voffB); PG8_STAGE(PG8_SA(1, 0), a3, voffA);
;             PG8_WAIT_V(8); PG8_WAIT_L(0); PG8_BAR; PG8_MMA(1, 0, At, B0); PG8_MMA(1, 1, At, B1); PG8_BAR; PG8_SCHED;
;         }
	s_setprio 0
	s_add_i32 s36, s82, s2
	v_lshl_add_u64 v[208:209], v[208:209], 0, s[8:9]
	s_mov_b32 m0, s36
	s_nop 0
	global_load_lds_dwordx4 v[208:209], off
	s_add_i32 m0, s36, 0x2000
	s_add_u32 s36, s46, 0x160080
	v_lshl_add_u64 v[208:209], v[210:211], 0, s[8:9]
	s_addc_u32 s37, s47, 0
	s_add_i32 s46, s85, s2
	global_load_lds_dwordx4 v[208:209], off
	v_lshl_add_u64 v[208:209], s[36:37], 0, v[0:1]
	s_mov_b32 m0, s46
	s_nop 0
	global_load_lds_dwordx4 v[208:209], off
	v_lshl_add_u64 v[208:209], s[36:37], 0, v[142:143]
	s_add_i32 m0, s46, 0x2000
	s_nop 0
	global_load_lds_dwordx4 v[208:209], off
	v_lshl_add_u64 v[208:209], v[212:213], 0, s[8:9]
	s_mov_b32 m0, s5
	s_nop 0
	global_load_lds_dwordx4 v[208:209], off
	v_lshl_add_u64 v[208:209], v[214:215], 0, s[8:9]
	s_mov_b32 m0, s59
	s_nop 0
	global_load_lds_dwordx4 v[208:209], off
	ds_read_b128 v[172:175], v236 offset:49152
	ds_read_b128 v[180:183], v236 offset:50176
	ds_read_b128 v[184:187], v236 offset:51200
	ds_read_b128 v[188:191], v236 offset:52224
	ds_read_b128 v[192:195], v236 offset:53248
	ds_read_b128 v[196:199], v236 offset:54272
	ds_read_b128 v[200:203], v236 offset:55296
	ds_read_b128 v[204:207], v236 offset:56320
	s_waitcnt vmcnt(8)
	s_waitcnt lgkmcnt(0)
	s_setprio 1
	s_barrier
	v_mfma_f32_16x16x32_bf16 v[62:65], v[130:133], v[172:175], v[62:65]
	v_mfma_f32_16x16x32_bf16 v[58:61], v[148:151], v[172:175], v[58:61]
	v_mfma_f32_16x16x32_bf16 v[46:49], v[130:133], v[184:187], v[46:49]
	v_mfma_f32_16x16x32_bf16 v[42:45], v[148:151], v[184:187], v[42:45]
	v_mfma_f32_16x16x32_bf16 v[30:33], v[130:133], v[192:195], v[30:33]
	v_mfma_f32_16x16x32_bf16 v[26:29], v[148:151], v[192:195], v[26:29]
	v_mfma_f32_16x16x32_bf16 v[14:17], v[130:133], v[200:203], v[14:17]
	v_mfma_f32_16x16x32_bf16 v[10:13], v[148:151], v[200:203], v[10:13]
	v_mfma_f32_16x16x32_bf16 v[62:65], v[134:137], v[180:183], v[62:65]
	v_mfma_f32_16x16x32_bf16 v[58:61], v[152:155], v[180:183], v[58:61]
	v_mfma_f32_16x16x32_bf16 v[46:49], v[134:137], v[188:191], v[46:49]
	v_mfma_f32_16x16x32_bf16 v[42:45], v[152:155], v[188:191], v[42:45]
	v_mfma_f32_16x16x32_bf16 v[30:33], v[134:137], v[196:199], v[30:33]
	v_mfma_f32_16x16x32_bf16 v[26:29], v[152:155], v[196:199], v[26:29]
	v_mfma_f32_16x16x32_bf16 v[14:17], v[134:137], v[204:207], v[14:17]
	v_mfma_f32_16x16x32_bf16 v[10:13], v[152:155], v[204:207], v[10:13]
	v_mfma_f32_16x16x32_bf16 v[54:57], v[156:159], v[172:175], v[54:57]
	v_mfma_f32_16x16x32_bf16 v[50:53], v[164:167], v[172:175], v[50:53]
	v_mfma_f32_16x16x32_bf16 v[38:41], v[156:159], v[184:187], v[38:41]
	v_mfma_f32_16x16x32_bf16 v[34:37], v[164:167], v[184:187], v[34:37]
	v_mfma_f32_16x16x32_bf16 v[22:25], v[156:159], v[192:195], v[22:25]
	v_mfma_f32_16x16x32_bf16 v[18:21], v[164:167], v[192:195], v[18:21]
	v_mfma_f32_16x16x32_bf16 v[6:9], v[156:159], v[200:203], v[6:9]
	v_mfma_f32_16x16x32_bf16 v[2:5], v[164:167], v[200:203], v[2:5]
	v_mfma_f32_16x16x32_bf16 v[54:57], v[160:163], v[180:183], v[54:57]
	v_mfma_f32_16x16x32_bf16 v[50:53], v[168:171], v[180:183], v[50:53]
	v_mfma_f32_16x16x32_bf16 v[38:41], v[160:163], v[188:191], v[38:41]
	v_mfma_f32_16x16x32_bf16 v[34:37], v[168:171], v[188:191], v[34:37]
	v_mfma_f32_16x16x32_bf16 v[22:25], v[160:163], v[196:199], v[22:25]
	v_mfma_f32_16x16x32_bf16 v[18:21], v[168:171], v[196:199], v[18:21]
	v_mfma_f32_16x16x32_bf16 v[6:9], v[160:163], v[204:207], v[6:9]
	v_mfma_f32_16x16x32_bf16 v[2:5], v[168:171], v[204:207], v[2:5]
	s_barrier
	s_setprio 0
	s_add_u32 s77, s77, 0x100
	s_addc_u32 s78, s78, 0
	s_cmp_ge_i32 s79, s75
	s_mov_b64 s[36:37], s[38:39]
	s_mov_b32 s46, s79
	s_cbranch_scc0 .LBB0_1893
	v_readlane_b32 s2, v252, 14
	v_readlane_b32 s3, v252, 15
	s_and_b64 vcc, exec, s[2:3]
	s_cbranch_vccz .LBB0_1896
	s_barrier

; #define PG8_STAGE(bufoff, gbase, voff) do { _Pragma("unroll") for (int _i = 0; _i < 2; ++_i) \
;         __builtin_amdgcn_global_load_lds((const unsigned*)((const char*)(gbase) + (voff)[_i]), (LAS unsigned*)(lds + (bufoff) + ldsw + _i * 8192), 16, 0, 0); } while (0)
; #define PG8_LDA(dst, b, h) do { _Pragma("unroll") for (int m = 0; m < 4; ++m) _Pragma("unroll") for (int k = 0; k < 2; ++k) dst[m][k] = *(const LAS bf16x8*)(lds + PG8_SA(b, h) + aoff + m * 2048 + k * 1024); } while (0)
; #define PG8_LDB(dst, b, h) do { _Pragma("unroll") for (int n = 0; n < 2; ++n) _Pragma("unroll") for (int k = 0; k < 2; ++k) dst[n][k] = *(const LAS bf16x8*)(lds + PG8_SB(b, h) + boff + n * 2048 + k * 1024); } while (0)
; #define PG8_MMA(ai, bj, At, Bt) do { __builtin_amdgcn_s_setprio(1); _Pragma("unroll") for (int m = 0; m < 4; ++m) _Pragma("unroll") for (int n = 0; n < 2; ++n) _Pragma("unroll") for (int k = 0; k < 2; ++k) \
;         acc[ai][bj][m][n] = __builtin_amdgcn_mfma_f32_16x16x32_bf16(Bt[n][k], At[m][k], acc[ai][bj][m][n], 0, 0, 0); __builtin_amdgcn_s_setprio(0); } while (0)
; #define PG8_WAIT_V(n) asm volatile("s_waitcnt vmcnt(" #n ")" ::: "memory")
; #define PG8_WAIT_L(n) asm volatile("s_waitcnt lgkmcnt(" #n ")" ::: "memory")
; #define PG8_BAR __builtin_amdgcn_s_barrier()
; template <class Epi, class Sched, int LDA, int LDB, bool ALIGN_EPI = true>
; __device__ __forceinline__ void gemm_phase(LAS unsigned char* lds, const Gemm g, const Sched& S, const Epi& E, int wave) {
;     ...
;         for (int t = 0; t < nt; t += 2) {
;             const bool last = (t == nt - 2);
;             const char* a1 = cA + (size_t)(t + 1) * kstep;
;             const char* a2 = last ? nA : cA + (size_t)(t + 2) * kstep; const char* b2 = last ? nB : cB + (size_t)(t + 2) * kstep;
;             const char* a3 = a2 + kstep; const char* b3 = b2 + kstep;
;             PG8_LDB(B0, 0, 0); PG8_LDB(B1, 0, 1); PG8_SCHED; PG8_LDA(At, 0, 0); PG8_STAGE(PG8_SA(1, 1), a1 + hstepA, voffA);
;             PG8_WAIT_V(8); PG8_WAIT_L(0); PG8_BAR; PG8_MMA(0, 0, At, B0); PG8_MMA(0, 1, At, B1); PG8_BAR; PG8_SCHED;
;             PG8_LDA(At, 0, 1); PG8_STAGE(PG8_SB(0, 0), b2, voffB); PG8_STAGE(PG8_SB(0, 1), b2 + hstepB, voffB); PG8_STAGE(PG8_SA(0, 0), a2, voffA);
;             PG8_WAIT_V(8); PG8_WAIT_L(0); PG8_BAR; PG8_MMA(1, 0, At, B0); PG8_MMA(1, 1, At, B1); PG8_BAR; PG8_SCHED;
.LBB0_2254:
	s_add_u32 s2, s0, 0x100
	s_addc_u32 s3, s1, 0
	s_add_i32 s64, 0, 0x10000
	s_cmp_eq_u32 s59, 28
	s_cselect_b32 s29, s15, s3
	s_cselect_b32 s28, s14, s2
	s_cselect_b32 s25, s13, s58
	s_cselect_b32 s24, s48, s49
	s_add_i32 s65, 0, 0x14000
	v_lshl_add_u64 v[216:217], s[0:1], 0, v[140:141]
	s_add_i32 m0, s19, 0xc000
	s_nop 0
	global_load_lds_dwordx4 v[216:217], off
	v_lshl_add_u64 v[216:217], s[0:1], 0, v[142:143]
	s_add_i32 m0, s19, 0xe000
	s_nop 0
	global_load_lds_dwordx4 v[216:217], off
	v_add_u32_e32 v0, s64, v161
	ds_read_b128 v[144:147], v0
	ds_read_b128 v[148:151], v0 offset:1024
	ds_read_b128 v[152:155], v0 offset:2048
	ds_read_b128 v[156:159], v0 offset:3072
	v_add_u32_e32 v0, s65, v161
	ds_read_b128 v[164:167], v0
	ds_read_b128 v[168:171], v0 offset:1024
	ds_read_b128 v[172:175], v0 offset:2048
	ds_read_b128 v[180:183], v0 offset:3072
	ds_read_b128 v[184:187], v163
	ds_read_b128 v[188:191], v163 offset:1024
	ds_read_b128 v[192:195], v163 offset:2048
	ds_read_b128 v[196:199], v163 offset:3072
	ds_read_b128 v[200:203], v163 offset:4096
	ds_read_b128 v[204:207], v163 offset:5120
	ds_read_b128 v[208:211], v163 offset:6144
	ds_read_b128 v[212:215], v163 offset:7168
	s_waitcnt vmcnt(8)
	s_waitcnt lgkmcnt(0)
	s_setprio 1
	s_barrier
	v_mfma_f32_16x16x32_bf16 v[126:129], v[144:147], v[184:187], v[126:129]
	v_mfma_f32_16x16x32_bf16 v[122:125], v[152:155], v[184:187], v[122:125]
	v_mfma_f32_16x16x32_bf16 v[118:121], v[144:147], v[192:195], v[118:121]
	v_mfma_f32_16x16x32_bf16 v[114:117], v[152:155], v[192:195], v[114:117]
	v_mfma_f32_16x16x32_bf16 v[110:113], v[144:147], v[200:203], v[110:113]
	v_mfma_f32_16x16x32_bf16 v[106:109], v[152:155], v[200:203], v[106:109]
	v_mfma_f32_16x16x32_bf16 v[102:105], v[144:147], v[208:211], v[102:105]
	v_mfma_f32_16x16x32_bf16 v[98:101], v[152:155], v[208:211], v[98:101]
	v_mfma_f32_16x16x32_bf16 v[126:129], v[148:151], v[188:191], v[126:129]
	v_mfma_f32_16x16x32_bf16 v[122:125], v[156:159], v[188:191], v[122:125]
	v_mfma_f32_16x16x32_bf16 v[118:121], v[148:151], v[196:199], v[118:121]
	v_mfma_f32_16x16x32_bf16 v[114:117], v[156:159], v[196:199], v[114:117]
	v_mfma_f32_16x16x32_bf16 v[110:113], v[148:151], v[204:207], v[110:113]
	v_mfma_f32_16x16x32_bf16 v[106:109], v[156:159], v[204:207], v[106:109]
	v_mfma_f32_16x16x32_bf16 v[102:105], v[148:151], v[212:215], v[102:105]
	v_mfma_f32_16x16x32_bf16 v[98:101], v[156:159], v[212:215], v[98:101]
	v_mfma_f32_16x16x32_bf16 v[62:65], v[164:167], v[184:187], v[62:65]
	v_mfma_f32_16x16x32_bf16 v[58:61], v[172:175], v[184:187], v[58:61]
	v_mfma_f32_16x16x32_bf16 v[54:57], v[164:167], v[192:195], v[54:57]
	v_mfma_f32_16x16x32_bf16 v[50:53], v[172:175], v[192:195], v[50:53]
	v_mfma_f32_16x16x32_bf16 v[46:49], v[164:167], v[200:203], v[46:49]
	v_mfma_f32_16x16x32_bf16 v[42:45], v[172:175], v[200:203], v[42:45]
	v_mfma_f32_16x16x32_bf16 v[38:41], v[164:167], v[208:211], v[38:41]
	v_mfma_f32_16x16x32_bf16 v[34:37], v[172:175], v[208:211], v[34:37]
	v_mfma_f32_16x16x32_bf16 v[62:65], v[168:171], v[188:191], v[62:65]
	v_mfma_f32_16x16x32_bf16 v[58:61], v[180:183], v[188:191], v[58:61]
	v_mfma_f32_16x16x32_bf16 v[54:57], v[168:171], v[196:199], v[54:57]
	v_mfma_f32_16x16x32_bf16 v[50:53], v[180:183], v[196:199], v[50:53]
	v_mfma_f32_16x16x32_bf16 v[46:49], v[168:171], v[204:207], v[46:49]
	v_mfma_f32_16x16x32_bf16 v[42:45], v[180:183], v[204:207], v[42:45]
	v_mfma_f32_16x16x32_bf16 v[38:41], v[168:171], v[212:215], v[38:41]
	v_mfma_f32_16x16x32_bf16 v[34:37], v[180:183], v[212:215], v[34:37]
	s_barrier
	s_setprio 0
	s_add_i32 s0, s64, s61
	v_lshl_add_u64 v[216:217], s[24:25], 0, v[132:133]
	s_mov_b32 m0, s0
	s_nop 0
	global_load_lds_dwordx4 v[216:217], off
	s_add_i32 m0, s0, 0x2000
	s_add_u32 s0, s24, 0x80000
	v_lshl_add_u64 v[218:219], s[24:25], 0, v[136:137]
	s_addc_u32 s1, s25, 0
	s_add_i32 s64, s65, s61
	global_load_lds_dwordx4 v[218:219], off
	v_lshl_add_u64 v[220:221], s[0:1], 0, v[132:133]
	s_mov_b32 m0, s64
	v_lshl_add_u64 v[222:223], s[28:29], 0, v[134:135]
	global_load_lds_dwordx4 v[220:221], off
	v_lshl_add_u64 v[220:221], s[0:1], 0, v[136:137]
	s_add_i32 m0, s64, 0x2000
	s_nop 0
	global_load_lds_dwordx4 v[220:221], off
	v_lshl_add_u64 v[220:221], s[28:29], 0, v[130:131]
	s_mov_b32 m0, s19
	s_nop 0
	global_load_lds_dwordx4 v[220:221], off
	s_mov_b32 m0, s35
	s_nop 0
	global_load_lds_dwordx4 v[222:223], off
	ds_read_b128 v[184:187], v163 offset:16384
	ds_read_b128 v[188:191], v163 offset:17408
	ds_read_b128 v[192:195], v163 offset:18432
	ds_read_b128 v[196:199], v163 offset:19456
	ds_read_b128 v[200:203], v163 offset:20480
	ds_read_b128 v[204:207], v163 offset:21504
	ds_read_b128 v[208:211], v163 offset:22528
	ds_read_b128 v[212:215], v163 offset:23552
	s_waitcnt vmcnt(8)
	s_waitcnt lgkmcnt(0)
	s_setprio 1
	s_barrier
; #define PG8_STAGE(bufoff, gbase, voff) do { _Pragma("unroll") for (int _i = 0; _i < 2; ++_i) \
;         __builtin_amdgcn_global_load_lds((const unsigned*)((const char*)(gbase) + (voff)[_i]), (LAS unsigned*)(lds + (bufoff) + ldsw + _i * 8192), 16, 0, 0); } while (0)
; #define PG8_LDA(dst, b, h) do { _Pragma("unroll") for (int m = 0; m < 4; ++m) _Pragma("unroll") for (int k = 0; k < 2; ++k) dst[m][k] = *(const LAS bf16x8*)(lds + PG8_SA(b, h) + aoff + m * 2048 + k * 1024); } while (0)
; #define PG8_LDB(dst, b, h) do { _Pragma("unroll") for (int n = 0; n < 2; ++n) _Pragma("unroll") for (int k = 0; k < 2; ++k) dst[n][k] = *(const LAS bf16x8*)(lds + PG8_SB(b, h) + boff + n * 2048 + k * 1024); } while (0)
; #define PG8_MMA(ai, bj, At, Bt) do { __builtin_amdgcn_s_setprio(1); _Pragma("unroll") for (int m = 0; m < 4; ++m) _Pragma("unroll") for (int n = 0; n < 2; ++n) _Pragma("unroll") for (int k = 0; k < 2; ++k) \
;         acc[ai][bj][m][n] = __builtin_amdgcn_mfma_f32_16x16x32_bf16(Bt[n][k], At[m][k], acc[ai][bj][m][n], 0, 0, 0); __builtin_amdgcn_s_setprio(0); } while (0)
; #define PG8_WAIT_V(n) asm volatile("s_waitcnt vmcnt(" #n ")" ::: "memory")
; #define PG8_WAIT_L(n) asm volatile("s_waitcnt lgkmcnt(" #n ")" ::: "memory")
; #define PG8_BAR __builtin_amdgcn_s_barrier()
; #define PG8_SCHED __builtin_amdgcn_sched_barrier(0)
; template <class Epi, class Sched, int LDA, int LDB, bool ALIGN_EPI = true>
; __device__ __forceinline__ void gemm_phase(LAS unsigned char* lds, const Gemm g, const Sched& S, const Epi& E, int wave) {
;     ...
;             PG8_WAIT_V(8); PG8_WAIT_L(0); PG8_BAR; PG8_MMA(1, 0, At, B0); PG8_MMA(1, 1, At, B1); PG8_BAR; PG8_SCHED;
;             PG8_LDB(B0, 1, 0); PG8_LDB(B1, 1, 1); PG8_SCHED; PG8_LDA(At, 1, 0); PG8_STAGE(PG8_SA(0, 1), a2 + hstepA, voffA);
;             PG8_WAIT_V(8); PG8_WAIT_L(0); PG8_BAR; PG8_MMA(0, 0, At, B0); PG8_MMA(0, 1, At, B1); PG8_BAR; PG8_SCHED;
	v_mfma_f32_16x16x32_bf16 v[94:97], v[144:147], v[184:187], v[94:97]
	v_mfma_f32_16x16x32_bf16 v[90:93], v[152:155], v[184:187], v[90:93]
	v_mfma_f32_16x16x32_bf16 v[86:89], v[144:147], v[192:195], v[86:89]
	v_mfma_f32_16x16x32_bf16 v[82:85], v[152:155], v[192:195], v[82:85]
	v_mfma_f32_16x16x32_bf16 v[78:81], v[144:147], v[200:203], v[78:81]
	v_mfma_f32_16x16x32_bf16 v[74:77], v[152:155], v[200:203], v[74:77]
	v_mfma_f32_16x16x32_bf16 v[70:73], v[144:147], v[208:211], v[70:73]
	v_mfma_f32_16x16x32_bf16 v[66:69], v[152:155], v[208:211], v[66:69]
	v_mfma_f32_16x16x32_bf16 v[94:97], v[148:151], v[188:191], v[94:97]
	v_mfma_f32_16x16x32_bf16 v[90:93], v[156:159], v[188:191], v[90:93]
	v_mfma_f32_16x16x32_bf16 v[86:89], v[148:151], v[196:199], v[86:89]
	v_mfma_f32_16x16x32_bf16 v[82:85], v[156:159], v[196:199], v[82:85]
	v_mfma_f32_16x16x32_bf16 v[78:81], v[148:151], v[204:207], v[78:81]
	v_mfma_f32_16x16x32_bf16 v[74:77], v[156:159], v[204:207], v[74:77]
	v_mfma_f32_16x16x32_bf16 v[70:73], v[148:151], v[212:215], v[70:73]
	v_mfma_f32_16x16x32_bf16 v[66:69], v[156:159], v[212:215], v[66:69]
	v_mfma_f32_16x16x32_bf16 v[30:33], v[164:167], v[184:187], v[30:33]
	v_mfma_f32_16x16x32_bf16 v[26:29], v[172:175], v[184:187], v[26:29]
	v_mfma_f32_16x16x32_bf16 v[22:25], v[164:167], v[192:195], v[22:25]
	v_mfma_f32_16x16x32_bf16 v[18:21], v[172:175], v[192:195], v[18:21]
	v_mfma_f32_16x16x32_bf16 v[14:17], v[164:167], v[200:203], v[14:17]
	v_mfma_f32_16x16x32_bf16 v[10:13], v[172:175], v[200:203], v[10:13]
	v_mfma_f32_16x16x32_bf16 v[6:9], v[164:167], v[208:211], v[6:9]
	v_mfma_f32_16x16x32_bf16 v[2:5], v[172:175], v[208:211], v[2:5]
	v_mfma_f32_16x16x32_bf16 v[30:33], v[168:171], v[188:191], v[30:33]
	v_mfma_f32_16x16x32_bf16 v[26:29], v[180:183], v[188:191], v[26:29]
	v_mfma_f32_16x16x32_bf16 v[22:25], v[168:171], v[196:199], v[22:25]
	v_mfma_f32_16x16x32_bf16 v[18:21], v[180:183], v[196:199], v[18:21]
	v_mfma_f32_16x16x32_bf16 v[14:17], v[168:171], v[204:207], v[14:17]
	v_mfma_f32_16x16x32_bf16 v[10:13], v[180:183], v[204:207], v[10:13]
	v_mfma_f32_16x16x32_bf16 v[6:9], v[168:171], v[212:215], v[6:9]
	v_mfma_f32_16x16x32_bf16 v[2:5], v[180:183], v[212:215], v[2:5]
	s_barrier
	s_setprio 0
	s_add_i32 s64, 0, 0x18000
	s_add_i32 s65, 0, 0x1c000
	s_add_u32 s0, s28, 0x84000
	s_addc_u32 s1, s29, 0
	s_mov_b32 m0, s36
	v_lshl_add_u64 v[224:225], s[0:1], 0, v[130:131]
	global_load_lds_dwordx4 v[224:225], off
	v_lshl_add_u64 v[224:225], s[0:1], 0, v[134:135]
	s_mov_b32 m0, s37
	s_nop 0
	global_load_lds_dwordx4 v[224:225], off
	v_add_u32_e32 v0, s64, v161
	ds_read_b128 v[144:147], v0
	ds_read_b128 v[148:151], v0 offset:1024
	ds_read_b128 v[152:155], v0 offset:2048
	ds_read_b128 v[156:159], v0 offset:3072
	v_add_u32_e32 v0, s65, v161
	ds_read_b128 v[164:167], v0
	ds_read_b128 v[168:171], v0 offset:1024
	ds_read_b128 v[172:175], v0 offset:2048
	ds_read_b128 v[180:183], v0 offset:3072
	ds_read_b128 v[184:187], v163 offset:32768
	ds_read_b128 v[188:191], v163 offset:33792
	ds_read_b128 v[192:195], v163 offset:34816
	ds_read_b128 v[196:199], v163 offset:35840
	ds_read_b128 v[200:203], v163 offset:36864
	ds_read_b128 v[204:207], v163 offset:37888
	ds_read_b128 v[208:211], v163 offset:38912
	ds_read_b128 v[212:215], v163 offset:39936
	s_waitcnt vmcnt(8)
	s_waitcnt lgkmcnt(0)
	s_setprio 1
	s_barrier
	v_mfma_f32_16x16x32_bf16 v[126:129], v[144:147], v[184:187], v[126:129]
	v_mfma_f32_16x16x32_bf16 v[122:125], v[152:155], v[184:187], v[122:125]
	v_mfma_f32_16x16x32_bf16 v[118:121], v[144:147], v[192:195], v[118:121]
	v_mfma_f32_16x16x32_bf16 v[114:117], v[152:155], v[192:195], v[114:117]
	v_mfma_f32_16x16x32_bf16 v[110:113], v[144:147], v[200:203], v[110:113]
	v_mfma_f32_16x16x32_bf16 v[106:109], v[152:155], v[200:203], v[106:109]
	v_mfma_f32_16x16x32_bf16 v[102:105], v[144:147], v[208:211], v[102:105]
	v_mfma_f32_16x16x32_bf16 v[98:101], v[152:155], v[208:211], v[98:101]
	v_mfma_f32_16x16x32_bf16 v[126:129], v[148:151], v[188:191], v[126:129]
	v_mfma_f32_16x16x32_bf16 v[122:125], v[156:159], v[188:191], v[122:125]
	v_mfma_f32_16x16x32_bf16 v[118:121], v[148:151], v[196:199], v[118:121]
	v_mfma_f32_16x16x32_bf16 v[114:117], v[156:159], v[196:199], v[114:117]
	v_mfma_f32_16x16x32_bf16 v[110:113], v[148:151], v[204:207], v[110:113]
	v_mfma_f32_16x16x32_bf16 v[106:109], v[156:159], v[204:207], v[106:109]
	v_mfma_f32_16x16x32_bf16 v[102:105], v[148:151], v[212:215], v[102:105]
	v_mfma_f32_16x16x32_bf16 v[98:101], v[156:159], v[212:215], v[98:101]
	v_mfma_f32_16x16x32_bf16 v[62:65], v[164:167], v[184:187], v[62:65]
	v_mfma_f32_16x16x32_bf16 v[58:61], v[172:175], v[184:187], v[58:61]
	v_mfma_f32_16x16x32_bf16 v[54:57], v[164:167], v[192:195], v[54:57]
	v_mfma_f32_16x16x32_bf16 v[50:53], v[172:175], v[192:195], v[50:53]
	v_mfma_f32_16x16x32_bf16 v[46:49], v[164:167], v[200:203], v[46:49]
	v_mfma_f32_16x16x32_bf16 v[42:45], v[172:175], v[200:203], v[42:45]
	v_mfma_f32_16x16x32_bf16 v[38:41], v[164:167], v[208:211], v[38:41]
	v_mfma_f32_16x16x32_bf16 v[34:37], v[172:175], v[208:211], v[34:37]
	v_mfma_f32_16x16x32_bf16 v[62:65], v[168:171], v[188:191], v[62:65]
	v_mfma_f32_16x16x32_bf16 v[58:61], v[180:183], v[188:191], v[58:61]
	v_mfma_f32_16x16x32_bf16 v[54:57], v[168:171], v[196:199], v[54:57]
	v_mfma_f32_16x16x32_bf16 v[50:53], v[180:183], v[196:199], v[50:53]
	v_mfma_f32_16x16x32_bf16 v[46:49], v[168:171], v[204:207], v[46:49]
	v_mfma_f32_16x16x32_bf16 v[42:45], v[180:183], v[204:207], v[42:45]
	v_mfma_f32_16x16x32_bf16 v[38:41], v[168:171], v[212:215], v[38:41]
	v_mfma_f32_16x16x32_bf16 v[34:37], v[180:183], v[212:215], v[34:37]
	s_barrier
; #define PG8_STAGE(bufoff, gbase, voff) do { _Pragma("unroll") for (int _i = 0; _i < 2; ++_i) \
;         __builtin_amdgcn_global_load_lds((const unsigned*)((const char*)(gbase) + (voff)[_i]), (LAS unsigned*)(lds + (bufoff) + ldsw + _i * 8192), 16, 0, 0); } while (0)
; #define PG8_LDA(dst, b, h) do { _Pragma("unroll") for (int m = 0; m < 4; ++m) _Pragma("unroll") for (int k = 0; k < 2; ++k) dst[m][k] = *(const LAS bf16x8*)(lds + PG8_SA(b, h) + aoff + m * 2048 + k * 1024); } while (0)
; #define PG8_MMA(ai, bj, At, Bt) do { __builtin_amdgcn_s_setprio(1); _Pragma("unroll") for (int m = 0; m < 4; ++m) _Pragma("unroll") for (int n = 0; n < 2; ++n) _Pragma("unroll") for (int k = 0; k < 2; ++k) \
;         acc[ai][bj][m][n] = __builtin_amdgcn_mfma_f32_16x16x32_bf16(Bt[n][k], At[m][k], acc[ai][bj][m][n], 0, 0, 0); __builtin_amdgcn_s_setprio(0); } while (0)
; #define PG8_WAIT_V(n) asm volatile("s_waitcnt vmcnt(" #n ")" ::: "memory")
; #define PG8_WAIT_L(n) asm volatile("s_waitcnt lgkmcnt(" #n ")" ::: "memory")
; #define PG8_BAR __builtin_amdgcn_s_barrier()
; #define PG8_SCHED __builtin_amdgcn_sched_barrier(0)
; template <class Epi, class Sched, int LDA, int LDB, bool ALIGN_EPI = true>
; __device__ __forceinline__ void gemm_phase(LAS unsigned char* lds, const Gemm g, const Sched& S, const Epi& E, int wave) {
;     ...
;             PG8_LDA(At, 1, 1); PG8_STAGE(PG8_SB(1, 0), b3, voffB); PG8_STAGE(PG8_SB(1, 1), b3 + hstepB, voffB); PG8_STAGE(PG8_SA(1, 0), a3, voffA);
;             PG8_WAIT_V(8); PG8_WAIT_L(0); PG8_BAR; PG8_MMA(1, 0, At, B0); PG8_MMA(1, 1, At, B1); PG8_BAR; PG8_SCHED;
;         }
	s_setprio 0
	s_add_i32 s0, s64, s61
	v_lshl_add_u64 v[216:217], v[216:217], 0, s[70:71]
	s_mov_b32 m0, s0
	s_nop 0
	global_load_lds_dwordx4 v[216:217], off
	s_add_i32 m0, s0, 0x2000
	s_add_u32 s0, s24, 0x80080
	v_lshl_add_u64 v[216:217], v[218:219], 0, s[70:71]
	s_addc_u32 s1, s25, 0
	s_add_i32 s24, s65, s61
	global_load_lds_dwordx4 v[216:217], off
	v_lshl_add_u64 v[216:217], s[0:1], 0, v[132:133]
	s_mov_b32 m0, s24
	s_nop 0
	global_load_lds_dwordx4 v[216:217], off
	v_lshl_add_u64 v[216:217], s[0:1], 0, v[136:137]
	s_add_i32 m0, s24, 0x2000
	s_nop 0
	global_load_lds_dwordx4 v[216:217], off
	v_lshl_add_u64 v[216:217], v[220:221], 0, s[70:71]
	s_mov_b32 m0, s38
	s_nop 0
	global_load_lds_dwordx4 v[216:217], off
	v_lshl_add_u64 v[216:217], v[222:223], 0, s[70:71]
	s_mov_b32 m0, s39
	s_nop 0
	global_load_lds_dwordx4 v[216:217], off
	ds_read_b128 v[184:187], v163 offset:49152
	ds_read_b128 v[188:191], v163 offset:50176
	ds_read_b128 v[192:195], v163 offset:51200
	ds_read_b128 v[196:199], v163 offset:52224
	ds_read_b128 v[200:203], v163 offset:53248
	ds_read_b128 v[204:207], v163 offset:54272
	ds_read_b128 v[208:211], v163 offset:55296
	ds_read_b128 v[212:215], v163 offset:56320
	s_waitcnt vmcnt(8)
	s_waitcnt lgkmcnt(0)
	s_setprio 1
	s_barrier
	v_mfma_f32_16x16x32_bf16 v[94:97], v[144:147], v[184:187], v[94:97]
	v_mfma_f32_16x16x32_bf16 v[90:93], v[152:155], v[184:187], v[90:93]
	v_mfma_f32_16x16x32_bf16 v[86:89], v[144:147], v[192:195], v[86:89]
	v_mfma_f32_16x16x32_bf16 v[82:85], v[152:155], v[192:195], v[82:85]
	v_mfma_f32_16x16x32_bf16 v[78:81], v[144:147], v[200:203], v[78:81]
	v_mfma_f32_16x16x32_bf16 v[74:77], v[152:155], v[200:203], v[74:77]
	v_mfma_f32_16x16x32_bf16 v[70:73], v[144:147], v[208:211], v[70:73]
	v_mfma_f32_16x16x32_bf16 v[66:69], v[152:155], v[208:211], v[66:69]
	v_mfma_f32_16x16x32_bf16 v[94:97], v[148:151], v[188:191], v[94:97]
	v_mfma_f32_16x16x32_bf16 v[90:93], v[156:159], v[188:191], v[90:93]
	v_mfma_f32_16x16x32_bf16 v[86:89], v[148:151], v[196:199], v[86:89]
	v_mfma_f32_16x16x32_bf16 v[82:85], v[156:159], v[196:199], v[82:85]
	v_mfma_f32_16x16x32_bf16 v[78:81], v[148:151], v[204:207], v[78:81]
	v_mfma_f32_16x16x32_bf16 v[74:77], v[156:159], v[204:207], v[74:77]
	v_mfma_f32_16x16x32_bf16 v[70:73], v[148:151], v[212:215], v[70:73]
	v_mfma_f32_16x16x32_bf16 v[66:69], v[156:159], v[212:215], v[66:69]
	v_mfma_f32_16x16x32_bf16 v[30:33], v[164:167], v[184:187], v[30:33]
	v_mfma_f32_16x16x32_bf16 v[26:29], v[172:175], v[184:187], v[26:29]
	v_mfma_f32_16x16x32_bf16 v[22:25], v[164:167], v[192:195], v[22:25]
	v_mfma_f32_16x16x32_bf16 v[18:21], v[172:175], v[192:195], v[18:21]
	v_mfma_f32_16x16x32_bf16 v[14:17], v[164:167], v[200:203], v[14:17]
	v_mfma_f32_16x16x32_bf16 v[10:13], v[172:175], v[200:203], v[10:13]
	v_mfma_f32_16x16x32_bf16 v[6:9], v[164:167], v[208:211], v[6:9]
	v_mfma_f32_16x16x32_bf16 v[2:5], v[172:175], v[208:211], v[2:5]
	v_mfma_f32_16x16x32_bf16 v[30:33], v[168:171], v[188:191], v[30:33]
	v_mfma_f32_16x16x32_bf16 v[26:29], v[180:183], v[188:191], v[26:29]
	v_mfma_f32_16x16x32_bf16 v[22:25], v[168:171], v[196:199], v[22:25]
	v_mfma_f32_16x16x32_bf16 v[18:21], v[180:183], v[196:199], v[18:21]
	v_mfma_f32_16x16x32_bf16 v[14:17], v[168:171], v[204:207], v[14:17]
	v_mfma_f32_16x16x32_bf16 v[10:13], v[180:183], v[204:207], v[10:13]
	v_mfma_f32_16x16x32_bf16 v[6:9], v[168:171], v[212:215], v[6:9]
	v_mfma_f32_16x16x32_bf16 v[2:5], v[180:183], v[212:215], v[2:5]
	s_barrier
	s_setprio 0
	s_add_i32 s59, s59, 2
	s_add_u32 s49, s49, 0x100
	s_addc_u32 s58, s58, 0
	s_cmp_gt_u32 s59, 29
	s_mov_b64 s[0:1], s[2:3]
	s_cbranch_scc0 .LBB0_2254
	v_readlane_b32 s0, v252, 14
	v_readlane_b32 s1, v252, 15
	s_and_b64 vcc, exec, s[0:1]
	s_cbranch_vccz .LBB0_2257
	s_barrier

; #define PG8_STAGE(bufoff, gbase, voff) do { _Pragma("unroll") for (int _i = 0; _i < 2; ++_i) \
;         __builtin_amdgcn_global_load_lds((const unsigned*)((const char*)(gbase) + (voff)[_i]), (LAS unsigned*)(lds + (bufoff) + ldsw + _i * 8192), 16, 0, 0); } while (0)
; #define PG8_LDA(dst, b, h) do { _Pragma("unroll") for (int m = 0; m < 4; ++m) _Pragma("unroll") for (int k = 0; k < 2; ++k) dst[m][k] = *(const LAS bf16x8*)(lds + PG8_SA(b, h) + aoff + m * 2048 + k * 1024); } while (0)
; #define PG8_LDB(dst, b, h) do { _Pragma("unroll") for (int n = 0; n < 2; ++n) _Pragma("unroll") for (int k = 0; k < 2; ++k) dst[n][k] = *(const LAS bf16x8*)(lds + PG8_SB(b, h) + boff + n * 2048 + k * 1024); } while (0)
; #define PG8_MMA(ai, bj, At, Bt) do { __builtin_amdgcn_s_setprio(1); _Pragma("unroll") for (int m = 0; m < 4; ++m) _Pragma("unroll") for (int n = 0; n < 2; ++n) _Pragma("unroll") for (int k = 0; k < 2; ++k) \
;         acc[ai][bj][m][n] = __builtin_amdgcn_mfma_f32_16x16x32_bf16(Bt[n][k], At[m][k], acc[ai][bj][m][n], 0, 0, 0); __builtin_amdgcn_s_setprio(0); } while (0)
; #define PG8_WAIT_V(n) asm volatile("s_waitcnt vmcnt(" #n ")" ::: "memory")
; #define PG8_WAIT_L(n) asm volatile("s_waitcnt lgkmcnt(" #n ")" ::: "memory")
; #define PG8_BAR __builtin_amdgcn_s_barrier()
; template <class Epi, class Sched, int LDA, int LDB, bool ALIGN_EPI = true>
; __device__ __forceinline__ void gemm_phase(LAS unsigned char* lds, const Gemm g, const Sched& S, const Epi& E, int wave) {
;     ...
;         for (int t = 0; t < nt; t += 2) {
;             const bool last = (t == nt - 2);
;             const char* a1 = cA + (size_t)(t + 1) * kstep;
;             const char* a2 = last ? nA : cA + (size_t)(t + 2) * kstep; const char* b2 = last ? nB : cB + (size_t)(t + 2) * kstep;
;             const char* a3 = a2 + kstep; const char* b3 = b2 + kstep;
;             PG8_LDB(B0, 0, 0); PG8_LDB(B1, 0, 1); PG8_SCHED; PG8_LDA(At, 0, 0); PG8_STAGE(PG8_SA(1, 1), a1 + hstepA, voffA);
;             PG8_WAIT_V(8); PG8_WAIT_L(0); PG8_BAR; PG8_MMA(0, 0, At, B0); PG8_MMA(0, 1, At, B1); PG8_BAR; PG8_SCHED;
;             PG8_LDA(At, 0, 1); PG8_STAGE(PG8_SB(0, 0), b2, voffB); PG8_STAGE(PG8_SB(0, 1), b2 + hstepB, voffB); PG8_STAGE(PG8_SA(0, 0), a2, voffA);
;             PG8_WAIT_V(8); PG8_WAIT_L(0); PG8_BAR; PG8_MMA(1, 0, At, B0); PG8_MMA(1, 1, At, B1); PG8_BAR; PG8_SCHED;
.LBB0_2415:
	s_add_u32 s12, s10, 0xfff80080
	s_addc_u32 s13, s11, -1
	s_add_i32 s39, 0, 0x10000
	s_cmp_eq_u32 s38, 28
	s_cselect_b32 s15, s1, s13
	s_cselect_b32 s14, s3, s12
	s_cselect_b32 s13, s7, s37
	s_cselect_b32 s12, s6, s36
	s_add_i32 s46, 0, 0x14000
	v_lshl_add_u64 v[140:141], s[10:11], 0, v[136:137]
	s_add_i32 m0, s18, 0xc000
	s_nop 0
	global_load_lds_dwordx4 v[140:141], off
	v_lshl_add_u64 v[140:141], s[10:11], 0, v[138:139]
	s_add_i32 m0, s18, 0xe000
	s_nop 0
	global_load_lds_dwordx4 v[140:141], off
	v_add_u32_e32 v140, s39, v143
	ds_read_b128 v[146:149], v140
	ds_read_b128 v[150:153], v140 offset:1024
	ds_read_b128 v[154:157], v140 offset:2048
	ds_read_b128 v[158:161], v140 offset:3072
	v_add_u32_e32 v140, s46, v143
	ds_read_b128 v[162:165], v140
	ds_read_b128 v[166:169], v140 offset:1024
	ds_read_b128 v[170:173], v140 offset:2048
	ds_read_b128 v[180:183], v140 offset:3072
	ds_read_b128 v[184:187], v145
	ds_read_b128 v[188:191], v145 offset:1024
	ds_read_b128 v[192:195], v145 offset:2048
	ds_read_b128 v[196:199], v145 offset:3072
	ds_read_b128 v[200:203], v145 offset:4096
	ds_read_b128 v[204:207], v145 offset:5120
	ds_read_b128 v[208:211], v145 offset:6144
	ds_read_b128 v[212:215], v145 offset:7168
	s_waitcnt vmcnt(8)
	s_waitcnt lgkmcnt(0)
	s_setprio 1
	s_barrier
	v_mfma_f32_16x16x32_bf16 v[126:129], v[146:149], v[184:187], v[126:129]
	v_mfma_f32_16x16x32_bf16 v[122:125], v[154:157], v[184:187], v[122:125]
	v_mfma_f32_16x16x32_bf16 v[114:117], v[146:149], v[192:195], v[114:117]
	v_mfma_f32_16x16x32_bf16 v[106:109], v[154:157], v[192:195], v[106:109]
	v_mfma_f32_16x16x32_bf16 v[98:101], v[146:149], v[200:203], v[98:101]
	v_mfma_f32_16x16x32_bf16 v[90:93], v[154:157], v[200:203], v[90:93]
	v_mfma_f32_16x16x32_bf16 v[82:85], v[146:149], v[208:211], v[82:85]
	v_mfma_f32_16x16x32_bf16 v[74:77], v[154:157], v[208:211], v[74:77]
	v_mfma_f32_16x16x32_bf16 v[126:129], v[150:153], v[188:191], v[126:129]
	v_mfma_f32_16x16x32_bf16 v[122:125], v[158:161], v[188:191], v[122:125]
	v_mfma_f32_16x16x32_bf16 v[114:117], v[150:153], v[196:199], v[114:117]
	v_mfma_f32_16x16x32_bf16 v[106:109], v[158:161], v[196:199], v[106:109]
	v_mfma_f32_16x16x32_bf16 v[98:101], v[150:153], v[204:207], v[98:101]
	v_mfma_f32_16x16x32_bf16 v[90:93], v[158:161], v[204:207], v[90:93]
	v_mfma_f32_16x16x32_bf16 v[82:85], v[150:153], v[212:215], v[82:85]
	v_mfma_f32_16x16x32_bf16 v[74:77], v[158:161], v[212:215], v[74:77]
	v_mfma_f32_16x16x32_bf16 v[118:121], v[162:165], v[184:187], v[118:121]
	v_mfma_f32_16x16x32_bf16 v[110:113], v[170:173], v[184:187], v[110:113]
	v_mfma_f32_16x16x32_bf16 v[102:105], v[162:165], v[192:195], v[102:105]
	v_mfma_f32_16x16x32_bf16 v[94:97], v[170:173], v[192:195], v[94:97]
	v_mfma_f32_16x16x32_bf16 v[86:89], v[162:165], v[200:203], v[86:89]
	v_mfma_f32_16x16x32_bf16 v[78:81], v[170:173], v[200:203], v[78:81]
	v_mfma_f32_16x16x32_bf16 v[70:73], v[162:165], v[208:211], v[70:73]
	v_mfma_f32_16x16x32_bf16 v[66:69], v[170:173], v[208:211], v[66:69]
	v_mfma_f32_16x16x32_bf16 v[118:121], v[166:169], v[188:191], v[118:121]
	v_mfma_f32_16x16x32_bf16 v[110:113], v[180:183], v[188:191], v[110:113]
	v_mfma_f32_16x16x32_bf16 v[102:105], v[166:169], v[196:199], v[102:105]
	v_mfma_f32_16x16x32_bf16 v[94:97], v[180:183], v[196:199], v[94:97]
	v_mfma_f32_16x16x32_bf16 v[86:89], v[166:169], v[204:207], v[86:89]
	v_mfma_f32_16x16x32_bf16 v[78:81], v[180:183], v[204:207], v[78:81]
	v_mfma_f32_16x16x32_bf16 v[70:73], v[166:169], v[212:215], v[70:73]
	v_mfma_f32_16x16x32_bf16 v[66:69], v[180:183], v[212:215], v[66:69]
	s_barrier
	s_setprio 0
	s_add_i32 s39, s39, s47
	v_lshl_add_u64 v[140:141], s[12:13], 0, v[0:1]
	s_mov_b32 m0, s39
	s_nop 0
	global_load_lds_dwordx4 v[140:141], off
	s_add_i32 m0, s39, 0x2000
	s_add_u32 s44, s12, 0x84000
	v_lshl_add_u64 v[174:175], s[12:13], 0, v[134:135]
	s_addc_u32 s45, s13, 0
	s_add_i32 s39, s46, s47
	global_load_lds_dwordx4 v[174:175], off
	v_lshl_add_u64 v[216:217], s[44:45], 0, v[0:1]
	s_mov_b32 m0, s39
	v_lshl_add_u64 v[218:219], s[14:15], 0, v[132:133]
	global_load_lds_dwordx4 v[216:217], off
	v_lshl_add_u64 v[216:217], s[44:45], 0, v[134:135]
	s_add_i32 m0, s39, 0x2000
	s_nop 0
	global_load_lds_dwordx4 v[216:217], off
	v_lshl_add_u64 v[216:217], s[14:15], 0, v[130:131]
	s_mov_b32 m0, s18
	s_nop 0
	global_load_lds_dwordx4 v[216:217], off
	s_mov_b32 m0, s19
	s_nop 0
	global_load_lds_dwordx4 v[218:219], off
	ds_read_b128 v[184:187], v145 offset:16384
	ds_read_b128 v[188:191], v145 offset:17408
	ds_read_b128 v[192:195], v145 offset:18432
	ds_read_b128 v[196:199], v145 offset:19456
	ds_read_b128 v[200:203], v145 offset:20480
	ds_read_b128 v[204:207], v145 offset:21504
	ds_read_b128 v[208:211], v145 offset:22528
	ds_read_b128 v[212:215], v145 offset:23552
	s_waitcnt vmcnt(8)
	s_waitcnt lgkmcnt(0)
	s_setprio 1
	s_barrier
; #define PG8_STAGE(bufoff, gbase, voff) do { _Pragma("unroll") for (int _i = 0; _i < 2; ++_i) \
;         __builtin_amdgcn_global_load_lds((const unsigned*)((const char*)(gbase) + (voff)[_i]), (LAS unsigned*)(lds + (bufoff) + ldsw + _i * 8192), 16, 0, 0); } while (0)
; #define PG8_LDA(dst, b, h) do { _Pragma("unroll") for (int m = 0; m < 4; ++m) _Pragma("unroll") for (int k = 0; k < 2; ++k) dst[m][k] = *(const LAS bf16x8*)(lds + PG8_SA(b, h) + aoff + m * 2048 + k * 1024); } while (0)
; #define PG8_LDB(dst, b, h) do { _Pragma("unroll") for (int n = 0; n < 2; ++n) _Pragma("unroll") for (int k = 0; k < 2; ++k) dst[n][k] = *(const LAS bf16x8*)(lds + PG8_SB(b, h) + boff + n * 2048 + k * 1024); } while (0)
; #define PG8_MMA(ai, bj, At, Bt) do { __builtin_amdgcn_s_setprio(1); _Pragma("unroll") for (int m = 0; m < 4; ++m) _Pragma("unroll") for (int n = 0; n < 2; ++n) _Pragma("unroll") for (int k = 0; k < 2; ++k) \
;         acc[ai][bj][m][n] = __builtin_amdgcn_mfma_f32_16x16x32_bf16(Bt[n][k], At[m][k], acc[ai][bj][m][n], 0, 0, 0); __builtin_amdgcn_s_setprio(0); } while (0)
; #define PG8_WAIT_V(n) asm volatile("s_waitcnt vmcnt(" #n ")" ::: "memory")
; #define PG8_WAIT_L(n) asm volatile("s_waitcnt lgkmcnt(" #n ")" ::: "memory")
; #define PG8_BAR __builtin_amdgcn_s_barrier()
; #define PG8_SCHED __builtin_amdgcn_sched_barrier(0)
; template <class Epi, class Sched, int LDA, int LDB, bool ALIGN_EPI = true>
; __device__ __forceinline__ void gemm_phase(LAS unsigned char* lds, const Gemm g, const Sched& S, const Epi& E, int wave) {
;     ...
;             PG8_WAIT_V(8); PG8_WAIT_L(0); PG8_BAR; PG8_MMA(1, 0, At, B0); PG8_MMA(1, 1, At, B1); PG8_BAR; PG8_SCHED;
;             PG8_LDB(B0, 1, 0); PG8_LDB(B1, 1, 1); PG8_SCHED; PG8_LDA(At, 1, 0); PG8_STAGE(PG8_SA(0, 1), a2 + hstepA, voffA);
;             PG8_WAIT_V(8); PG8_WAIT_L(0); PG8_BAR; PG8_MMA(0, 0, At, B0); PG8_MMA(0, 1, At, B1); PG8_BAR; PG8_SCHED;
	v_mfma_f32_16x16x32_bf16 v[62:65], v[146:149], v[184:187], v[62:65]
	v_mfma_f32_16x16x32_bf16 v[58:61], v[154:157], v[184:187], v[58:61]
	v_mfma_f32_16x16x32_bf16 v[50:53], v[146:149], v[192:195], v[50:53]
	v_mfma_f32_16x16x32_bf16 v[42:45], v[154:157], v[192:195], v[42:45]
	v_mfma_f32_16x16x32_bf16 v[34:37], v[146:149], v[200:203], v[34:37]
	v_mfma_f32_16x16x32_bf16 v[26:29], v[154:157], v[200:203], v[26:29]
	v_mfma_f32_16x16x32_bf16 v[18:21], v[146:149], v[208:211], v[18:21]
	v_mfma_f32_16x16x32_bf16 v[10:13], v[154:157], v[208:211], v[10:13]
	v_mfma_f32_16x16x32_bf16 v[62:65], v[150:153], v[188:191], v[62:65]
	v_mfma_f32_16x16x32_bf16 v[58:61], v[158:161], v[188:191], v[58:61]
	v_mfma_f32_16x16x32_bf16 v[50:53], v[150:153], v[196:199], v[50:53]
	v_mfma_f32_16x16x32_bf16 v[42:45], v[158:161], v[196:199], v[42:45]
	v_mfma_f32_16x16x32_bf16 v[34:37], v[150:153], v[204:207], v[34:37]
	v_mfma_f32_16x16x32_bf16 v[26:29], v[158:161], v[204:207], v[26:29]
	v_mfma_f32_16x16x32_bf16 v[18:21], v[150:153], v[212:215], v[18:21]
	v_mfma_f32_16x16x32_bf16 v[10:13], v[158:161], v[212:215], v[10:13]
	v_mfma_f32_16x16x32_bf16 v[54:57], v[162:165], v[184:187], v[54:57]
	v_mfma_f32_16x16x32_bf16 v[46:49], v[170:173], v[184:187], v[46:49]
	v_mfma_f32_16x16x32_bf16 v[38:41], v[162:165], v[192:195], v[38:41]
	v_mfma_f32_16x16x32_bf16 v[30:33], v[170:173], v[192:195], v[30:33]
	v_mfma_f32_16x16x32_bf16 v[22:25], v[162:165], v[200:203], v[22:25]
	v_mfma_f32_16x16x32_bf16 v[14:17], v[170:173], v[200:203], v[14:17]
	v_mfma_f32_16x16x32_bf16 v[6:9], v[162:165], v[208:211], v[6:9]
	v_mfma_f32_16x16x32_bf16 v[2:5], v[170:173], v[208:211], v[2:5]
	v_mfma_f32_16x16x32_bf16 v[54:57], v[166:169], v[188:191], v[54:57]
	v_mfma_f32_16x16x32_bf16 v[46:49], v[180:183], v[188:191], v[46:49]
	v_mfma_f32_16x16x32_bf16 v[38:41], v[166:169], v[196:199], v[38:41]
	v_mfma_f32_16x16x32_bf16 v[30:33], v[180:183], v[196:199], v[30:33]
	v_mfma_f32_16x16x32_bf16 v[22:25], v[166:169], v[204:207], v[22:25]
	v_mfma_f32_16x16x32_bf16 v[14:17], v[180:183], v[204:207], v[14:17]
	v_mfma_f32_16x16x32_bf16 v[6:9], v[166:169], v[212:215], v[6:9]
	v_mfma_f32_16x16x32_bf16 v[2:5], v[180:183], v[212:215], v[2:5]
	s_barrier
	s_setprio 0
	s_add_i32 s39, 0, 0x18000
	s_add_i32 s44, 0, 0x1c000
	s_add_u32 s14, s14, 0x80000
	s_addc_u32 s15, s15, 0
	s_mov_b32 m0, s24
	v_lshl_add_u64 v[220:221], s[14:15], 0, v[130:131]
	global_load_lds_dwordx4 v[220:221], off
	v_lshl_add_u64 v[220:221], s[14:15], 0, v[132:133]
	s_mov_b32 m0, s25
	s_nop 0
	global_load_lds_dwordx4 v[220:221], off
	v_add_u32_e32 v158, s39, v143
	v_add_u32_e32 v180, s44, v143
	ds_read_b128 v[146:149], v158
	ds_read_b128 v[150:153], v158 offset:1024
	ds_read_b128 v[154:157], v158 offset:2048
	ds_read_b128 v[158:161], v158 offset:3072
	ds_read_b128 v[162:165], v180
	ds_read_b128 v[166:169], v180 offset:1024
	ds_read_b128 v[170:173], v180 offset:2048
	ds_read_b128 v[180:183], v180 offset:3072
	ds_read_b128 v[184:187], v145 offset:32768
	ds_read_b128 v[188:191], v145 offset:33792
	ds_read_b128 v[192:195], v145 offset:34816
	ds_read_b128 v[196:199], v145 offset:35840
	ds_read_b128 v[200:203], v145 offset:36864
	ds_read_b128 v[204:207], v145 offset:37888
	ds_read_b128 v[208:211], v145 offset:38912
	ds_read_b128 v[212:215], v145 offset:39936
	s_waitcnt vmcnt(8)
	s_waitcnt lgkmcnt(0)
	s_setprio 1
	s_barrier
	v_mfma_f32_16x16x32_bf16 v[126:129], v[146:149], v[184:187], v[126:129]
	v_mfma_f32_16x16x32_bf16 v[122:125], v[154:157], v[184:187], v[122:125]
	v_mfma_f32_16x16x32_bf16 v[114:117], v[146:149], v[192:195], v[114:117]
	v_mfma_f32_16x16x32_bf16 v[106:109], v[154:157], v[192:195], v[106:109]
	v_mfma_f32_16x16x32_bf16 v[98:101], v[146:149], v[200:203], v[98:101]
	v_mfma_f32_16x16x32_bf16 v[90:93], v[154:157], v[200:203], v[90:93]
	v_mfma_f32_16x16x32_bf16 v[82:85], v[146:149], v[208:211], v[82:85]
	v_mfma_f32_16x16x32_bf16 v[74:77], v[154:157], v[208:211], v[74:77]
	v_mfma_f32_16x16x32_bf16 v[126:129], v[150:153], v[188:191], v[126:129]
	v_mfma_f32_16x16x32_bf16 v[122:125], v[158:161], v[188:191], v[122:125]
	v_mfma_f32_16x16x32_bf16 v[114:117], v[150:153], v[196:199], v[114:117]
	v_mfma_f32_16x16x32_bf16 v[106:109], v[158:161], v[196:199], v[106:109]
	v_mfma_f32_16x16x32_bf16 v[98:101], v[150:153], v[204:207], v[98:101]
	v_mfma_f32_16x16x32_bf16 v[90:93], v[158:161], v[204:207], v[90:93]
	v_mfma_f32_16x16x32_bf16 v[82:85], v[150:153], v[212:215], v[82:85]
	v_mfma_f32_16x16x32_bf16 v[74:77], v[158:161], v[212:215], v[74:77]
	v_mfma_f32_16x16x32_bf16 v[118:121], v[162:165], v[184:187], v[118:121]
	v_mfma_f32_16x16x32_bf16 v[110:113], v[170:173], v[184:187], v[110:113]
	v_mfma_f32_16x16x32_bf16 v[102:105], v[162:165], v[192:195], v[102:105]
	v_mfma_f32_16x16x32_bf16 v[94:97], v[170:173], v[192:195], v[94:97]
	v_mfma_f32_16x16x32_bf16 v[86:89], v[162:165], v[200:203], v[86:89]
	v_mfma_f32_16x16x32_bf16 v[78:81], v[170:173], v[200:203], v[78:81]
	v_mfma_f32_16x16x32_bf16 v[70:73], v[162:165], v[208:211], v[70:73]
	v_mfma_f32_16x16x32_bf16 v[66:69], v[170:173], v[208:211], v[66:69]
	v_mfma_f32_16x16x32_bf16 v[118:121], v[166:169], v[188:191], v[118:121]
	v_mfma_f32_16x16x32_bf16 v[110:113], v[180:183], v[188:191], v[110:113]
	v_mfma_f32_16x16x32_bf16 v[102:105], v[166:169], v[196:199], v[102:105]
	v_mfma_f32_16x16x32_bf16 v[94:97], v[180:183], v[196:199], v[94:97]
	v_mfma_f32_16x16x32_bf16 v[86:89], v[166:169], v[204:207], v[86:89]
	v_mfma_f32_16x16x32_bf16 v[78:81], v[180:183], v[204:207], v[78:81]
	v_mfma_f32_16x16x32_bf16 v[70:73], v[166:169], v[212:215], v[70:73]
	v_mfma_f32_16x16x32_bf16 v[66:69], v[180:183], v[212:215], v[66:69]
	s_barrier
; #define PG8_STAGE(bufoff, gbase, voff) do { _Pragma("unroll") for (int _i = 0; _i < 2; ++_i) \
;         __builtin_amdgcn_global_load_lds((const unsigned*)((const char*)(gbase) + (voff)[_i]), (LAS unsigned*)(lds + (bufoff) + ldsw + _i * 8192), 16, 0, 0); } while (0)
; #define PG8_LDA(dst, b, h) do { _Pragma("unroll") for (int m = 0; m < 4; ++m) _Pragma("unroll") for (int k = 0; k < 2; ++k) dst[m][k] = *(const LAS bf16x8*)(lds + PG8_SA(b, h) + aoff + m * 2048 + k * 1024); } while (0)
; #define PG8_MMA(ai, bj, At, Bt) do { __builtin_amdgcn_s_setprio(1); _Pragma("unroll") for (int m = 0; m < 4; ++m) _Pragma("unroll") for (int n = 0; n < 2; ++n) _Pragma("unroll") for (int k = 0; k < 2; ++k) \
;         acc[ai][bj][m][n] = __builtin_amdgcn_mfma_f32_16x16x32_bf16(Bt[n][k], At[m][k], acc[ai][bj][m][n], 0, 0, 0); __builtin_amdgcn_s_setprio(0); } while (0)
; #define PG8_WAIT_V(n) asm volatile("s_waitcnt vmcnt(" #n ")" ::: "memory")
; #define PG8_WAIT_L(n) asm volatile("s_waitcnt lgkmcnt(" #n ")" ::: "memory")
; #define PG8_BAR __builtin_amdgcn_s_barrier()
; #define PG8_SCHED __builtin_amdgcn_sched_barrier(0)
; template <class Epi, class Sched, int LDA, int LDB, bool ALIGN_EPI = true>
; __device__ __forceinline__ void gemm_phase(LAS unsigned char* lds, const Gemm g, const Sched& S, const Epi& E, int wave) {
;     ...
;             PG8_LDA(At, 1, 1); PG8_STAGE(PG8_SB(1, 0), b3, voffB); PG8_STAGE(PG8_SB(1, 1), b3 + hstepB, voffB); PG8_STAGE(PG8_SA(1, 0), a3, voffA);
;             PG8_WAIT_V(8); PG8_WAIT_L(0); PG8_BAR; PG8_MMA(1, 0, At, B0); PG8_MMA(1, 1, At, B1); PG8_BAR; PG8_SCHED;
;         }
	s_setprio 0
	s_add_i32 s14, s39, s47
	v_lshl_add_u64 v[140:141], v[140:141], 0, s[48:49]
	s_mov_b32 m0, s14
	s_nop 0
	global_load_lds_dwordx4 v[140:141], off
	s_add_i32 m0, s14, 0x2000
	s_add_u32 s12, s12, 0x84080
	v_lshl_add_u64 v[140:141], v[174:175], 0, s[48:49]
	s_addc_u32 s13, s13, 0
	s_add_i32 s14, s44, s47
	global_load_lds_dwordx4 v[140:141], off
	v_lshl_add_u64 v[140:141], s[12:13], 0, v[0:1]
	s_mov_b32 m0, s14
	s_nop 0
	global_load_lds_dwordx4 v[140:141], off
	v_lshl_add_u64 v[140:141], s[12:13], 0, v[134:135]
	s_add_i32 m0, s14, 0x2000
	s_nop 0
	global_load_lds_dwordx4 v[140:141], off
	v_lshl_add_u64 v[140:141], v[216:217], 0, s[48:49]
	s_mov_b32 m0, s26
	s_nop 0
	global_load_lds_dwordx4 v[140:141], off
	v_lshl_add_u64 v[140:141], v[218:219], 0, s[48:49]
	s_mov_b32 m0, s27
	s_nop 0
	global_load_lds_dwordx4 v[140:141], off
	ds_read_b128 v[184:187], v145 offset:49152
	ds_read_b128 v[188:191], v145 offset:50176
	ds_read_b128 v[192:195], v145 offset:51200
	ds_read_b128 v[196:199], v145 offset:52224
	ds_read_b128 v[200:203], v145 offset:53248
	ds_read_b128 v[204:207], v145 offset:54272
	ds_read_b128 v[208:211], v145 offset:55296
	ds_read_b128 v[212:215], v145 offset:56320
	s_waitcnt vmcnt(8)
	s_waitcnt lgkmcnt(0)
	s_setprio 1
	s_barrier
	v_mfma_f32_16x16x32_bf16 v[62:65], v[146:149], v[184:187], v[62:65]
	v_mfma_f32_16x16x32_bf16 v[58:61], v[154:157], v[184:187], v[58:61]
	v_mfma_f32_16x16x32_bf16 v[50:53], v[146:149], v[192:195], v[50:53]
	v_mfma_f32_16x16x32_bf16 v[42:45], v[154:157], v[192:195], v[42:45]
	v_mfma_f32_16x16x32_bf16 v[34:37], v[146:149], v[200:203], v[34:37]
	v_mfma_f32_16x16x32_bf16 v[26:29], v[154:157], v[200:203], v[26:29]
	v_mfma_f32_16x16x32_bf16 v[18:21], v[146:149], v[208:211], v[18:21]
	v_mfma_f32_16x16x32_bf16 v[10:13], v[154:157], v[208:211], v[10:13]
	v_mfma_f32_16x16x32_bf16 v[62:65], v[150:153], v[188:191], v[62:65]
	v_mfma_f32_16x16x32_bf16 v[58:61], v[158:161], v[188:191], v[58:61]
	v_mfma_f32_16x16x32_bf16 v[50:53], v[150:153], v[196:199], v[50:53]
	v_mfma_f32_16x16x32_bf16 v[42:45], v[158:161], v[196:199], v[42:45]
	v_mfma_f32_16x16x32_bf16 v[34:37], v[150:153], v[204:207], v[34:37]
	v_mfma_f32_16x16x32_bf16 v[26:29], v[158:161], v[204:207], v[26:29]
	v_mfma_f32_16x16x32_bf16 v[18:21], v[150:153], v[212:215], v[18:21]
	v_mfma_f32_16x16x32_bf16 v[10:13], v[158:161], v[212:215], v[10:13]
	v_mfma_f32_16x16x32_bf16 v[54:57], v[162:165], v[184:187], v[54:57]
	v_mfma_f32_16x16x32_bf16 v[46:49], v[170:173], v[184:187], v[46:49]
	v_mfma_f32_16x16x32_bf16 v[38:41], v[162:165], v[192:195], v[38:41]
	v_mfma_f32_16x16x32_bf16 v[30:33], v[170:173], v[192:195], v[30:33]
	v_mfma_f32_16x16x32_bf16 v[22:25], v[162:165], v[200:203], v[22:25]
	v_mfma_f32_16x16x32_bf16 v[14:17], v[170:173], v[200:203], v[14:17]
	v_mfma_f32_16x16x32_bf16 v[6:9], v[162:165], v[208:211], v[6:9]
	v_mfma_f32_16x16x32_bf16 v[2:5], v[170:173], v[208:211], v[2:5]
	v_mfma_f32_16x16x32_bf16 v[54:57], v[166:169], v[188:191], v[54:57]
	v_mfma_f32_16x16x32_bf16 v[46:49], v[180:183], v[188:191], v[46:49]
	v_mfma_f32_16x16x32_bf16 v[38:41], v[166:169], v[196:199], v[38:41]
	v_mfma_f32_16x16x32_bf16 v[30:33], v[180:183], v[196:199], v[30:33]
	v_mfma_f32_16x16x32_bf16 v[22:25], v[166:169], v[204:207], v[22:25]
	v_mfma_f32_16x16x32_bf16 v[14:17], v[180:183], v[204:207], v[14:17]
	v_mfma_f32_16x16x32_bf16 v[6:9], v[166:169], v[212:215], v[6:9]
	v_mfma_f32_16x16x32_bf16 v[2:5], v[180:183], v[212:215], v[2:5]
	s_barrier
	s_setprio 0
	s_add_i32 s38, s38, 2
	s_add_u32 s10, s10, 0x100
	s_addc_u32 s11, s11, 0
	s_add_u32 s36, s36, 0x100
	s_addc_u32 s37, s37, 0
	s_cmp_gt_u32 s38, 29
	s_cbranch_scc0 .LBB0_2415
	v_readlane_b32 s10, v252, 14
	v_readlane_b32 s11, v252, 15
	s_and_b64 vcc, exec, s[10:11]
	s_cbranch_vccz .LBB0_2418
	s_barrier

; #define PG8_STAGE(bufoff, gbase, voff) do { _Pragma("unroll") for (int _i = 0; _i < 2; ++_i) \
;         __builtin_amdgcn_global_load_lds((const unsigned*)((const char*)(gbase) + (voff)[_i]), (LAS unsigned*)(lds + (bufoff) + ldsw + _i * 8192), 16, 0, 0); } while (0)
; #define PG8_LDA(dst, b, h) do { _Pragma("unroll") for (int m = 0; m < 4; ++m) _Pragma("unroll") for (int k = 0; k < 2; ++k) dst[m][k] = *(const LAS bf16x8*)(lds + PG8_SA(b, h) + aoff + m * 2048 + k * 1024); } while (0)
; #define PG8_LDB(dst, b, h) do { _Pragma("unroll") for (int n = 0; n < 2; ++n) _Pragma("unroll") for (int k = 0; k < 2; ++k) dst[n][k] = *(const LAS bf16x8*)(lds + PG8_SB(b, h) + boff + n * 2048 + k * 1024); } while (0)
; #define PG8_MMA(ai, bj, At, Bt) do { __builtin_amdgcn_s_setprio(1); _Pragma("unroll") for (int m = 0; m < 4; ++m) _Pragma("unroll") for (int n = 0; n < 2; ++n) _Pragma("unroll") for (int k = 0; k < 2; ++k) \
;         acc[ai][bj][m][n] = __builtin_amdgcn_mfma_f32_16x16x32_bf16(Bt[n][k], At[m][k], acc[ai][bj][m][n], 0, 0, 0); __builtin_amdgcn_s_setprio(0); } while (0)
; #define PG8_WAIT_V(n) asm volatile("s_waitcnt vmcnt(" #n ")" ::: "memory")
; #define PG8_WAIT_L(n) asm volatile("s_waitcnt lgkmcnt(" #n ")" ::: "memory")
; #define PG8_BAR __builtin_amdgcn_s_barrier()
; template <class Epi, class Sched, int LDA, int LDB, bool ALIGN_EPI = true>
; __device__ __forceinline__ void gemm_phase(LAS unsigned char* lds, const Gemm g, const Sched& S, const Epi& E, int wave) {
;     ...
;         for (int t = 0; t < nt; t += 2) {
;             const bool last = (t == nt - 2);
;             const char* a1 = cA + (size_t)(t + 1) * kstep;
;             const char* a2 = last ? nA : cA + (size_t)(t + 2) * kstep; const char* b2 = last ? nB : cB + (size_t)(t + 2) * kstep;
;             const char* a3 = a2 + kstep; const char* b3 = b2 + kstep;
;             PG8_LDB(B0, 0, 0); PG8_LDB(B1, 0, 1); PG8_SCHED; PG8_LDA(At, 0, 0); PG8_STAGE(PG8_SA(1, 1), a1 + hstepA, voffA);
;             PG8_WAIT_V(8); PG8_WAIT_L(0); PG8_BAR; PG8_MMA(0, 0, At, B0); PG8_MMA(0, 1, At, B1); PG8_BAR; PG8_SCHED;
;             PG8_LDA(At, 0, 1); PG8_STAGE(PG8_SB(0, 0), b2, voffB); PG8_STAGE(PG8_SB(0, 1), b2 + hstepB, voffB); PG8_STAGE(PG8_SA(0, 0), a2, voffA);
;             PG8_WAIT_V(8); PG8_WAIT_L(0); PG8_BAR; PG8_MMA(1, 0, At, B0); PG8_MMA(1, 1, At, B1); PG8_BAR; PG8_SCHED;
.LBB0_2513:
	s_add_u32 s14, s12, 0xfff80080
	s_addc_u32 s15, s13, -1
	s_add_i32 s44, 0, 0x10000
	s_cmp_eq_u32 s39, 28
	s_cselect_b32 s17, s1, s15
	s_cselect_b32 s16, s3, s14
	s_cselect_b32 s15, s9, s38
	s_cselect_b32 s14, s8, s37
	s_add_i32 s46, 0, 0x14000
	v_lshl_add_u64 v[140:141], s[12:13], 0, v[136:137]
	s_add_i32 m0, s24, 0xc000
	s_nop 0
	global_load_lds_dwordx4 v[140:141], off
	v_lshl_add_u64 v[140:141], s[12:13], 0, v[138:139]
	s_add_i32 m0, s24, 0xe000
	s_nop 0
	global_load_lds_dwordx4 v[140:141], off
	v_add_u32_e32 v140, s44, v143
	ds_read_b128 v[146:149], v140
	ds_read_b128 v[150:153], v140 offset:1024
	ds_read_b128 v[154:157], v140 offset:2048
	ds_read_b128 v[158:161], v140 offset:3072
	v_add_u32_e32 v140, s46, v143
	ds_read_b128 v[162:165], v140
	ds_read_b128 v[166:169], v140 offset:1024
	ds_read_b128 v[170:173], v140 offset:2048
	ds_read_b128 v[180:183], v140 offset:3072
	ds_read_b128 v[184:187], v145
	ds_read_b128 v[188:191], v145 offset:1024
	ds_read_b128 v[192:195], v145 offset:2048
	ds_read_b128 v[196:199], v145 offset:3072
	ds_read_b128 v[200:203], v145 offset:4096
	ds_read_b128 v[204:207], v145 offset:5120
	ds_read_b128 v[208:211], v145 offset:6144
	ds_read_b128 v[212:215], v145 offset:7168
	s_waitcnt vmcnt(8)
	s_waitcnt lgkmcnt(0)
	s_setprio 1
	s_barrier
	v_mfma_f32_16x16x32_bf16 v[126:129], v[146:149], v[184:187], v[126:129]
	v_mfma_f32_16x16x32_bf16 v[122:125], v[154:157], v[184:187], v[122:125]
	v_mfma_f32_16x16x32_bf16 v[114:117], v[146:149], v[192:195], v[114:117]
	v_mfma_f32_16x16x32_bf16 v[106:109], v[154:157], v[192:195], v[106:109]
	v_mfma_f32_16x16x32_bf16 v[98:101], v[146:149], v[200:203], v[98:101]
	v_mfma_f32_16x16x32_bf16 v[90:93], v[154:157], v[200:203], v[90:93]
	v_mfma_f32_16x16x32_bf16 v[82:85], v[146:149], v[208:211], v[82:85]
	v_mfma_f32_16x16x32_bf16 v[74:77], v[154:157], v[208:211], v[74:77]
	v_mfma_f32_16x16x32_bf16 v[126:129], v[150:153], v[188:191], v[126:129]
	v_mfma_f32_16x16x32_bf16 v[122:125], v[158:161], v[188:191], v[122:125]
	v_mfma_f32_16x16x32_bf16 v[114:117], v[150:153], v[196:199], v[114:117]
	v_mfma_f32_16x16x32_bf16 v[106:109], v[158:161], v[196:199], v[106:109]
	v_mfma_f32_16x16x32_bf16 v[98:101], v[150:153], v[204:207], v[98:101]
	v_mfma_f32_16x16x32_bf16 v[90:93], v[158:161], v[204:207], v[90:93]
	v_mfma_f32_16x16x32_bf16 v[82:85], v[150:153], v[212:215], v[82:85]
	v_mfma_f32_16x16x32_bf16 v[74:77], v[158:161], v[212:215], v[74:77]
	v_mfma_f32_16x16x32_bf16 v[118:121], v[162:165], v[184:187], v[118:121]
	v_mfma_f32_16x16x32_bf16 v[110:113], v[170:173], v[184:187], v[110:113]
	v_mfma_f32_16x16x32_bf16 v[102:105], v[162:165], v[192:195], v[102:105]
	v_mfma_f32_16x16x32_bf16 v[94:97], v[170:173], v[192:195], v[94:97]
	v_mfma_f32_16x16x32_bf16 v[86:89], v[162:165], v[200:203], v[86:89]
	v_mfma_f32_16x16x32_bf16 v[78:81], v[170:173], v[200:203], v[78:81]
	v_mfma_f32_16x16x32_bf16 v[70:73], v[162:165], v[208:211], v[70:73]
	v_mfma_f32_16x16x32_bf16 v[66:69], v[170:173], v[208:211], v[66:69]
	v_mfma_f32_16x16x32_bf16 v[118:121], v[166:169], v[188:191], v[118:121]
	v_mfma_f32_16x16x32_bf16 v[110:113], v[180:183], v[188:191], v[110:113]
	v_mfma_f32_16x16x32_bf16 v[102:105], v[166:169], v[196:199], v[102:105]
	v_mfma_f32_16x16x32_bf16 v[94:97], v[180:183], v[196:199], v[94:97]
	v_mfma_f32_16x16x32_bf16 v[86:89], v[166:169], v[204:207], v[86:89]
	v_mfma_f32_16x16x32_bf16 v[78:81], v[180:183], v[204:207], v[78:81]
	v_mfma_f32_16x16x32_bf16 v[70:73], v[166:169], v[212:215], v[70:73]
	v_mfma_f32_16x16x32_bf16 v[66:69], v[180:183], v[212:215], v[66:69]
	s_barrier
	s_setprio 0
	s_add_i32 s44, s44, s47
	v_lshl_add_u64 v[140:141], s[14:15], 0, v[0:1]
	s_mov_b32 m0, s44
	s_nop 0
	global_load_lds_dwordx4 v[140:141], off
	s_add_i32 m0, s44, 0x2000
	s_add_u32 s44, s14, 0x84000
	v_lshl_add_u64 v[174:175], s[14:15], 0, v[134:135]
	s_addc_u32 s45, s15, 0
	s_add_i32 s46, s46, s47
	global_load_lds_dwordx4 v[174:175], off
	v_lshl_add_u64 v[216:217], s[44:45], 0, v[0:1]
	s_mov_b32 m0, s46
	v_lshl_add_u64 v[218:219], s[16:17], 0, v[132:133]
	global_load_lds_dwordx4 v[216:217], off
	v_lshl_add_u64 v[216:217], s[44:45], 0, v[134:135]
	s_add_i32 m0, s46, 0x2000
	s_nop 0
	global_load_lds_dwordx4 v[216:217], off
	v_lshl_add_u64 v[216:217], s[16:17], 0, v[130:131]
	s_mov_b32 m0, s24
	s_nop 0
	global_load_lds_dwordx4 v[216:217], off
	s_mov_b32 m0, s25
	s_nop 0
	global_load_lds_dwordx4 v[218:219], off
	ds_read_b128 v[184:187], v145 offset:16384
	ds_read_b128 v[188:191], v145 offset:17408
	ds_read_b128 v[192:195], v145 offset:18432
	ds_read_b128 v[196:199], v145 offset:19456
	ds_read_b128 v[200:203], v145 offset:20480
	ds_read_b128 v[204:207], v145 offset:21504
	ds_read_b128 v[208:211], v145 offset:22528
	ds_read_b128 v[212:215], v145 offset:23552
	s_waitcnt vmcnt(8)
	s_waitcnt lgkmcnt(0)
	s_setprio 1
	s_barrier
; #define PG8_STAGE(bufoff, gbase, voff) do { _Pragma("unroll") for (int _i = 0; _i < 2; ++_i) \
;         __builtin_amdgcn_global_load_lds((const unsigned*)((const char*)(gbase) + (voff)[_i]), (LAS unsigned*)(lds + (bufoff) + ldsw + _i * 8192), 16, 0, 0); } while (0)
; #define PG8_LDA(dst, b, h) do { _Pragma("unroll") for (int m = 0; m < 4; ++m) _Pragma("unroll") for (int k = 0; k < 2; ++k) dst[m][k] = *(const LAS bf16x8*)(lds + PG8_SA(b, h) + aoff + m * 2048 + k * 1024); } while (0)
; #define PG8_LDB(dst, b, h) do { _Pragma("unroll") for (int n = 0; n < 2; ++n) _Pragma("unroll") for (int k = 0; k < 2; ++k) dst[n][k] = *(const LAS bf16x8*)(lds + PG8_SB(b, h) + boff + n * 2048 + k * 1024); } while (0)
; #define PG8_MMA(ai, bj, At, Bt) do { __builtin_amdgcn_s_setprio(1); _Pragma("unroll") for (int m = 0; m < 4; ++m) _Pragma("unroll") for (int n = 0; n < 2; ++n) _Pragma("unroll") for (int k = 0; k < 2; ++k) \
;         acc[ai][bj][m][n] = __builtin_amdgcn_mfma_f32_16x16x32_bf16(Bt[n][k], At[m][k], acc[ai][bj][m][n], 0, 0, 0); __builtin_amdgcn_s_setprio(0); } while (0)
; #define PG8_WAIT_V(n) asm volatile("s_waitcnt vmcnt(" #n ")" ::: "memory")
; #define PG8_WAIT_L(n) asm volatile("s_waitcnt lgkmcnt(" #n ")" ::: "memory")
; #define PG8_BAR __builtin_amdgcn_s_barrier()
; #define PG8_SCHED __builtin_amdgcn_sched_barrier(0)
; template <class Epi, class Sched, int LDA, int LDB, bool ALIGN_EPI = true>
; __device__ __forceinline__ void gemm_phase(LAS unsigned char* lds, const Gemm g, const Sched& S, const Epi& E, int wave) {
;     ...
;             PG8_WAIT_V(8); PG8_WAIT_L(0); PG8_BAR; PG8_MMA(1, 0, At, B0); PG8_MMA(1, 1, At, B1); PG8_BAR; PG8_SCHED;
;             PG8_LDB(B0, 1, 0); PG8_LDB(B1, 1, 1); PG8_SCHED; PG8_LDA(At, 1, 0); PG8_STAGE(PG8_SA(0, 1), a2 + hstepA, voffA);
;             PG8_WAIT_V(8); PG8_WAIT_L(0); PG8_BAR; PG8_MMA(0, 0, At, B0); PG8_MMA(0, 1, At, B1); PG8_BAR; PG8_SCHED;
	v_mfma_f32_16x16x32_bf16 v[62:65], v[146:149], v[184:187], v[62:65]
	v_mfma_f32_16x16x32_bf16 v[58:61], v[154:157], v[184:187], v[58:61]
	v_mfma_f32_16x16x32_bf16 v[50:53], v[146:149], v[192:195], v[50:53]
	v_mfma_f32_16x16x32_bf16 v[42:45], v[154:157], v[192:195], v[42:45]
	v_mfma_f32_16x16x32_bf16 v[34:37], v[146:149], v[200:203], v[34:37]
	v_mfma_f32_16x16x32_bf16 v[26:29], v[154:157], v[200:203], v[26:29]
	v_mfma_f32_16x16x32_bf16 v[18:21], v[146:149], v[208:211], v[18:21]
	v_mfma_f32_16x16x32_bf16 v[10:13], v[154:157], v[208:211], v[10:13]
	v_mfma_f32_16x16x32_bf16 v[62:65], v[150:153], v[188:191], v[62:65]
	v_mfma_f32_16x16x32_bf16 v[58:61], v[158:161], v[188:191], v[58:61]
	v_mfma_f32_16x16x32_bf16 v[50:53], v[150:153], v[196:199], v[50:53]
	v_mfma_f32_16x16x32_bf16 v[42:45], v[158:161], v[196:199], v[42:45]
	v_mfma_f32_16x16x32_bf16 v[34:37], v[150:153], v[204:207], v[34:37]
	v_mfma_f32_16x16x32_bf16 v[26:29], v[158:161], v[204:207], v[26:29]
	v_mfma_f32_16x16x32_bf16 v[18:21], v[150:153], v[212:215], v[18:21]
	v_mfma_f32_16x16x32_bf16 v[10:13], v[158:161], v[212:215], v[10:13]
	v_mfma_f32_16x16x32_bf16 v[54:57], v[162:165], v[184:187], v[54:57]
	v_mfma_f32_16x16x32_bf16 v[46:49], v[170:173], v[184:187], v[46:49]
	v_mfma_f32_16x16x32_bf16 v[38:41], v[162:165], v[192:195], v[38:41]
	v_mfma_f32_16x16x32_bf16 v[30:33], v[170:173], v[192:195], v[30:33]
	v_mfma_f32_16x16x32_bf16 v[22:25], v[162:165], v[200:203], v[22:25]
	v_mfma_f32_16x16x32_bf16 v[14:17], v[170:173], v[200:203], v[14:17]
	v_mfma_f32_16x16x32_bf16 v[6:9], v[162:165], v[208:211], v[6:9]
	v_mfma_f32_16x16x32_bf16 v[2:5], v[170:173], v[208:211], v[2:5]
	v_mfma_f32_16x16x32_bf16 v[54:57], v[166:169], v[188:191], v[54:57]
	v_mfma_f32_16x16x32_bf16 v[46:49], v[180:183], v[188:191], v[46:49]
	v_mfma_f32_16x16x32_bf16 v[38:41], v[166:169], v[196:199], v[38:41]
	v_mfma_f32_16x16x32_bf16 v[30:33], v[180:183], v[196:199], v[30:33]
	v_mfma_f32_16x16x32_bf16 v[22:25], v[166:169], v[204:207], v[22:25]
	v_mfma_f32_16x16x32_bf16 v[14:17], v[180:183], v[204:207], v[14:17]
	v_mfma_f32_16x16x32_bf16 v[6:9], v[166:169], v[212:215], v[6:9]
	v_mfma_f32_16x16x32_bf16 v[2:5], v[180:183], v[212:215], v[2:5]
	s_barrier
	s_setprio 0
	s_add_i32 s44, 0, 0x18000
	s_add_i32 s45, 0, 0x1c000
	s_add_u32 s16, s16, 0x80000
	s_addc_u32 s17, s17, 0
	s_mov_b32 m0, s26
	v_lshl_add_u64 v[220:221], s[16:17], 0, v[130:131]
	global_load_lds_dwordx4 v[220:221], off
	v_lshl_add_u64 v[220:221], s[16:17], 0, v[132:133]
	s_mov_b32 m0, s27
	s_nop 0
	global_load_lds_dwordx4 v[220:221], off
	v_add_u32_e32 v158, s44, v143
	v_add_u32_e32 v180, s45, v143
	ds_read_b128 v[146:149], v158
	ds_read_b128 v[150:153], v158 offset:1024
	ds_read_b128 v[154:157], v158 offset:2048
	ds_read_b128 v[158:161], v158 offset:3072
	ds_read_b128 v[162:165], v180
	ds_read_b128 v[166:169], v180 offset:1024
	ds_read_b128 v[170:173], v180 offset:2048
	ds_read_b128 v[180:183], v180 offset:3072
	ds_read_b128 v[184:187], v145 offset:32768
	ds_read_b128 v[188:191], v145 offset:33792
	ds_read_b128 v[192:195], v145 offset:34816
	ds_read_b128 v[196:199], v145 offset:35840
	ds_read_b128 v[200:203], v145 offset:36864
	ds_read_b128 v[204:207], v145 offset:37888
	ds_read_b128 v[208:211], v145 offset:38912
	ds_read_b128 v[212:215], v145 offset:39936
	s_waitcnt vmcnt(8)
	s_waitcnt lgkmcnt(0)
	s_setprio 1
	s_barrier
	v_mfma_f32_16x16x32_bf16 v[126:129], v[146:149], v[184:187], v[126:129]
	v_mfma_f32_16x16x32_bf16 v[122:125], v[154:157], v[184:187], v[122:125]
	v_mfma_f32_16x16x32_bf16 v[114:117], v[146:149], v[192:195], v[114:117]
	v_mfma_f32_16x16x32_bf16 v[106:109], v[154:157], v[192:195], v[106:109]
	v_mfma_f32_16x16x32_bf16 v[98:101], v[146:149], v[200:203], v[98:101]
	v_mfma_f32_16x16x32_bf16 v[90:93], v[154:157], v[200:203], v[90:93]
	v_mfma_f32_16x16x32_bf16 v[82:85], v[146:149], v[208:211], v[82:85]
	v_mfma_f32_16x16x32_bf16 v[74:77], v[154:157], v[208:211], v[74:77]
	v_mfma_f32_16x16x32_bf16 v[126:129], v[150:153], v[188:191], v[126:129]
	v_mfma_f32_16x16x32_bf16 v[122:125], v[158:161], v[188:191], v[122:125]
	v_mfma_f32_16x16x32_bf16 v[114:117], v[150:153], v[196:199], v[114:117]
	v_mfma_f32_16x16x32_bf16 v[106:109], v[158:161], v[196:199], v[106:109]
	v_mfma_f32_16x16x32_bf16 v[98:101], v[150:153], v[204:207], v[98:101]
	v_mfma_f32_16x16x32_bf16 v[90:93], v[158:161], v[204:207], v[90:93]
	v_mfma_f32_16x16x32_bf16 v[82:85], v[150:153], v[212:215], v[82:85]
	v_mfma_f32_16x16x32_bf16 v[74:77], v[158:161], v[212:215], v[74:77]
	v_mfma_f32_16x16x32_bf16 v[118:121], v[162:165], v[184:187], v[118:121]
	v_mfma_f32_16x16x32_bf16 v[110:113], v[170:173], v[184:187], v[110:113]
	v_mfma_f32_16x16x32_bf16 v[102:105], v[162:165], v[192:195], v[102:105]
	v_mfma_f32_16x16x32_bf16 v[94:97], v[170:173], v[192:195], v[94:97]
	v_mfma_f32_16x16x32_bf16 v[86:89], v[162:165], v[200:203], v[86:89]
	v_mfma_f32_16x16x32_bf16 v[78:81], v[170:173], v[200:203], v[78:81]
	v_mfma_f32_16x16x32_bf16 v[70:73], v[162:165], v[208:211], v[70:73]
	v_mfma_f32_16x16x32_bf16 v[66:69], v[170:173], v[208:211], v[66:69]
	v_mfma_f32_16x16x32_bf16 v[118:121], v[166:169], v[188:191], v[118:121]
	v_mfma_f32_16x16x32_bf16 v[110:113], v[180:183], v[188:191], v[110:113]
	v_mfma_f32_16x16x32_bf16 v[102:105], v[166:169], v[196:199], v[102:105]
	v_mfma_f32_16x16x32_bf16 v[94:97], v[180:183], v[196:199], v[94:97]
	v_mfma_f32_16x16x32_bf16 v[86:89], v[166:169], v[204:207], v[86:89]
	v_mfma_f32_16x16x32_bf16 v[78:81], v[180:183], v[204:207], v[78:81]
	v_mfma_f32_16x16x32_bf16 v[70:73], v[166:169], v[212:215], v[70:73]
	v_mfma_f32_16x16x32_bf16 v[66:69], v[180:183], v[212:215], v[66:69]
	s_barrier
; #define PG8_STAGE(bufoff, gbase, voff) do { _Pragma("unroll") for (int _i = 0; _i < 2; ++_i) \
;         __builtin_amdgcn_global_load_lds((const unsigned*)((const char*)(gbase) + (voff)[_i]), (LAS unsigned*)(lds + (bufoff) + ldsw + _i * 8192), 16, 0, 0); } while (0)
; #define PG8_LDA(dst, b, h) do { _Pragma("unroll") for (int m = 0; m < 4; ++m) _Pragma("unroll") for (int k = 0; k < 2; ++k) dst[m][k] = *(const LAS bf16x8*)(lds + PG8_SA(b, h) + aoff + m * 2048 + k * 1024); } while (0)
; #define PG8_MMA(ai, bj, At, Bt) do { __builtin_amdgcn_s_setprio(1); _Pragma("unroll") for (int m = 0; m < 4; ++m) _Pragma("unroll") for (int n = 0; n < 2; ++n) _Pragma("unroll") for (int k = 0; k < 2; ++k) \
;         acc[ai][bj][m][n] = __builtin_amdgcn_mfma_f32_16x16x32_bf16(Bt[n][k], At[m][k], acc[ai][bj][m][n], 0, 0, 0); __builtin_amdgcn_s_setprio(0); } while (0)
; #define PG8_WAIT_V(n) asm volatile("s_waitcnt vmcnt(" #n ")" ::: "memory")
; #define PG8_WAIT_L(n) asm volatile("s_waitcnt lgkmcnt(" #n ")" ::: "memory")
; #define PG8_BAR __builtin_amdgcn_s_barrier()
; #define PG8_SCHED __builtin_amdgcn_sched_barrier(0)
; template <class Epi, class Sched, int LDA, int LDB, bool ALIGN_EPI = true>
; __device__ __forceinline__ void gemm_phase(LAS unsigned char* lds, const Gemm g, const Sched& S, const Epi& E, int wave) {
;     ...
;             PG8_LDA(At, 1, 1); PG8_STAGE(PG8_SB(1, 0), b3, voffB); PG8_STAGE(PG8_SB(1, 1), b3 + hstepB, voffB); PG8_STAGE(PG8_SA(1, 0), a3, voffA);
;             PG8_WAIT_V(8); PG8_WAIT_L(0); PG8_BAR; PG8_MMA(1, 0, At, B0); PG8_MMA(1, 1, At, B1); PG8_BAR; PG8_SCHED;
;         }
	s_setprio 0
	s_add_i32 s16, s44, s47
	v_lshl_add_u64 v[140:141], v[140:141], 0, s[72:73]
	s_mov_b32 m0, s16
	s_nop 0
	global_load_lds_dwordx4 v[140:141], off
	s_add_i32 m0, s16, 0x2000
	s_add_u32 s14, s14, 0x84080
	v_lshl_add_u64 v[140:141], v[174:175], 0, s[72:73]
	s_addc_u32 s15, s15, 0
	s_add_i32 s16, s45, s47
	global_load_lds_dwordx4 v[140:141], off
	v_lshl_add_u64 v[140:141], s[14:15], 0, v[0:1]
	s_mov_b32 m0, s16
	s_nop 0
	global_load_lds_dwordx4 v[140:141], off
	v_lshl_add_u64 v[140:141], s[14:15], 0, v[134:135]
	s_add_i32 m0, s16, 0x2000
	s_nop 0
	global_load_lds_dwordx4 v[140:141], off
	v_lshl_add_u64 v[140:141], v[216:217], 0, s[72:73]
	s_mov_b32 m0, s28
	s_nop 0
	global_load_lds_dwordx4 v[140:141], off
	v_lshl_add_u64 v[140:141], v[218:219], 0, s[72:73]
	s_mov_b32 m0, s29
	s_nop 0
	global_load_lds_dwordx4 v[140:141], off
	ds_read_b128 v[184:187], v145 offset:49152
	ds_read_b128 v[188:191], v145 offset:50176
	ds_read_b128 v[192:195], v145 offset:51200
	ds_read_b128 v[196:199], v145 offset:52224
	ds_read_b128 v[200:203], v145 offset:53248
	ds_read_b128 v[204:207], v145 offset:54272
	ds_read_b128 v[208:211], v145 offset:55296
	ds_read_b128 v[212:215], v145 offset:56320
	s_waitcnt vmcnt(8)
	s_waitcnt lgkmcnt(0)
	s_setprio 1
	s_barrier
	v_mfma_f32_16x16x32_bf16 v[62:65], v[146:149], v[184:187], v[62:65]
	v_mfma_f32_16x16x32_bf16 v[58:61], v[154:157], v[184:187], v[58:61]
	v_mfma_f32_16x16x32_bf16 v[50:53], v[146:149], v[192:195], v[50:53]
	v_mfma_f32_16x16x32_bf16 v[42:45], v[154:157], v[192:195], v[42:45]
	v_mfma_f32_16x16x32_bf16 v[34:37], v[146:149], v[200:203], v[34:37]
	v_mfma_f32_16x16x32_bf16 v[26:29], v[154:157], v[200:203], v[26:29]
	v_mfma_f32_16x16x32_bf16 v[18:21], v[146:149], v[208:211], v[18:21]
	v_mfma_f32_16x16x32_bf16 v[10:13], v[154:157], v[208:211], v[10:13]
	v_mfma_f32_16x16x32_bf16 v[62:65], v[150:153], v[188:191], v[62:65]
	v_mfma_f32_16x16x32_bf16 v[58:61], v[158:161], v[188:191], v[58:61]
	v_mfma_f32_16x16x32_bf16 v[50:53], v[150:153], v[196:199], v[50:53]
	v_mfma_f32_16x16x32_bf16 v[42:45], v[158:161], v[196:199], v[42:45]
	v_mfma_f32_16x16x32_bf16 v[34:37], v[150:153], v[204:207], v[34:37]
	v_mfma_f32_16x16x32_bf16 v[26:29], v[158:161], v[204:207], v[26:29]
	v_mfma_f32_16x16x32_bf16 v[18:21], v[150:153], v[212:215], v[18:21]
	v_mfma_f32_16x16x32_bf16 v[10:13], v[158:161], v[212:215], v[10:13]
	v_mfma_f32_16x16x32_bf16 v[54:57], v[162:165], v[184:187], v[54:57]
	v_mfma_f32_16x16x32_bf16 v[46:49], v[170:173], v[184:187], v[46:49]
	v_mfma_f32_16x16x32_bf16 v[38:41], v[162:165], v[192:195], v[38:41]
	v_mfma_f32_16x16x32_bf16 v[30:33], v[170:173], v[192:195], v[30:33]
	v_mfma_f32_16x16x32_bf16 v[22:25], v[162:165], v[200:203], v[22:25]
	v_mfma_f32_16x16x32_bf16 v[14:17], v[170:173], v[200:203], v[14:17]
	v_mfma_f32_16x16x32_bf16 v[6:9], v[162:165], v[208:211], v[6:9]
	v_mfma_f32_16x16x32_bf16 v[2:5], v[170:173], v[208:211], v[2:5]
	v_mfma_f32_16x16x32_bf16 v[54:57], v[166:169], v[188:191], v[54:57]
	v_mfma_f32_16x16x32_bf16 v[46:49], v[180:183], v[188:191], v[46:49]
	v_mfma_f32_16x16x32_bf16 v[38:41], v[166:169], v[196:199], v[38:41]
	v_mfma_f32_16x16x32_bf16 v[30:33], v[180:183], v[196:199], v[30:33]
	v_mfma_f32_16x16x32_bf16 v[22:25], v[166:169], v[204:207], v[22:25]
	v_mfma_f32_16x16x32_bf16 v[14:17], v[180:183], v[204:207], v[14:17]
	v_mfma_f32_16x16x32_bf16 v[6:9], v[166:169], v[212:215], v[6:9]
	v_mfma_f32_16x16x32_bf16 v[2:5], v[180:183], v[212:215], v[2:5]
	s_barrier
	s_setprio 0
	s_add_i32 s39, s39, 2
	s_add_u32 s12, s12, 0x100
	s_addc_u32 s13, s13, 0
	s_add_u32 s37, s37, 0x100
	s_addc_u32 s38, s38, 0
	s_cmp_gt_u32 s39, 29
	s_cbranch_scc0 .LBB0_2513
	v_readlane_b32 s12, v252, 14
	v_readlane_b32 s13, v252, 15
	s_and_b64 vcc, exec, s[12:13]
	s_cbranch_vccz .LBB0_2516
	s_barrier

; #define PG8_STAGE(bufoff, gbase, voff) do { _Pragma("unroll") for (int _i = 0; _i < 2; ++_i) \
;         __builtin_amdgcn_global_load_lds((const unsigned*)((const char*)(gbase) + (voff)[_i]), (LAS unsigned*)(lds + (bufoff) + ldsw + _i * 8192), 16, 0, 0); } while (0)
; #define PG8_LDA(dst, b, h) do { _Pragma("unroll") for (int m = 0; m < 4; ++m) _Pragma("unroll") for (int k = 0; k < 2; ++k) dst[m][k] = *(const LAS bf16x8*)(lds + PG8_SA(b, h) + aoff + m * 2048 + k * 1024); } while (0)
; #define PG8_LDB(dst, b, h) do { _Pragma("unroll") for (int n = 0; n < 2; ++n) _Pragma("unroll") for (int k = 0; k < 2; ++k) dst[n][k] = *(const LAS bf16x8*)(lds + PG8_SB(b, h) + boff + n * 2048 + k * 1024); } while (0)
; #define PG8_MMA(ai, bj, At, Bt) do { __builtin_amdgcn_s_setprio(1); _Pragma("unroll") for (int m = 0; m < 4; ++m) _Pragma("unroll") for (int n = 0; n < 2; ++n) _Pragma("unroll") for (int k = 0; k < 2; ++k) \
;         acc[ai][bj][m][n] = __builtin_amdgcn_mfma_f32_16x16x32_bf16(Bt[n][k], At[m][k], acc[ai][bj][m][n], 0, 0, 0); __builtin_amdgcn_s_setprio(0); } while (0)
; #define PG8_WAIT_V(n) asm volatile("s_waitcnt vmcnt(" #n ")" ::: "memory")
; #define PG8_WAIT_L(n) asm volatile("s_waitcnt lgkmcnt(" #n ")" ::: "memory")
; #define PG8_BAR __builtin_amdgcn_s_barrier()
; template <class Epi, class Sched, int LDA, int LDB, bool ALIGN_EPI = true>
; __device__ __forceinline__ void gemm_phase(LAS unsigned char* lds, const Gemm g, const Sched& S, const Epi& E, int wave) {
;     ...
;         for (int t = 0; t < nt; t += 2) {
;             const bool last = (t == nt - 2);
;             const char* a1 = cA + (size_t)(t + 1) * kstep;
;             const char* a2 = last ? nA : cA + (size_t)(t + 2) * kstep; const char* b2 = last ? nB : cB + (size_t)(t + 2) * kstep;
;             const char* a3 = a2 + kstep; const char* b3 = b2 + kstep;
;             PG8_LDB(B0, 0, 0); PG8_LDB(B1, 0, 1); PG8_SCHED; PG8_LDA(At, 0, 0); PG8_STAGE(PG8_SA(1, 1), a1 + hstepA, voffA);
;             PG8_WAIT_V(8); PG8_WAIT_L(0); PG8_BAR; PG8_MMA(0, 0, At, B0); PG8_MMA(0, 1, At, B1); PG8_BAR; PG8_SCHED;
;             PG8_LDA(At, 0, 1); PG8_STAGE(PG8_SB(0, 0), b2, voffB); PG8_STAGE(PG8_SB(0, 1), b2 + hstepB, voffB); PG8_STAGE(PG8_SA(0, 0), a2, voffA);
;             PG8_WAIT_V(8); PG8_WAIT_L(0); PG8_BAR; PG8_MMA(1, 0, At, B0); PG8_MMA(1, 1, At, B1); PG8_BAR; PG8_SCHED;
.LBB0_2551:
	s_add_u32 s2, s0, 0x100
	s_addc_u32 s3, s1, 0
	s_add_i32 s50, 0, 0x10000
	s_cmp_eq_u32 s49, 8
	s_cselect_b32 s17, s11, s3
	s_cselect_b32 s16, s10, s2
	s_cselect_b32 s15, s13, s47
	s_cselect_b32 s14, s12, s46
	s_add_i32 s51, 0, 0x14000
	v_lshl_add_u64 v[152:153], s[0:1], 0, v[144:145]
	s_add_i32 m0, s28, 0xc000
	s_nop 0
	global_load_lds_dwordx4 v[152:153], off
	v_lshl_add_u64 v[152:153], s[0:1], 0, v[146:147]
	s_add_i32 m0, s28, 0xe000
	s_nop 0
	global_load_lds_dwordx4 v[152:153], off
	v_add_u32_e32 v0, s50, v154
	ds_read_b128 v[130:133], v0
	ds_read_b128 v[148:151], v0 offset:1024
	ds_read_b128 v[158:161], v0 offset:2048
	ds_read_b128 v[162:165], v0 offset:3072
	v_add_u32_e32 v0, s51, v154
	ds_read_b128 v[166:169], v0
	ds_read_b128 v[170:173], v0 offset:1024
	ds_read_b128 v[180:183], v0 offset:2048
	ds_read_b128 v[184:187], v0 offset:3072
	ds_read_b128 v[188:191], v156
	ds_read_b128 v[192:195], v156 offset:1024
	ds_read_b128 v[196:199], v156 offset:2048
	ds_read_b128 v[200:203], v156 offset:3072
	ds_read_b128 v[204:207], v156 offset:4096
	ds_read_b128 v[208:211], v156 offset:5120
	ds_read_b128 v[212:215], v156 offset:6144
	ds_read_b128 v[216:219], v156 offset:7168
	s_waitcnt vmcnt(8)
	s_waitcnt lgkmcnt(0)
	s_setprio 1
	s_barrier
	v_mfma_f32_16x16x32_bf16 v[126:129], v[130:133], v[188:191], v[126:129]
	v_mfma_f32_16x16x32_bf16 v[122:125], v[158:161], v[188:191], v[122:125]
	v_mfma_f32_16x16x32_bf16 v[118:121], v[130:133], v[196:199], v[118:121]
	v_mfma_f32_16x16x32_bf16 v[114:117], v[158:161], v[196:199], v[114:117]
	v_mfma_f32_16x16x32_bf16 v[110:113], v[130:133], v[204:207], v[110:113]
	v_mfma_f32_16x16x32_bf16 v[106:109], v[158:161], v[204:207], v[106:109]
	v_mfma_f32_16x16x32_bf16 v[102:105], v[130:133], v[212:215], v[102:105]
	v_mfma_f32_16x16x32_bf16 v[98:101], v[158:161], v[212:215], v[98:101]
	v_mfma_f32_16x16x32_bf16 v[126:129], v[148:151], v[192:195], v[126:129]
	v_mfma_f32_16x16x32_bf16 v[122:125], v[162:165], v[192:195], v[122:125]
	v_mfma_f32_16x16x32_bf16 v[118:121], v[148:151], v[200:203], v[118:121]
	v_mfma_f32_16x16x32_bf16 v[114:117], v[162:165], v[200:203], v[114:117]
	v_mfma_f32_16x16x32_bf16 v[110:113], v[148:151], v[208:211], v[110:113]
	v_mfma_f32_16x16x32_bf16 v[106:109], v[162:165], v[208:211], v[106:109]
	v_mfma_f32_16x16x32_bf16 v[102:105], v[148:151], v[216:219], v[102:105]
	v_mfma_f32_16x16x32_bf16 v[98:101], v[162:165], v[216:219], v[98:101]
	v_mfma_f32_16x16x32_bf16 v[62:65], v[166:169], v[188:191], v[62:65]
	v_mfma_f32_16x16x32_bf16 v[58:61], v[180:183], v[188:191], v[58:61]
	v_mfma_f32_16x16x32_bf16 v[54:57], v[166:169], v[196:199], v[54:57]
	v_mfma_f32_16x16x32_bf16 v[50:53], v[180:183], v[196:199], v[50:53]
	v_mfma_f32_16x16x32_bf16 v[46:49], v[166:169], v[204:207], v[46:49]
	v_mfma_f32_16x16x32_bf16 v[42:45], v[180:183], v[204:207], v[42:45]
	v_mfma_f32_16x16x32_bf16 v[38:41], v[166:169], v[212:215], v[38:41]
	v_mfma_f32_16x16x32_bf16 v[34:37], v[180:183], v[212:215], v[34:37]
	v_mfma_f32_16x16x32_bf16 v[62:65], v[170:173], v[192:195], v[62:65]
	v_mfma_f32_16x16x32_bf16 v[58:61], v[184:187], v[192:195], v[58:61]
	v_mfma_f32_16x16x32_bf16 v[54:57], v[170:173], v[200:203], v[54:57]
	v_mfma_f32_16x16x32_bf16 v[50:53], v[184:187], v[200:203], v[50:53]
	v_mfma_f32_16x16x32_bf16 v[46:49], v[170:173], v[208:211], v[46:49]
	v_mfma_f32_16x16x32_bf16 v[42:45], v[184:187], v[208:211], v[42:45]
	v_mfma_f32_16x16x32_bf16 v[38:41], v[170:173], v[216:219], v[38:41]
	v_mfma_f32_16x16x32_bf16 v[34:37], v[184:187], v[216:219], v[34:37]
	s_barrier
	s_setprio 0
	s_add_i32 s0, s50, s54
	v_lshl_add_u64 v[152:153], s[14:15], 0, v[136:137]
	s_mov_b32 m0, s0
	s_nop 0
	global_load_lds_dwordx4 v[152:153], off
	s_add_i32 m0, s0, 0x2000
	s_add_u32 s0, s14, 0x30000
	v_lshl_add_u64 v[174:175], s[14:15], 0, v[140:141]
	s_addc_u32 s1, s15, 0
	s_add_i32 s50, s51, s54
	global_load_lds_dwordx4 v[174:175], off
	v_lshl_add_u64 v[220:221], s[0:1], 0, v[136:137]
	s_mov_b32 m0, s50
	v_lshl_add_u64 v[222:223], s[16:17], 0, v[138:139]
	global_load_lds_dwordx4 v[220:221], off
	v_lshl_add_u64 v[220:221], s[0:1], 0, v[140:141]
	s_add_i32 m0, s50, 0x2000
	s_nop 0
	global_load_lds_dwordx4 v[220:221], off
	v_lshl_add_u64 v[220:221], s[16:17], 0, v[134:135]
	s_mov_b32 m0, s28
	s_nop 0
	global_load_lds_dwordx4 v[220:221], off
	s_mov_b32 m0, s29
	s_nop 0
	global_load_lds_dwordx4 v[222:223], off
	ds_read_b128 v[188:191], v156 offset:16384
	ds_read_b128 v[192:195], v156 offset:17408
	ds_read_b128 v[196:199], v156 offset:18432
	ds_read_b128 v[200:203], v156 offset:19456
	ds_read_b128 v[204:207], v156 offset:20480
	ds_read_b128 v[208:211], v156 offset:21504
	ds_read_b128 v[212:215], v156 offset:22528
	ds_read_b128 v[216:219], v156 offset:23552
	s_waitcnt vmcnt(8)
	s_waitcnt lgkmcnt(0)
	s_setprio 1
	s_barrier
; #define PG8_STAGE(bufoff, gbase, voff) do { _Pragma("unroll") for (int _i = 0; _i < 2; ++_i) \
;         __builtin_amdgcn_global_load_lds((const unsigned*)((const char*)(gbase) + (voff)[_i]), (LAS unsigned*)(lds + (bufoff) + ldsw + _i * 8192), 16, 0, 0); } while (0)
; #define PG8_LDA(dst, b, h) do { _Pragma("unroll") for (int m = 0; m < 4; ++m) _Pragma("unroll") for (int k = 0; k < 2; ++k) dst[m][k] = *(const LAS bf16x8*)(lds + PG8_SA(b, h) + aoff + m * 2048 + k * 1024); } while (0)
; #define PG8_LDB(dst, b, h) do { _Pragma("unroll") for (int n = 0; n < 2; ++n) _Pragma("unroll") for (int k = 0; k < 2; ++k) dst[n][k] = *(const LAS bf16x8*)(lds + PG8_SB(b, h) + boff + n * 2048 + k * 1024); } while (0)
; #define PG8_MMA(ai, bj, At, Bt) do { __builtin_amdgcn_s_setprio(1); _Pragma("unroll") for (int m = 0; m < 4; ++m) _Pragma("unroll") for (int n = 0; n < 2; ++n) _Pragma("unroll") for (int k = 0; k < 2; ++k) \
;         acc[ai][bj][m][n] = __builtin_amdgcn_mfma_f32_16x16x32_bf16(Bt[n][k], At[m][k], acc[ai][bj][m][n], 0, 0, 0); __builtin_amdgcn_s_setprio(0); } while (0)
; #define PG8_WAIT_V(n) asm volatile("s_waitcnt vmcnt(" #n ")" ::: "memory")
; #define PG8_WAIT_L(n) asm volatile("s_waitcnt lgkmcnt(" #n ")" ::: "memory")
; #define PG8_BAR __builtin_amdgcn_s_barrier()
; #define PG8_SCHED __builtin_amdgcn_sched_barrier(0)
; template <class Epi, class Sched, int LDA, int LDB, bool ALIGN_EPI = true>
; __device__ __forceinline__ void gemm_phase(LAS unsigned char* lds, const Gemm g, const Sched& S, const Epi& E, int wave) {
;     ...
;             PG8_WAIT_V(8); PG8_WAIT_L(0); PG8_BAR; PG8_MMA(1, 0, At, B0); PG8_MMA(1, 1, At, B1); PG8_BAR; PG8_SCHED;
;             PG8_LDB(B0, 1, 0); PG8_LDB(B1, 1, 1); PG8_SCHED; PG8_LDA(At, 1, 0); PG8_STAGE(PG8_SA(0, 1), a2 + hstepA, voffA);
;             PG8_WAIT_V(8); PG8_WAIT_L(0); PG8_BAR; PG8_MMA(0, 0, At, B0); PG8_MMA(0, 1, At, B1); PG8_BAR; PG8_SCHED;
	v_mfma_f32_16x16x32_bf16 v[94:97], v[130:133], v[188:191], v[94:97]
	v_mfma_f32_16x16x32_bf16 v[90:93], v[158:161], v[188:191], v[90:93]
	v_mfma_f32_16x16x32_bf16 v[86:89], v[130:133], v[196:199], v[86:89]
	v_mfma_f32_16x16x32_bf16 v[82:85], v[158:161], v[196:199], v[82:85]
	v_mfma_f32_16x16x32_bf16 v[78:81], v[130:133], v[204:207], v[78:81]
	v_mfma_f32_16x16x32_bf16 v[74:77], v[158:161], v[204:207], v[74:77]
	v_mfma_f32_16x16x32_bf16 v[70:73], v[130:133], v[212:215], v[70:73]
	v_mfma_f32_16x16x32_bf16 v[66:69], v[158:161], v[212:215], v[66:69]
	v_mfma_f32_16x16x32_bf16 v[94:97], v[148:151], v[192:195], v[94:97]
	v_mfma_f32_16x16x32_bf16 v[90:93], v[162:165], v[192:195], v[90:93]
	v_mfma_f32_16x16x32_bf16 v[86:89], v[148:151], v[200:203], v[86:89]
	v_mfma_f32_16x16x32_bf16 v[82:85], v[162:165], v[200:203], v[82:85]
	v_mfma_f32_16x16x32_bf16 v[78:81], v[148:151], v[208:211], v[78:81]
	v_mfma_f32_16x16x32_bf16 v[74:77], v[162:165], v[208:211], v[74:77]
	v_mfma_f32_16x16x32_bf16 v[70:73], v[148:151], v[216:219], v[70:73]
	v_mfma_f32_16x16x32_bf16 v[66:69], v[162:165], v[216:219], v[66:69]
	v_mfma_f32_16x16x32_bf16 v[30:33], v[166:169], v[188:191], v[30:33]
	v_mfma_f32_16x16x32_bf16 v[26:29], v[180:183], v[188:191], v[26:29]
	v_mfma_f32_16x16x32_bf16 v[22:25], v[166:169], v[196:199], v[22:25]
	v_mfma_f32_16x16x32_bf16 v[18:21], v[180:183], v[196:199], v[18:21]
	v_mfma_f32_16x16x32_bf16 v[14:17], v[166:169], v[204:207], v[14:17]
	v_mfma_f32_16x16x32_bf16 v[10:13], v[180:183], v[204:207], v[10:13]
	v_mfma_f32_16x16x32_bf16 v[6:9], v[166:169], v[212:215], v[6:9]
	v_mfma_f32_16x16x32_bf16 v[2:5], v[180:183], v[212:215], v[2:5]
	v_mfma_f32_16x16x32_bf16 v[30:33], v[170:173], v[192:195], v[30:33]
	v_mfma_f32_16x16x32_bf16 v[26:29], v[184:187], v[192:195], v[26:29]
	v_mfma_f32_16x16x32_bf16 v[22:25], v[170:173], v[200:203], v[22:25]
	v_mfma_f32_16x16x32_bf16 v[18:21], v[184:187], v[200:203], v[18:21]
	v_mfma_f32_16x16x32_bf16 v[14:17], v[170:173], v[208:211], v[14:17]
	v_mfma_f32_16x16x32_bf16 v[10:13], v[184:187], v[208:211], v[10:13]
	v_mfma_f32_16x16x32_bf16 v[6:9], v[170:173], v[216:219], v[6:9]
	v_mfma_f32_16x16x32_bf16 v[2:5], v[184:187], v[216:219], v[2:5]
	s_barrier
	s_setprio 0
	s_add_i32 s50, 0, 0x18000
	s_add_i32 s51, 0, 0x1c000
	s_add_u32 s0, s16, 0x30000
	s_addc_u32 s1, s17, 0
	s_mov_b32 m0, s34
	v_lshl_add_u64 v[224:225], s[0:1], 0, v[134:135]
	global_load_lds_dwordx4 v[224:225], off
	v_lshl_add_u64 v[224:225], s[0:1], 0, v[138:139]
	s_mov_b32 m0, s35
	s_nop 0
	global_load_lds_dwordx4 v[224:225], off
	v_add_u32_e32 v0, s50, v154
	ds_read_b128 v[130:133], v0
	ds_read_b128 v[148:151], v0 offset:1024
	ds_read_b128 v[158:161], v0 offset:2048
	ds_read_b128 v[162:165], v0 offset:3072
	v_add_u32_e32 v0, s51, v154
	ds_read_b128 v[166:169], v0
	ds_read_b128 v[170:173], v0 offset:1024
	ds_read_b128 v[180:183], v0 offset:2048
	ds_read_b128 v[184:187], v0 offset:3072
	ds_read_b128 v[188:191], v156 offset:32768
	ds_read_b128 v[192:195], v156 offset:33792
	ds_read_b128 v[196:199], v156 offset:34816
	ds_read_b128 v[200:203], v156 offset:35840
	ds_read_b128 v[204:207], v156 offset:36864
	ds_read_b128 v[208:211], v156 offset:37888
	ds_read_b128 v[212:215], v156 offset:38912
	ds_read_b128 v[216:219], v156 offset:39936
	s_waitcnt vmcnt(8)
	s_waitcnt lgkmcnt(0)
	s_setprio 1
	s_barrier
	v_mfma_f32_16x16x32_bf16 v[126:129], v[130:133], v[188:191], v[126:129]
	v_mfma_f32_16x16x32_bf16 v[122:125], v[158:161], v[188:191], v[122:125]
	v_mfma_f32_16x16x32_bf16 v[118:121], v[130:133], v[196:199], v[118:121]
	v_mfma_f32_16x16x32_bf16 v[114:117], v[158:161], v[196:199], v[114:117]
	v_mfma_f32_16x16x32_bf16 v[110:113], v[130:133], v[204:207], v[110:113]
	v_mfma_f32_16x16x32_bf16 v[106:109], v[158:161], v[204:207], v[106:109]
	v_mfma_f32_16x16x32_bf16 v[102:105], v[130:133], v[212:215], v[102:105]
	v_mfma_f32_16x16x32_bf16 v[98:101], v[158:161], v[212:215], v[98:101]
	v_mfma_f32_16x16x32_bf16 v[126:129], v[148:151], v[192:195], v[126:129]
	v_mfma_f32_16x16x32_bf16 v[122:125], v[162:165], v[192:195], v[122:125]
	v_mfma_f32_16x16x32_bf16 v[118:121], v[148:151], v[200:203], v[118:121]
	v_mfma_f32_16x16x32_bf16 v[114:117], v[162:165], v[200:203], v[114:117]
	v_mfma_f32_16x16x32_bf16 v[110:113], v[148:151], v[208:211], v[110:113]
	v_mfma_f32_16x16x32_bf16 v[106:109], v[162:165], v[208:211], v[106:109]
	v_mfma_f32_16x16x32_bf16 v[102:105], v[148:151], v[216:219], v[102:105]
	v_mfma_f32_16x16x32_bf16 v[98:101], v[162:165], v[216:219], v[98:101]
	v_mfma_f32_16x16x32_bf16 v[62:65], v[166:169], v[188:191], v[62:65]
	v_mfma_f32_16x16x32_bf16 v[58:61], v[180:183], v[188:191], v[58:61]
	v_mfma_f32_16x16x32_bf16 v[54:57], v[166:169], v[196:199], v[54:57]
	v_mfma_f32_16x16x32_bf16 v[50:53], v[180:183], v[196:199], v[50:53]
	v_mfma_f32_16x16x32_bf16 v[46:49], v[166:169], v[204:207], v[46:49]
	v_mfma_f32_16x16x32_bf16 v[42:45], v[180:183], v[204:207], v[42:45]
	v_mfma_f32_16x16x32_bf16 v[38:41], v[166:169], v[212:215], v[38:41]
	v_mfma_f32_16x16x32_bf16 v[34:37], v[180:183], v[212:215], v[34:37]
	v_mfma_f32_16x16x32_bf16 v[62:65], v[170:173], v[192:195], v[62:65]
	v_mfma_f32_16x16x32_bf16 v[58:61], v[184:187], v[192:195], v[58:61]
	v_mfma_f32_16x16x32_bf16 v[54:57], v[170:173], v[200:203], v[54:57]
	v_mfma_f32_16x16x32_bf16 v[50:53], v[184:187], v[200:203], v[50:53]
	v_mfma_f32_16x16x32_bf16 v[46:49], v[170:173], v[208:211], v[46:49]
	v_mfma_f32_16x16x32_bf16 v[42:45], v[184:187], v[208:211], v[42:45]
	v_mfma_f32_16x16x32_bf16 v[38:41], v[170:173], v[216:219], v[38:41]
	v_mfma_f32_16x16x32_bf16 v[34:37], v[184:187], v[216:219], v[34:37]
	s_barrier
; #define PG8_STAGE(bufoff, gbase, voff) do { _Pragma("unroll") for (int _i = 0; _i < 2; ++_i) \
;         __builtin_amdgcn_global_load_lds((const unsigned*)((const char*)(gbase) + (voff)[_i]), (LAS unsigned*)(lds + (bufoff) + ldsw + _i * 8192), 16, 0, 0); } while (0)
; #define PG8_LDA(dst, b, h) do { _Pragma("unroll") for (int m = 0; m < 4; ++m) _Pragma("unroll") for (int k = 0; k < 2; ++k) dst[m][k] = *(const LAS bf16x8*)(lds + PG8_SA(b, h) + aoff + m * 2048 + k * 1024); } while (0)
; #define PG8_MMA(ai, bj, At, Bt) do { __builtin_amdgcn_s_setprio(1); _Pragma("unroll") for (int m = 0; m < 4; ++m) _Pragma("unroll") for (int n = 0; n < 2; ++n) _Pragma("unroll") for (int k = 0; k < 2; ++k) \
;         acc[ai][bj][m][n] = __builtin_amdgcn_mfma_f32_16x16x32_bf16(Bt[n][k], At[m][k], acc[ai][bj][m][n], 0, 0, 0); __builtin_amdgcn_s_setprio(0); } while (0)
; #define PG8_WAIT_V(n) asm volatile("s_waitcnt vmcnt(" #n ")" ::: "memory")
; #define PG8_WAIT_L(n) asm volatile("s_waitcnt lgkmcnt(" #n ")" ::: "memory")
; #define PG8_BAR __builtin_amdgcn_s_barrier()
; #define PG8_SCHED __builtin_amdgcn_sched_barrier(0)
; template <class Epi, class Sched, int LDA, int LDB, bool ALIGN_EPI = true>
; __device__ __forceinline__ void gemm_phase(LAS unsigned char* lds, const Gemm g, const Sched& S, const Epi& E, int wave) {
;     ...
;             PG8_LDA(At, 1, 1); PG8_STAGE(PG8_SB(1, 0), b3, voffB); PG8_STAGE(PG8_SB(1, 1), b3 + hstepB, voffB); PG8_STAGE(PG8_SA(1, 0), a3, voffA);
;             PG8_WAIT_V(8); PG8_WAIT_L(0); PG8_BAR; PG8_MMA(1, 0, At, B0); PG8_MMA(1, 1, At, B1); PG8_BAR; PG8_SCHED;
;         }
;         if constexpr (ALIGN_EPI) { if (wr == 0) PG8_BAR; }
	s_setprio 0
	s_add_i32 s0, s50, s54
	v_lshl_add_u64 v[152:153], v[152:153], 0, s[72:73]
	s_mov_b32 m0, s0
	s_nop 0
	global_load_lds_dwordx4 v[152:153], off
	s_add_i32 m0, s0, 0x2000
	s_add_u32 s0, s14, 0x30080
	v_lshl_add_u64 v[152:153], v[174:175], 0, s[72:73]
	s_addc_u32 s1, s15, 0
	s_add_i32 s14, s51, s54
	global_load_lds_dwordx4 v[152:153], off
	v_lshl_add_u64 v[152:153], s[0:1], 0, v[136:137]
	s_mov_b32 m0, s14
	s_nop 0
	global_load_lds_dwordx4 v[152:153], off
	v_lshl_add_u64 v[152:153], s[0:1], 0, v[140:141]
	s_add_i32 m0, s14, 0x2000
	s_nop 0
	global_load_lds_dwordx4 v[152:153], off
	v_lshl_add_u64 v[152:153], v[220:221], 0, s[72:73]
	s_mov_b32 m0, s36
	s_nop 0
	global_load_lds_dwordx4 v[152:153], off
	v_lshl_add_u64 v[152:153], v[222:223], 0, s[72:73]
	s_mov_b32 m0, s37
	s_nop 0
	global_load_lds_dwordx4 v[152:153], off
	ds_read_b128 v[188:191], v156 offset:49152
	ds_read_b128 v[192:195], v156 offset:50176
	ds_read_b128 v[196:199], v156 offset:51200
	ds_read_b128 v[200:203], v156 offset:52224
	ds_read_b128 v[204:207], v156 offset:53248
	ds_read_b128 v[208:211], v156 offset:54272
	ds_read_b128 v[212:215], v156 offset:55296
	ds_read_b128 v[216:219], v156 offset:56320
	s_waitcnt vmcnt(8)
	s_waitcnt lgkmcnt(0)
	s_setprio 1
	s_barrier
	v_mfma_f32_16x16x32_bf16 v[94:97], v[130:133], v[188:191], v[94:97]
	v_mfma_f32_16x16x32_bf16 v[90:93], v[158:161], v[188:191], v[90:93]
	v_mfma_f32_16x16x32_bf16 v[86:89], v[130:133], v[196:199], v[86:89]
	v_mfma_f32_16x16x32_bf16 v[82:85], v[158:161], v[196:199], v[82:85]
	v_mfma_f32_16x16x32_bf16 v[78:81], v[130:133], v[204:207], v[78:81]
	v_mfma_f32_16x16x32_bf16 v[74:77], v[158:161], v[204:207], v[74:77]
	v_mfma_f32_16x16x32_bf16 v[70:73], v[130:133], v[212:215], v[70:73]
	v_mfma_f32_16x16x32_bf16 v[66:69], v[158:161], v[212:215], v[66:69]
	v_mfma_f32_16x16x32_bf16 v[94:97], v[148:151], v[192:195], v[94:97]
	v_mfma_f32_16x16x32_bf16 v[90:93], v[162:165], v[192:195], v[90:93]
	v_mfma_f32_16x16x32_bf16 v[86:89], v[148:151], v[200:203], v[86:89]
	v_mfma_f32_16x16x32_bf16 v[82:85], v[162:165], v[200:203], v[82:85]
	v_mfma_f32_16x16x32_bf16 v[78:81], v[148:151], v[208:211], v[78:81]
	v_mfma_f32_16x16x32_bf16 v[74:77], v[162:165], v[208:211], v[74:77]
	v_mfma_f32_16x16x32_bf16 v[70:73], v[148:151], v[216:219], v[70:73]
	v_mfma_f32_16x16x32_bf16 v[66:69], v[162:165], v[216:219], v[66:69]
	v_mfma_f32_16x16x32_bf16 v[30:33], v[166:169], v[188:191], v[30:33]
	v_mfma_f32_16x16x32_bf16 v[26:29], v[180:183], v[188:191], v[26:29]
	v_mfma_f32_16x16x32_bf16 v[22:25], v[166:169], v[196:199], v[22:25]
	v_mfma_f32_16x16x32_bf16 v[18:21], v[180:183], v[196:199], v[18:21]
	v_mfma_f32_16x16x32_bf16 v[14:17], v[166:169], v[204:207], v[14:17]
	v_mfma_f32_16x16x32_bf16 v[10:13], v[180:183], v[204:207], v[10:13]
	v_mfma_f32_16x16x32_bf16 v[6:9], v[166:169], v[212:215], v[6:9]
	v_mfma_f32_16x16x32_bf16 v[2:5], v[180:183], v[212:215], v[2:5]
	v_mfma_f32_16x16x32_bf16 v[30:33], v[170:173], v[192:195], v[30:33]
	v_mfma_f32_16x16x32_bf16 v[26:29], v[184:187], v[192:195], v[26:29]
	v_mfma_f32_16x16x32_bf16 v[22:25], v[170:173], v[200:203], v[22:25]
	v_mfma_f32_16x16x32_bf16 v[18:21], v[184:187], v[200:203], v[18:21]
	v_mfma_f32_16x16x32_bf16 v[14:17], v[170:173], v[208:211], v[14:17]
	v_mfma_f32_16x16x32_bf16 v[10:13], v[184:187], v[208:211], v[10:13]
	v_mfma_f32_16x16x32_bf16 v[6:9], v[170:173], v[216:219], v[6:9]
	v_mfma_f32_16x16x32_bf16 v[2:5], v[184:187], v[216:219], v[2:5]
	s_barrier
	s_setprio 0
	s_add_i32 s49, s49, 2
	s_add_u32 s46, s46, 0x100
	s_addc_u32 s47, s47, 0
	s_cmp_gt_u32 s49, 9
	s_mov_b64 s[0:1], s[2:3]
	s_cbranch_scc0 .LBB0_2551
	v_readlane_b32 s0, v252, 14
	v_readlane_b32 s1, v252, 15
	s_and_b64 vcc, exec, s[0:1]
	s_cbranch_vccz .LBB0_2554
	s_barrier

; #define PG8_STAGE(bufoff, gbase, voff) do { _Pragma("unroll") for (int _i = 0; _i < 2; ++_i) \
;         __builtin_amdgcn_global_load_lds((const unsigned*)((const char*)(gbase) + (voff)[_i]), (LAS unsigned*)(lds + (bufoff) + ldsw + _i * 8192), 16, 0, 0); } while (0)
; #define PG8_LDA(dst, b, h) do { _Pragma("unroll") for (int m = 0; m < 4; ++m) _Pragma("unroll") for (int k = 0; k < 2; ++k) dst[m][k] = *(const LAS bf16x8*)(lds + PG8_SA(b, h) + aoff + m * 2048 + k * 1024); } while (0)
; #define PG8_LDB(dst, b, h) do { _Pragma("unroll") for (int n = 0; n < 2; ++n) _Pragma("unroll") for (int k = 0; k < 2; ++k) dst[n][k] = *(const LAS bf16x8*)(lds + PG8_SB(b, h) + boff + n * 2048 + k * 1024); } while (0)
; #define PG8_MMA(ai, bj, At, Bt) do { __builtin_amdgcn_s_setprio(1); _Pragma("unroll") for (int m = 0; m < 4; ++m) _Pragma("unroll") for (int n = 0; n < 2; ++n) _Pragma("unroll") for (int k = 0; k < 2; ++k) \
;         acc[ai][bj][m][n] = __builtin_amdgcn_mfma_f32_16x16x32_bf16(Bt[n][k], At[m][k], acc[ai][bj][m][n], 0, 0, 0); __builtin_amdgcn_s_setprio(0); } while (0)
; #define PG8_WAIT_V(n) asm volatile("s_waitcnt vmcnt(" #n ")" ::: "memory")
; #define PG8_WAIT_L(n) asm volatile("s_waitcnt lgkmcnt(" #n ")" ::: "memory")
; #define PG8_BAR __builtin_amdgcn_s_barrier()
; #define PG8_SCHED __builtin_amdgcn_sched_barrier(0)
; template <class Epi, class Sched, int LDA, int LDB, bool ALIGN_EPI = true>
; __device__ __forceinline__ void gemm_phase(LAS unsigned char* lds, const Gemm g, const Sched& S, const Epi& E, int wave) {
;     ...
;             PG8_LDB(B0, 0, 0); PG8_LDB(B1, 0, 1); PG8_SCHED; PG8_LDA(At, 0, 0); PG8_STAGE(PG8_SA(1, 1), a1 + hstepA, voffA);
;             PG8_WAIT_V(8); PG8_WAIT_L(0); PG8_BAR; PG8_MMA(0, 0, At, B0); PG8_MMA(0, 1, At, B1); PG8_BAR; PG8_SCHED;
;             PG8_LDA(At, 0, 1); PG8_STAGE(PG8_SB(0, 0), b2, voffB); PG8_STAGE(PG8_SB(0, 1), b2 + hstepB, voffB); PG8_STAGE(PG8_SA(0, 0), a2, voffA);
;             PG8_WAIT_V(8); PG8_WAIT_L(0); PG8_BAR; PG8_MMA(1, 0, At, B0); PG8_MMA(1, 1, At, B1); PG8_BAR; PG8_SCHED;
.LBB0_2619:
	s_add_u32 s16, s14, 0xfffe0080
	s_addc_u32 s17, s15, -1
	s_add_i32 s53, 0, 0x10000
	s_cmp_eq_u32 s52, 4
	s_cselect_b32 s19, s7, s17
	s_cselect_b32 s18, s13, s16
	s_cselect_b32 s17, s3, s51
	s_cselect_b32 s16, s44, s45
	s_add_i32 s58, 0, 0x14000
	v_lshl_add_u64 v[148:149], s[14:15], 0, v[140:141]
	s_add_i32 m0, s36, 0xc000
	s_nop 0
	global_load_lds_dwordx4 v[148:149], off
	v_lshl_add_u64 v[148:149], s[14:15], 0, v[142:143]
	s_add_i32 m0, s36, 0xe000
	s_nop 0
	global_load_lds_dwordx4 v[148:149], off
	v_add_u32_e32 v0, s53, v150
	ds_read_b128 v[144:147], v0
	ds_read_b128 v[152:155], v0 offset:1024
	ds_read_b128 v[156:159], v0 offset:2048
	ds_read_b128 v[160:163], v0 offset:3072
	v_add_u32_e32 v0, s58, v150
	ds_read_b128 v[164:167], v0
	ds_read_b128 v[168:171], v0 offset:1024
	ds_read_b128 v[172:175], v0 offset:2048
	ds_read_b128 v[180:183], v0 offset:3072
	ds_read_b128 v[184:187], v151
	ds_read_b128 v[188:191], v151 offset:1024
	ds_read_b128 v[192:195], v151 offset:2048
	ds_read_b128 v[196:199], v151 offset:3072
	ds_read_b128 v[200:203], v151 offset:4096
	ds_read_b128 v[204:207], v151 offset:5120
	ds_read_b128 v[208:211], v151 offset:6144
	ds_read_b128 v[212:215], v151 offset:7168
	s_waitcnt vmcnt(8)
	s_waitcnt lgkmcnt(0)
	s_setprio 1
	s_barrier
	v_mfma_f32_16x16x32_bf16 v[126:129], v[144:147], v[184:187], v[126:129]
	v_mfma_f32_16x16x32_bf16 v[122:125], v[156:159], v[184:187], v[122:125]
	v_mfma_f32_16x16x32_bf16 v[118:121], v[144:147], v[192:195], v[118:121]
	v_mfma_f32_16x16x32_bf16 v[114:117], v[156:159], v[192:195], v[114:117]
	v_mfma_f32_16x16x32_bf16 v[110:113], v[144:147], v[200:203], v[110:113]
	v_mfma_f32_16x16x32_bf16 v[106:109], v[156:159], v[200:203], v[106:109]
	v_mfma_f32_16x16x32_bf16 v[102:105], v[144:147], v[208:211], v[102:105]
	v_mfma_f32_16x16x32_bf16 v[98:101], v[156:159], v[208:211], v[98:101]
	v_mfma_f32_16x16x32_bf16 v[126:129], v[152:155], v[188:191], v[126:129]
	v_mfma_f32_16x16x32_bf16 v[122:125], v[160:163], v[188:191], v[122:125]
	v_mfma_f32_16x16x32_bf16 v[118:121], v[152:155], v[196:199], v[118:121]
	v_mfma_f32_16x16x32_bf16 v[114:117], v[160:163], v[196:199], v[114:117]
	v_mfma_f32_16x16x32_bf16 v[110:113], v[152:155], v[204:207], v[110:113]
	v_mfma_f32_16x16x32_bf16 v[106:109], v[160:163], v[204:207], v[106:109]
	v_mfma_f32_16x16x32_bf16 v[102:105], v[152:155], v[212:215], v[102:105]
	v_mfma_f32_16x16x32_bf16 v[98:101], v[160:163], v[212:215], v[98:101]
	v_mfma_f32_16x16x32_bf16 v[62:65], v[164:167], v[184:187], v[62:65]
	v_mfma_f32_16x16x32_bf16 v[58:61], v[172:175], v[184:187], v[58:61]
	v_mfma_f32_16x16x32_bf16 v[54:57], v[164:167], v[192:195], v[54:57]
	v_mfma_f32_16x16x32_bf16 v[50:53], v[172:175], v[192:195], v[50:53]
	v_mfma_f32_16x16x32_bf16 v[46:49], v[164:167], v[200:203], v[46:49]
	v_mfma_f32_16x16x32_bf16 v[42:45], v[172:175], v[200:203], v[42:45]
	v_mfma_f32_16x16x32_bf16 v[38:41], v[164:167], v[208:211], v[38:41]
	v_mfma_f32_16x16x32_bf16 v[34:37], v[172:175], v[208:211], v[34:37]
	v_mfma_f32_16x16x32_bf16 v[62:65], v[168:171], v[188:191], v[62:65]
	v_mfma_f32_16x16x32_bf16 v[58:61], v[180:183], v[188:191], v[58:61]
	v_mfma_f32_16x16x32_bf16 v[54:57], v[168:171], v[196:199], v[54:57]
	v_mfma_f32_16x16x32_bf16 v[50:53], v[180:183], v[196:199], v[50:53]
	v_mfma_f32_16x16x32_bf16 v[46:49], v[168:171], v[204:207], v[46:49]
	v_mfma_f32_16x16x32_bf16 v[42:45], v[180:183], v[204:207], v[42:45]
	v_mfma_f32_16x16x32_bf16 v[38:41], v[168:171], v[212:215], v[38:41]
	v_mfma_f32_16x16x32_bf16 v[34:37], v[180:183], v[212:215], v[34:37]
	s_barrier
	s_setprio 0
	s_add_i32 s53, s53, s59
	v_lshl_add_u64 v[148:149], s[16:17], 0, v[132:133]
	s_mov_b32 m0, s53
	s_nop 0
	global_load_lds_dwordx4 v[148:149], off
	s_add_i32 m0, s53, 0x2000
	s_add_u32 s54, s16, 0x20000
	v_lshl_add_u64 v[216:217], s[16:17], 0, v[136:137]
	s_addc_u32 s55, s17, 0
	s_add_i32 s53, s58, s59
	global_load_lds_dwordx4 v[216:217], off
	v_lshl_add_u64 v[218:219], s[54:55], 0, v[132:133]
	s_mov_b32 m0, s53
	v_lshl_add_u64 v[220:221], s[18:19], 0, v[134:135]
	global_load_lds_dwordx4 v[218:219], off
	v_lshl_add_u64 v[218:219], s[54:55], 0, v[136:137]
	s_add_i32 m0, s53, 0x2000
	s_nop 0
	global_load_lds_dwordx4 v[218:219], off
	v_lshl_add_u64 v[218:219], s[18:19], 0, v[130:131]
	s_mov_b32 m0, s36
	s_nop 0
	global_load_lds_dwordx4 v[218:219], off
	s_mov_b32 m0, s37
	s_nop 0
	global_load_lds_dwordx4 v[220:221], off
	ds_read_b128 v[184:187], v151 offset:16384
	ds_read_b128 v[188:191], v151 offset:17408
	ds_read_b128 v[192:195], v151 offset:18432
	ds_read_b128 v[196:199], v151 offset:19456
	ds_read_b128 v[200:203], v151 offset:20480
	ds_read_b128 v[204:207], v151 offset:21504
	ds_read_b128 v[208:211], v151 offset:22528
	ds_read_b128 v[212:215], v151 offset:23552
	s_waitcnt vmcnt(8)
	s_waitcnt lgkmcnt(0)
	s_setprio 1
	s_barrier
; #define PG8_STAGE(bufoff, gbase, voff) do { _Pragma("unroll") for (int _i = 0; _i < 2; ++_i) \
;         __builtin_amdgcn_global_load_lds((const unsigned*)((const char*)(gbase) + (voff)[_i]), (LAS unsigned*)(lds + (bufoff) + ldsw + _i * 8192), 16, 0, 0); } while (0)
; #define PG8_LDA(dst, b, h) do { _Pragma("unroll") for (int m = 0; m < 4; ++m) _Pragma("unroll") for (int k = 0; k < 2; ++k) dst[m][k] = *(const LAS bf16x8*)(lds + PG8_SA(b, h) + aoff + m * 2048 + k * 1024); } while (0)
; #define PG8_LDB(dst, b, h) do { _Pragma("unroll") for (int n = 0; n < 2; ++n) _Pragma("unroll") for (int k = 0; k < 2; ++k) dst[n][k] = *(const LAS bf16x8*)(lds + PG8_SB(b, h) + boff + n * 2048 + k * 1024); } while (0)
; #define PG8_MMA(ai, bj, At, Bt) do { __builtin_amdgcn_s_setprio(1); _Pragma("unroll") for (int m = 0; m < 4; ++m) _Pragma("unroll") for (int n = 0; n < 2; ++n) _Pragma("unroll") for (int k = 0; k < 2; ++k) \
;         acc[ai][bj][m][n] = __builtin_amdgcn_mfma_f32_16x16x32_bf16(Bt[n][k], At[m][k], acc[ai][bj][m][n], 0, 0, 0); __builtin_amdgcn_s_setprio(0); } while (0)
; #define PG8_WAIT_V(n) asm volatile("s_waitcnt vmcnt(" #n ")" ::: "memory")
; #define PG8_WAIT_L(n) asm volatile("s_waitcnt lgkmcnt(" #n ")" ::: "memory")
; #define PG8_BAR __builtin_amdgcn_s_barrier()
; #define PG8_SCHED __builtin_amdgcn_sched_barrier(0)
; template <class Epi, class Sched, int LDA, int LDB, bool ALIGN_EPI = true>
; __device__ __forceinline__ void gemm_phase(LAS unsigned char* lds, const Gemm g, const Sched& S, const Epi& E, int wave) {
;     ...
;             PG8_WAIT_V(8); PG8_WAIT_L(0); PG8_BAR; PG8_MMA(1, 0, At, B0); PG8_MMA(1, 1, At, B1); PG8_BAR; PG8_SCHED;
;             PG8_LDB(B0, 1, 0); PG8_LDB(B1, 1, 1); PG8_SCHED; PG8_LDA(At, 1, 0); PG8_STAGE(PG8_SA(0, 1), a2 + hstepA, voffA);
;             PG8_WAIT_V(8); PG8_WAIT_L(0); PG8_BAR; PG8_MMA(0, 0, At, B0); PG8_MMA(0, 1, At, B1); PG8_BAR; PG8_SCHED;
	v_mfma_f32_16x16x32_bf16 v[94:97], v[144:147], v[184:187], v[94:97]
	v_mfma_f32_16x16x32_bf16 v[90:93], v[156:159], v[184:187], v[90:93]
	v_mfma_f32_16x16x32_bf16 v[86:89], v[144:147], v[192:195], v[86:89]
	v_mfma_f32_16x16x32_bf16 v[82:85], v[156:159], v[192:195], v[82:85]
	v_mfma_f32_16x16x32_bf16 v[78:81], v[144:147], v[200:203], v[78:81]
	v_mfma_f32_16x16x32_bf16 v[74:77], v[156:159], v[200:203], v[74:77]
	v_mfma_f32_16x16x32_bf16 v[70:73], v[144:147], v[208:211], v[70:73]
	v_mfma_f32_16x16x32_bf16 v[66:69], v[156:159], v[208:211], v[66:69]
	v_mfma_f32_16x16x32_bf16 v[94:97], v[152:155], v[188:191], v[94:97]
	v_mfma_f32_16x16x32_bf16 v[90:93], v[160:163], v[188:191], v[90:93]
	v_mfma_f32_16x16x32_bf16 v[86:89], v[152:155], v[196:199], v[86:89]
	v_mfma_f32_16x16x32_bf16 v[82:85], v[160:163], v[196:199], v[82:85]
	v_mfma_f32_16x16x32_bf16 v[78:81], v[152:155], v[204:207], v[78:81]
	v_mfma_f32_16x16x32_bf16 v[74:77], v[160:163], v[204:207], v[74:77]
	v_mfma_f32_16x16x32_bf16 v[70:73], v[152:155], v[212:215], v[70:73]
	v_mfma_f32_16x16x32_bf16 v[66:69], v[160:163], v[212:215], v[66:69]
	v_mfma_f32_16x16x32_bf16 v[30:33], v[164:167], v[184:187], v[30:33]
	v_mfma_f32_16x16x32_bf16 v[26:29], v[172:175], v[184:187], v[26:29]
	v_mfma_f32_16x16x32_bf16 v[22:25], v[164:167], v[192:195], v[22:25]
	v_mfma_f32_16x16x32_bf16 v[18:21], v[172:175], v[192:195], v[18:21]
	v_mfma_f32_16x16x32_bf16 v[14:17], v[164:167], v[200:203], v[14:17]
	v_mfma_f32_16x16x32_bf16 v[10:13], v[172:175], v[200:203], v[10:13]
	v_mfma_f32_16x16x32_bf16 v[6:9], v[164:167], v[208:211], v[6:9]
	v_mfma_f32_16x16x32_bf16 v[2:5], v[172:175], v[208:211], v[2:5]
	v_mfma_f32_16x16x32_bf16 v[30:33], v[168:171], v[188:191], v[30:33]
	v_mfma_f32_16x16x32_bf16 v[26:29], v[180:183], v[188:191], v[26:29]
	v_mfma_f32_16x16x32_bf16 v[22:25], v[168:171], v[196:199], v[22:25]
	v_mfma_f32_16x16x32_bf16 v[18:21], v[180:183], v[196:199], v[18:21]
	v_mfma_f32_16x16x32_bf16 v[14:17], v[168:171], v[204:207], v[14:17]
	v_mfma_f32_16x16x32_bf16 v[10:13], v[180:183], v[204:207], v[10:13]
	v_mfma_f32_16x16x32_bf16 v[6:9], v[168:171], v[212:215], v[6:9]
	v_mfma_f32_16x16x32_bf16 v[2:5], v[180:183], v[212:215], v[2:5]
	s_barrier
	s_setprio 0
	s_add_i32 s53, 0, 0x18000
	s_add_i32 s54, 0, 0x1c000
	s_add_u32 s18, s18, 0x20000
	s_addc_u32 s19, s19, 0
	s_mov_b32 m0, s38
	v_lshl_add_u64 v[222:223], s[18:19], 0, v[130:131]
	global_load_lds_dwordx4 v[222:223], off
	v_lshl_add_u64 v[222:223], s[18:19], 0, v[134:135]
	s_mov_b32 m0, s39
	s_nop 0
	global_load_lds_dwordx4 v[222:223], off
	v_add_u32_e32 v0, s53, v150
	ds_read_b128 v[144:147], v0
	ds_read_b128 v[152:155], v0 offset:1024
	ds_read_b128 v[156:159], v0 offset:2048
	ds_read_b128 v[160:163], v0 offset:3072
	v_add_u32_e32 v0, s54, v150
	ds_read_b128 v[164:167], v0
	ds_read_b128 v[168:171], v0 offset:1024
	ds_read_b128 v[172:175], v0 offset:2048
	ds_read_b128 v[180:183], v0 offset:3072
	ds_read_b128 v[184:187], v151 offset:32768
	ds_read_b128 v[188:191], v151 offset:33792
	ds_read_b128 v[192:195], v151 offset:34816
	ds_read_b128 v[196:199], v151 offset:35840
	ds_read_b128 v[200:203], v151 offset:36864
	ds_read_b128 v[204:207], v151 offset:37888
	ds_read_b128 v[208:211], v151 offset:38912
	ds_read_b128 v[212:215], v151 offset:39936
	s_waitcnt vmcnt(8)
	s_waitcnt lgkmcnt(0)
	s_setprio 1
	s_barrier
	v_mfma_f32_16x16x32_bf16 v[126:129], v[144:147], v[184:187], v[126:129]
	v_mfma_f32_16x16x32_bf16 v[122:125], v[156:159], v[184:187], v[122:125]
	v_mfma_f32_16x16x32_bf16 v[118:121], v[144:147], v[192:195], v[118:121]
	v_mfma_f32_16x16x32_bf16 v[114:117], v[156:159], v[192:195], v[114:117]
	v_mfma_f32_16x16x32_bf16 v[110:113], v[144:147], v[200:203], v[110:113]
	v_mfma_f32_16x16x32_bf16 v[106:109], v[156:159], v[200:203], v[106:109]
	v_mfma_f32_16x16x32_bf16 v[102:105], v[144:147], v[208:211], v[102:105]
	v_mfma_f32_16x16x32_bf16 v[98:101], v[156:159], v[208:211], v[98:101]
	v_mfma_f32_16x16x32_bf16 v[126:129], v[152:155], v[188:191], v[126:129]
	v_mfma_f32_16x16x32_bf16 v[122:125], v[160:163], v[188:191], v[122:125]
	v_mfma_f32_16x16x32_bf16 v[118:121], v[152:155], v[196:199], v[118:121]
	v_mfma_f32_16x16x32_bf16 v[114:117], v[160:163], v[196:199], v[114:117]
	v_mfma_f32_16x16x32_bf16 v[110:113], v[152:155], v[204:207], v[110:113]
	v_mfma_f32_16x16x32_bf16 v[106:109], v[160:163], v[204:207], v[106:109]
	v_mfma_f32_16x16x32_bf16 v[102:105], v[152:155], v[212:215], v[102:105]
	v_mfma_f32_16x16x32_bf16 v[98:101], v[160:163], v[212:215], v[98:101]
	v_mfma_f32_16x16x32_bf16 v[62:65], v[164:167], v[184:187], v[62:65]
	v_mfma_f32_16x16x32_bf16 v[58:61], v[172:175], v[184:187], v[58:61]
	v_mfma_f32_16x16x32_bf16 v[54:57], v[164:167], v[192:195], v[54:57]
	v_mfma_f32_16x16x32_bf16 v[50:53], v[172:175], v[192:195], v[50:53]
	v_mfma_f32_16x16x32_bf16 v[46:49], v[164:167], v[200:203], v[46:49]
	v_mfma_f32_16x16x32_bf16 v[42:45], v[172:175], v[200:203], v[42:45]
	v_mfma_f32_16x16x32_bf16 v[38:41], v[164:167], v[208:211], v[38:41]
	v_mfma_f32_16x16x32_bf16 v[34:37], v[172:175], v[208:211], v[34:37]
	v_mfma_f32_16x16x32_bf16 v[62:65], v[168:171], v[188:191], v[62:65]
	v_mfma_f32_16x16x32_bf16 v[58:61], v[180:183], v[188:191], v[58:61]
	v_mfma_f32_16x16x32_bf16 v[54:57], v[168:171], v[196:199], v[54:57]
	v_mfma_f32_16x16x32_bf16 v[50:53], v[180:183], v[196:199], v[50:53]
	v_mfma_f32_16x16x32_bf16 v[46:49], v[168:171], v[204:207], v[46:49]
	v_mfma_f32_16x16x32_bf16 v[42:45], v[180:183], v[204:207], v[42:45]
	v_mfma_f32_16x16x32_bf16 v[38:41], v[168:171], v[212:215], v[38:41]
	v_mfma_f32_16x16x32_bf16 v[34:37], v[180:183], v[212:215], v[34:37]
	s_barrier
; #define PG8_STAGE(bufoff, gbase, voff) do { _Pragma("unroll") for (int _i = 0; _i < 2; ++_i) \
;         __builtin_amdgcn_global_load_lds((const unsigned*)((const char*)(gbase) + (voff)[_i]), (LAS unsigned*)(lds + (bufoff) + ldsw + _i * 8192), 16, 0, 0); } while (0)
; #define PG8_LDA(dst, b, h) do { _Pragma("unroll") for (int m = 0; m < 4; ++m) _Pragma("unroll") for (int k = 0; k < 2; ++k) dst[m][k] = *(const LAS bf16x8*)(lds + PG8_SA(b, h) + aoff + m * 2048 + k * 1024); } while (0)
; #define PG8_MMA(ai, bj, At, Bt) do { __builtin_amdgcn_s_setprio(1); _Pragma("unroll") for (int m = 0; m < 4; ++m) _Pragma("unroll") for (int n = 0; n < 2; ++n) _Pragma("unroll") for (int k = 0; k < 2; ++k) \
;         acc[ai][bj][m][n] = __builtin_amdgcn_mfma_f32_16x16x32_bf16(Bt[n][k], At[m][k], acc[ai][bj][m][n], 0, 0, 0); __builtin_amdgcn_s_setprio(0); } while (0)
; #define PG8_WAIT_V(n) asm volatile("s_waitcnt vmcnt(" #n ")" ::: "memory")
; #define PG8_WAIT_L(n) asm volatile("s_waitcnt lgkmcnt(" #n ")" ::: "memory")
; #define PG8_BAR __builtin_amdgcn_s_barrier()
; #define PG8_SCHED __builtin_amdgcn_sched_barrier(0)
; template <class Epi, class Sched, int LDA, int LDB, bool ALIGN_EPI = true>
; __device__ __forceinline__ void gemm_phase(LAS unsigned char* lds, const Gemm g, const Sched& S, const Epi& E, int wave) {
;     ...
;             PG8_LDA(At, 1, 1); PG8_STAGE(PG8_SB(1, 0), b3, voffB); PG8_STAGE(PG8_SB(1, 1), b3 + hstepB, voffB); PG8_STAGE(PG8_SA(1, 0), a3, voffA);
;             PG8_WAIT_V(8); PG8_WAIT_L(0); PG8_BAR; PG8_MMA(1, 0, At, B0); PG8_MMA(1, 1, At, B1); PG8_BAR; PG8_SCHED;
;         }
;         if constexpr (ALIGN_EPI) { if (wr == 0) PG8_BAR; }
	s_setprio 0
	s_add_i32 s18, s53, s59
	v_lshl_add_u64 v[148:149], v[148:149], 0, s[70:71]
	s_mov_b32 m0, s18
	s_nop 0
	global_load_lds_dwordx4 v[148:149], off
	s_add_i32 m0, s18, 0x2000
	s_add_u32 s16, s16, 0x20080
	v_lshl_add_u64 v[148:149], v[216:217], 0, s[70:71]
	s_addc_u32 s17, s17, 0
	s_add_i32 s18, s54, s59
	global_load_lds_dwordx4 v[148:149], off
	v_lshl_add_u64 v[148:149], s[16:17], 0, v[132:133]
	s_mov_b32 m0, s18
	s_nop 0
	global_load_lds_dwordx4 v[148:149], off
	v_lshl_add_u64 v[148:149], s[16:17], 0, v[136:137]
	s_add_i32 m0, s18, 0x2000
	s_nop 0
	global_load_lds_dwordx4 v[148:149], off
	v_lshl_add_u64 v[148:149], v[218:219], 0, s[70:71]
	s_mov_b32 m0, s46
	s_nop 0
	global_load_lds_dwordx4 v[148:149], off
	v_lshl_add_u64 v[148:149], v[220:221], 0, s[70:71]
	s_mov_b32 m0, s47
	s_nop 0
	global_load_lds_dwordx4 v[148:149], off
	ds_read_b128 v[184:187], v151 offset:49152
	ds_read_b128 v[188:191], v151 offset:50176
	ds_read_b128 v[192:195], v151 offset:51200
	ds_read_b128 v[196:199], v151 offset:52224
	ds_read_b128 v[200:203], v151 offset:53248
	ds_read_b128 v[204:207], v151 offset:54272
	ds_read_b128 v[208:211], v151 offset:55296
	ds_read_b128 v[212:215], v151 offset:56320
	s_waitcnt vmcnt(8)
	s_waitcnt lgkmcnt(0)
	s_setprio 1
	s_barrier
	v_mfma_f32_16x16x32_bf16 v[94:97], v[144:147], v[184:187], v[94:97]
	v_mfma_f32_16x16x32_bf16 v[90:93], v[156:159], v[184:187], v[90:93]
	v_mfma_f32_16x16x32_bf16 v[86:89], v[144:147], v[192:195], v[86:89]
	v_mfma_f32_16x16x32_bf16 v[82:85], v[156:159], v[192:195], v[82:85]
	v_mfma_f32_16x16x32_bf16 v[78:81], v[144:147], v[200:203], v[78:81]
	v_mfma_f32_16x16x32_bf16 v[74:77], v[156:159], v[200:203], v[74:77]
	v_mfma_f32_16x16x32_bf16 v[70:73], v[144:147], v[208:211], v[70:73]
	v_mfma_f32_16x16x32_bf16 v[66:69], v[156:159], v[208:211], v[66:69]
	v_mfma_f32_16x16x32_bf16 v[94:97], v[152:155], v[188:191], v[94:97]
	v_mfma_f32_16x16x32_bf16 v[90:93], v[160:163], v[188:191], v[90:93]
	v_mfma_f32_16x16x32_bf16 v[86:89], v[152:155], v[196:199], v[86:89]
	v_mfma_f32_16x16x32_bf16 v[82:85], v[160:163], v[196:199], v[82:85]
	v_mfma_f32_16x16x32_bf16 v[78:81], v[152:155], v[204:207], v[78:81]
	v_mfma_f32_16x16x32_bf16 v[74:77], v[160:163], v[204:207], v[74:77]
	v_mfma_f32_16x16x32_bf16 v[70:73], v[152:155], v[212:215], v[70:73]
	v_mfma_f32_16x16x32_bf16 v[66:69], v[160:163], v[212:215], v[66:69]
	v_mfma_f32_16x16x32_bf16 v[30:33], v[164:167], v[184:187], v[30:33]
	v_mfma_f32_16x16x32_bf16 v[26:29], v[172:175], v[184:187], v[26:29]
	v_mfma_f32_16x16x32_bf16 v[22:25], v[164:167], v[192:195], v[22:25]
	v_mfma_f32_16x16x32_bf16 v[18:21], v[172:175], v[192:195], v[18:21]
	v_mfma_f32_16x16x32_bf16 v[14:17], v[164:167], v[200:203], v[14:17]
	v_mfma_f32_16x16x32_bf16 v[10:13], v[172:175], v[200:203], v[10:13]
	v_mfma_f32_16x16x32_bf16 v[6:9], v[164:167], v[208:211], v[6:9]
	v_mfma_f32_16x16x32_bf16 v[2:5], v[172:175], v[208:211], v[2:5]
	v_mfma_f32_16x16x32_bf16 v[30:33], v[168:171], v[188:191], v[30:33]
	v_mfma_f32_16x16x32_bf16 v[26:29], v[180:183], v[188:191], v[26:29]
	v_mfma_f32_16x16x32_bf16 v[22:25], v[168:171], v[196:199], v[22:25]
	v_mfma_f32_16x16x32_bf16 v[18:21], v[180:183], v[196:199], v[18:21]
	v_mfma_f32_16x16x32_bf16 v[14:17], v[168:171], v[204:207], v[14:17]
	v_mfma_f32_16x16x32_bf16 v[10:13], v[180:183], v[204:207], v[10:13]
	v_mfma_f32_16x16x32_bf16 v[6:9], v[168:171], v[212:215], v[6:9]
	v_mfma_f32_16x16x32_bf16 v[2:5], v[180:183], v[212:215], v[2:5]
	s_barrier
	s_setprio 0
	s_add_i32 s52, s52, 2
	s_add_u32 s14, s14, 0x100
	s_addc_u32 s15, s15, 0
	s_add_u32 s45, s45, 0x100
	s_addc_u32 s51, s51, 0
	s_cmp_gt_u32 s52, 5
	s_cbranch_scc0 .LBB0_2619
	v_readlane_b32 s14, v252, 14
	v_readlane_b32 s15, v252, 15
	s_and_b64 vcc, exec, s[14:15]
	s_cbranch_vccz .LBB0_2622
	s_barrier

; #define PG8_STAGE(bufoff, gbase, voff) do { _Pragma("unroll") for (int _i = 0; _i < 2; ++_i) \
;         __builtin_amdgcn_global_load_lds((const unsigned*)((const char*)(gbase) + (voff)[_i]), (LAS unsigned*)(lds + (bufoff) + ldsw + _i * 8192), 16, 0, 0); } while (0)
; #define PG8_LDA(dst, b, h) do { _Pragma("unroll") for (int m = 0; m < 4; ++m) _Pragma("unroll") for (int k = 0; k < 2; ++k) dst[m][k] = *(const LAS bf16x8*)(lds + PG8_SA(b, h) + aoff + m * 2048 + k * 1024); } while (0)
; #define PG8_LDB(dst, b, h) do { _Pragma("unroll") for (int n = 0; n < 2; ++n) _Pragma("unroll") for (int k = 0; k < 2; ++k) dst[n][k] = *(const LAS bf16x8*)(lds + PG8_SB(b, h) + boff + n * 2048 + k * 1024); } while (0)
; #define PG8_MMA(ai, bj, At, Bt) do { __builtin_amdgcn_s_setprio(1); _Pragma("unroll") for (int m = 0; m < 4; ++m) _Pragma("unroll") for (int n = 0; n < 2; ++n) _Pragma("unroll") for (int k = 0; k < 2; ++k) \
;         acc[ai][bj][m][n] = __builtin_amdgcn_mfma_f32_16x16x32_bf16(Bt[n][k], At[m][k], acc[ai][bj][m][n], 0, 0, 0); __builtin_amdgcn_s_setprio(0); } while (0)
; #define PG8_WAIT_V(n) asm volatile("s_waitcnt vmcnt(" #n ")" ::: "memory")
; #define PG8_WAIT_L(n) asm volatile("s_waitcnt lgkmcnt(" #n ")" ::: "memory")
; #define PG8_BAR __builtin_amdgcn_s_barrier()
; #define PG8_SCHED __builtin_amdgcn_sched_barrier(0)
; template <class Epi, class Sched, int LDA, int LDB, bool ALIGN_EPI = true>
; __device__ __forceinline__ void gemm_phase(LAS unsigned char* lds, const Gemm g, const Sched& S, const Epi& E, int wave) {
;     ...
;             PG8_LDB(B0, 0, 0); PG8_LDB(B1, 0, 1); PG8_SCHED; PG8_LDA(At, 0, 0); PG8_STAGE(PG8_SA(1, 1), a1 + hstepA, voffA);
;             PG8_WAIT_V(8); PG8_WAIT_L(0); PG8_BAR; PG8_MMA(0, 0, At, B0); PG8_MMA(0, 1, At, B1); PG8_BAR; PG8_SCHED;
;             PG8_LDA(At, 0, 1); PG8_STAGE(PG8_SB(0, 0), b2, voffB); PG8_STAGE(PG8_SB(0, 1), b2 + hstepB, voffB); PG8_STAGE(PG8_SA(0, 0), a2, voffA);
;             PG8_WAIT_V(8); PG8_WAIT_L(0); PG8_BAR; PG8_MMA(1, 0, At, B0); PG8_MMA(1, 1, At, B1); PG8_BAR; PG8_SCHED;
.LBB0_2649:
	s_add_u32 s18, s16, 0xfffe0080
	s_addc_u32 s19, s17, -1
	s_add_i32 s48, 0, 0x10000
	s_cmp_eq_u32 s47, 4
	s_cselect_b32 s25, s7, s19
	s_cselect_b32 s24, s13, s18
	s_cselect_b32 s19, s3, s46
	s_cselect_b32 s18, s44, s45
	s_add_i32 s50, 0, 0x14000
	v_lshl_add_u64 v[212:213], s[16:17], 0, v[144:145]
	s_add_i32 m0, s15, 0xc000
	s_nop 0
	global_load_lds_dwordx4 v[212:213], off
	v_lshl_add_u64 v[212:213], s[16:17], 0, v[146:147]
	s_add_i32 m0, s15, 0xe000
	s_nop 0
	global_load_lds_dwordx4 v[212:213], off
	v_add_u32_e32 v152, s48, v161
	v_add_u32_e32 v172, s50, v161
	ds_read_b128 v[130:133], v152
	ds_read_b128 v[134:137], v152 offset:1024
	ds_read_b128 v[148:151], v152 offset:2048
	ds_read_b128 v[152:155], v152 offset:3072
	ds_read_b128 v[156:159], v172
	ds_read_b128 v[164:167], v172 offset:1024
	ds_read_b128 v[168:171], v172 offset:2048
	ds_read_b128 v[172:175], v172 offset:3072
	ds_read_b128 v[180:183], v163
	ds_read_b128 v[184:187], v163 offset:1024
	ds_read_b128 v[188:191], v163 offset:2048
	ds_read_b128 v[192:195], v163 offset:3072
	ds_read_b128 v[196:199], v163 offset:4096
	ds_read_b128 v[200:203], v163 offset:5120
	ds_read_b128 v[204:207], v163 offset:6144
	ds_read_b128 v[208:211], v163 offset:7168
	s_waitcnt vmcnt(8)
	s_waitcnt lgkmcnt(0)
	s_setprio 1
	s_barrier
	v_mfma_f32_16x16x32_bf16 v[126:129], v[130:133], v[180:183], v[126:129]
	v_mfma_f32_16x16x32_bf16 v[122:125], v[148:151], v[180:183], v[122:125]
	v_mfma_f32_16x16x32_bf16 v[110:113], v[130:133], v[188:191], v[110:113]
	v_mfma_f32_16x16x32_bf16 v[106:109], v[148:151], v[188:191], v[106:109]
	v_mfma_f32_16x16x32_bf16 v[94:97], v[130:133], v[196:199], v[94:97]
	v_mfma_f32_16x16x32_bf16 v[90:93], v[148:151], v[196:199], v[90:93]
	v_mfma_f32_16x16x32_bf16 v[78:81], v[130:133], v[204:207], v[78:81]
	v_mfma_f32_16x16x32_bf16 v[74:77], v[148:151], v[204:207], v[74:77]
	v_mfma_f32_16x16x32_bf16 v[126:129], v[134:137], v[184:187], v[126:129]
	v_mfma_f32_16x16x32_bf16 v[122:125], v[152:155], v[184:187], v[122:125]
	v_mfma_f32_16x16x32_bf16 v[110:113], v[134:137], v[192:195], v[110:113]
	v_mfma_f32_16x16x32_bf16 v[106:109], v[152:155], v[192:195], v[106:109]
	v_mfma_f32_16x16x32_bf16 v[94:97], v[134:137], v[200:203], v[94:97]
	v_mfma_f32_16x16x32_bf16 v[90:93], v[152:155], v[200:203], v[90:93]
	v_mfma_f32_16x16x32_bf16 v[78:81], v[134:137], v[208:211], v[78:81]
	v_mfma_f32_16x16x32_bf16 v[74:77], v[152:155], v[208:211], v[74:77]
	v_mfma_f32_16x16x32_bf16 v[118:121], v[156:159], v[180:183], v[118:121]
	v_mfma_f32_16x16x32_bf16 v[114:117], v[168:171], v[180:183], v[114:117]
	v_mfma_f32_16x16x32_bf16 v[102:105], v[156:159], v[188:191], v[102:105]
	v_mfma_f32_16x16x32_bf16 v[98:101], v[168:171], v[188:191], v[98:101]
	v_mfma_f32_16x16x32_bf16 v[86:89], v[156:159], v[196:199], v[86:89]
	v_mfma_f32_16x16x32_bf16 v[82:85], v[168:171], v[196:199], v[82:85]
	v_mfma_f32_16x16x32_bf16 v[70:73], v[156:159], v[204:207], v[70:73]
	v_mfma_f32_16x16x32_bf16 v[66:69], v[168:171], v[204:207], v[66:69]
	v_mfma_f32_16x16x32_bf16 v[118:121], v[164:167], v[184:187], v[118:121]
	v_mfma_f32_16x16x32_bf16 v[114:117], v[172:175], v[184:187], v[114:117]
	v_mfma_f32_16x16x32_bf16 v[102:105], v[164:167], v[192:195], v[102:105]
	v_mfma_f32_16x16x32_bf16 v[98:101], v[172:175], v[192:195], v[98:101]
	v_mfma_f32_16x16x32_bf16 v[86:89], v[164:167], v[200:203], v[86:89]
	v_mfma_f32_16x16x32_bf16 v[82:85], v[172:175], v[200:203], v[82:85]
	v_mfma_f32_16x16x32_bf16 v[70:73], v[164:167], v[208:211], v[70:73]
	v_mfma_f32_16x16x32_bf16 v[66:69], v[172:175], v[208:211], v[66:69]
	s_barrier
	s_setprio 0
	s_add_i32 s48, s48, s51
	v_lshl_add_u64 v[212:213], s[18:19], 0, v[0:1]
	s_mov_b32 m0, s48
	s_nop 0
	global_load_lds_dwordx4 v[212:213], off
	s_add_i32 m0, s48, 0x2000
	s_add_u32 s48, s18, 0x20000
	v_lshl_add_u64 v[214:215], s[18:19], 0, v[142:143]
	s_addc_u32 s49, s19, 0
	s_add_i32 s50, s50, s51
	global_load_lds_dwordx4 v[214:215], off
	v_lshl_add_u64 v[216:217], s[48:49], 0, v[0:1]
	s_mov_b32 m0, s50
	v_lshl_add_u64 v[218:219], s[24:25], 0, v[140:141]
	global_load_lds_dwordx4 v[216:217], off
	v_lshl_add_u64 v[216:217], s[48:49], 0, v[142:143]
	s_add_i32 m0, s50, 0x2000
	s_nop 0
	global_load_lds_dwordx4 v[216:217], off
	v_lshl_add_u64 v[216:217], s[24:25], 0, v[138:139]
	s_mov_b32 m0, s15
	s_nop 0
	global_load_lds_dwordx4 v[216:217], off
	s_mov_b32 m0, s28
	s_nop 0
	global_load_lds_dwordx4 v[218:219], off
	ds_read_b128 v[180:183], v163 offset:16384
	ds_read_b128 v[184:187], v163 offset:17408
	ds_read_b128 v[188:191], v163 offset:18432
	ds_read_b128 v[192:195], v163 offset:19456
	ds_read_b128 v[196:199], v163 offset:20480
	ds_read_b128 v[200:203], v163 offset:21504
	ds_read_b128 v[204:207], v163 offset:22528
	ds_read_b128 v[208:211], v163 offset:23552
	s_waitcnt vmcnt(8)
	s_waitcnt lgkmcnt(0)
	s_setprio 1
	s_barrier
; #define PG8_STAGE(bufoff, gbase, voff) do { _Pragma("unroll") for (int _i = 0; _i < 2; ++_i) \
;         __builtin_amdgcn_global_load_lds((const unsigned*)((const char*)(gbase) + (voff)[_i]), (LAS unsigned*)(lds + (bufoff) + ldsw + _i * 8192), 16, 0, 0); } while (0)
; #define PG8_LDA(dst, b, h) do { _Pragma("unroll") for (int m = 0; m < 4; ++m) _Pragma("unroll") for (int k = 0; k < 2; ++k) dst[m][k] = *(const LAS bf16x8*)(lds + PG8_SA(b, h) + aoff + m * 2048 + k * 1024); } while (0)
; #define PG8_LDB(dst, b, h) do { _Pragma("unroll") for (int n = 0; n < 2; ++n) _Pragma("unroll") for (int k = 0; k < 2; ++k) dst[n][k] = *(const LAS bf16x8*)(lds + PG8_SB(b, h) + boff + n * 2048 + k * 1024); } while (0)
; #define PG8_MMA(ai, bj, At, Bt) do { __builtin_amdgcn_s_setprio(1); _Pragma("unroll") for (int m = 0; m < 4; ++m) _Pragma("unroll") for (int n = 0; n < 2; ++n) _Pragma("unroll") for (int k = 0; k < 2; ++k) \
;         acc[ai][bj][m][n] = __builtin_amdgcn_mfma_f32_16x16x32_bf16(Bt[n][k], At[m][k], acc[ai][bj][m][n], 0, 0, 0); __builtin_amdgcn_s_setprio(0); } while (0)
; #define PG8_WAIT_V(n) asm volatile("s_waitcnt vmcnt(" #n ")" ::: "memory")
; #define PG8_WAIT_L(n) asm volatile("s_waitcnt lgkmcnt(" #n ")" ::: "memory")
; #define PG8_BAR __builtin_amdgcn_s_barrier()
; #define PG8_SCHED __builtin_amdgcn_sched_barrier(0)
; template <class Epi, class Sched, int LDA, int LDB, bool ALIGN_EPI = true>
; __device__ __forceinline__ void gemm_phase(LAS unsigned char* lds, const Gemm g, const Sched& S, const Epi& E, int wave) {
;     ...
;             PG8_WAIT_V(8); PG8_WAIT_L(0); PG8_BAR; PG8_MMA(1, 0, At, B0); PG8_MMA(1, 1, At, B1); PG8_BAR; PG8_SCHED;
;             PG8_LDB(B0, 1, 0); PG8_LDB(B1, 1, 1); PG8_SCHED; PG8_LDA(At, 1, 0); PG8_STAGE(PG8_SA(0, 1), a2 + hstepA, voffA);
;             PG8_WAIT_V(8); PG8_WAIT_L(0); PG8_BAR; PG8_MMA(0, 0, At, B0); PG8_MMA(0, 1, At, B1); PG8_BAR; PG8_SCHED;
	v_mfma_f32_16x16x32_bf16 v[62:65], v[130:133], v[180:183], v[62:65]
	v_mfma_f32_16x16x32_bf16 v[58:61], v[148:151], v[180:183], v[58:61]
	v_mfma_f32_16x16x32_bf16 v[46:49], v[130:133], v[188:191], v[46:49]
	v_mfma_f32_16x16x32_bf16 v[42:45], v[148:151], v[188:191], v[42:45]
	v_mfma_f32_16x16x32_bf16 v[30:33], v[130:133], v[196:199], v[30:33]
	v_mfma_f32_16x16x32_bf16 v[26:29], v[148:151], v[196:199], v[26:29]
	v_mfma_f32_16x16x32_bf16 v[14:17], v[130:133], v[204:207], v[14:17]
	v_mfma_f32_16x16x32_bf16 v[10:13], v[148:151], v[204:207], v[10:13]
	v_mfma_f32_16x16x32_bf16 v[62:65], v[134:137], v[184:187], v[62:65]
	v_mfma_f32_16x16x32_bf16 v[58:61], v[152:155], v[184:187], v[58:61]
	v_mfma_f32_16x16x32_bf16 v[46:49], v[134:137], v[192:195], v[46:49]
	v_mfma_f32_16x16x32_bf16 v[42:45], v[152:155], v[192:195], v[42:45]
	v_mfma_f32_16x16x32_bf16 v[30:33], v[134:137], v[200:203], v[30:33]
	v_mfma_f32_16x16x32_bf16 v[26:29], v[152:155], v[200:203], v[26:29]
	v_mfma_f32_16x16x32_bf16 v[14:17], v[134:137], v[208:211], v[14:17]
	v_mfma_f32_16x16x32_bf16 v[10:13], v[152:155], v[208:211], v[10:13]
	v_mfma_f32_16x16x32_bf16 v[54:57], v[156:159], v[180:183], v[54:57]
	v_mfma_f32_16x16x32_bf16 v[50:53], v[168:171], v[180:183], v[50:53]
	v_mfma_f32_16x16x32_bf16 v[38:41], v[156:159], v[188:191], v[38:41]
	v_mfma_f32_16x16x32_bf16 v[34:37], v[168:171], v[188:191], v[34:37]
	v_mfma_f32_16x16x32_bf16 v[22:25], v[156:159], v[196:199], v[22:25]
	v_mfma_f32_16x16x32_bf16 v[18:21], v[168:171], v[196:199], v[18:21]
	v_mfma_f32_16x16x32_bf16 v[6:9], v[156:159], v[204:207], v[6:9]
	v_mfma_f32_16x16x32_bf16 v[2:5], v[168:171], v[204:207], v[2:5]
	v_mfma_f32_16x16x32_bf16 v[54:57], v[164:167], v[184:187], v[54:57]
	v_mfma_f32_16x16x32_bf16 v[50:53], v[172:175], v[184:187], v[50:53]
	v_mfma_f32_16x16x32_bf16 v[38:41], v[164:167], v[192:195], v[38:41]
	v_mfma_f32_16x16x32_bf16 v[34:37], v[172:175], v[192:195], v[34:37]
	v_mfma_f32_16x16x32_bf16 v[22:25], v[164:167], v[200:203], v[22:25]
	v_mfma_f32_16x16x32_bf16 v[18:21], v[172:175], v[200:203], v[18:21]
	v_mfma_f32_16x16x32_bf16 v[6:9], v[164:167], v[208:211], v[6:9]
	v_mfma_f32_16x16x32_bf16 v[2:5], v[172:175], v[208:211], v[2:5]
	s_barrier
	s_setprio 0
	s_add_i32 s48, 0, 0x18000
	s_add_i32 s49, 0, 0x1c000
	s_add_u32 s24, s24, 0x20000
	s_addc_u32 s25, s25, 0
	s_mov_b32 m0, s29
	v_lshl_add_u64 v[220:221], s[24:25], 0, v[138:139]
	global_load_lds_dwordx4 v[220:221], off
	v_lshl_add_u64 v[220:221], s[24:25], 0, v[140:141]
	s_mov_b32 m0, s34
	s_nop 0
	global_load_lds_dwordx4 v[220:221], off
	v_add_u32_e32 v152, s48, v161
	v_add_u32_e32 v172, s49, v161
	ds_read_b128 v[130:133], v152
	ds_read_b128 v[134:137], v152 offset:1024
	ds_read_b128 v[148:151], v152 offset:2048
	ds_read_b128 v[152:155], v152 offset:3072
	ds_read_b128 v[156:159], v172
	ds_read_b128 v[164:167], v172 offset:1024
	ds_read_b128 v[168:171], v172 offset:2048
	ds_read_b128 v[172:175], v172 offset:3072
	ds_read_b128 v[180:183], v163 offset:32768
	ds_read_b128 v[184:187], v163 offset:33792
	ds_read_b128 v[188:191], v163 offset:34816
	ds_read_b128 v[192:195], v163 offset:35840
	ds_read_b128 v[196:199], v163 offset:36864
	ds_read_b128 v[200:203], v163 offset:37888
	ds_read_b128 v[204:207], v163 offset:38912
	ds_read_b128 v[208:211], v163 offset:39936
	s_waitcnt vmcnt(8)
	s_waitcnt lgkmcnt(0)
	s_setprio 1
	s_barrier
	v_mfma_f32_16x16x32_bf16 v[126:129], v[130:133], v[180:183], v[126:129]
	v_mfma_f32_16x16x32_bf16 v[122:125], v[148:151], v[180:183], v[122:125]
	v_mfma_f32_16x16x32_bf16 v[110:113], v[130:133], v[188:191], v[110:113]
	v_mfma_f32_16x16x32_bf16 v[106:109], v[148:151], v[188:191], v[106:109]
	v_mfma_f32_16x16x32_bf16 v[94:97], v[130:133], v[196:199], v[94:97]
	v_mfma_f32_16x16x32_bf16 v[90:93], v[148:151], v[196:199], v[90:93]
	v_mfma_f32_16x16x32_bf16 v[78:81], v[130:133], v[204:207], v[78:81]
	v_mfma_f32_16x16x32_bf16 v[74:77], v[148:151], v[204:207], v[74:77]
	v_mfma_f32_16x16x32_bf16 v[126:129], v[134:137], v[184:187], v[126:129]
	v_mfma_f32_16x16x32_bf16 v[122:125], v[152:155], v[184:187], v[122:125]
	v_mfma_f32_16x16x32_bf16 v[110:113], v[134:137], v[192:195], v[110:113]
	v_mfma_f32_16x16x32_bf16 v[106:109], v[152:155], v[192:195], v[106:109]
	v_mfma_f32_16x16x32_bf16 v[94:97], v[134:137], v[200:203], v[94:97]
	v_mfma_f32_16x16x32_bf16 v[90:93], v[152:155], v[200:203], v[90:93]
	v_mfma_f32_16x16x32_bf16 v[78:81], v[134:137], v[208:211], v[78:81]
	v_mfma_f32_16x16x32_bf16 v[74:77], v[152:155], v[208:211], v[74:77]
	v_mfma_f32_16x16x32_bf16 v[118:121], v[156:159], v[180:183], v[118:121]
	v_mfma_f32_16x16x32_bf16 v[114:117], v[168:171], v[180:183], v[114:117]
	v_mfma_f32_16x16x32_bf16 v[102:105], v[156:159], v[188:191], v[102:105]
	v_mfma_f32_16x16x32_bf16 v[98:101], v[168:171], v[188:191], v[98:101]
	v_mfma_f32_16x16x32_bf16 v[86:89], v[156:159], v[196:199], v[86:89]
	v_mfma_f32_16x16x32_bf16 v[82:85], v[168:171], v[196:199], v[82:85]
	v_mfma_f32_16x16x32_bf16 v[70:73], v[156:159], v[204:207], v[70:73]
	v_mfma_f32_16x16x32_bf16 v[66:69], v[168:171], v[204:207], v[66:69]
	v_mfma_f32_16x16x32_bf16 v[118:121], v[164:167], v[184:187], v[118:121]
	v_mfma_f32_16x16x32_bf16 v[114:117], v[172:175], v[184:187], v[114:117]
	v_mfma_f32_16x16x32_bf16 v[102:105], v[164:167], v[192:195], v[102:105]
	v_mfma_f32_16x16x32_bf16 v[98:101], v[172:175], v[192:195], v[98:101]
	v_mfma_f32_16x16x32_bf16 v[86:89], v[164:167], v[200:203], v[86:89]
	v_mfma_f32_16x16x32_bf16 v[82:85], v[172:175], v[200:203], v[82:85]
	v_mfma_f32_16x16x32_bf16 v[70:73], v[164:167], v[208:211], v[70:73]
	v_mfma_f32_16x16x32_bf16 v[66:69], v[172:175], v[208:211], v[66:69]
	s_barrier
; #define PG8_STAGE(bufoff, gbase, voff) do { _Pragma("unroll") for (int _i = 0; _i < 2; ++_i) \
;         __builtin_amdgcn_global_load_lds((const unsigned*)((const char*)(gbase) + (voff)[_i]), (LAS unsigned*)(lds + (bufoff) + ldsw + _i * 8192), 16, 0, 0); } while (0)
; #define PG8_LDA(dst, b, h) do { _Pragma("unroll") for (int m = 0; m < 4; ++m) _Pragma("unroll") for (int k = 0; k < 2; ++k) dst[m][k] = *(const LAS bf16x8*)(lds + PG8_SA(b, h) + aoff + m * 2048 + k * 1024); } while (0)
; #define PG8_MMA(ai, bj, At, Bt) do { __builtin_amdgcn_s_setprio(1); _Pragma("unroll") for (int m = 0; m < 4; ++m) _Pragma("unroll") for (int n = 0; n < 2; ++n) _Pragma("unroll") for (int k = 0; k < 2; ++k) \
;         acc[ai][bj][m][n] = __builtin_amdgcn_mfma_f32_16x16x32_bf16(Bt[n][k], At[m][k], acc[ai][bj][m][n], 0, 0, 0); __builtin_amdgcn_s_setprio(0); } while (0)
; #define PG8_WAIT_V(n) asm volatile("s_waitcnt vmcnt(" #n ")" ::: "memory")
; #define PG8_WAIT_L(n) asm volatile("s_waitcnt lgkmcnt(" #n ")" ::: "memory")
; #define PG8_BAR __builtin_amdgcn_s_barrier()
; #define PG8_SCHED __builtin_amdgcn_sched_barrier(0)
; template <class Epi, class Sched, int LDA, int LDB, bool ALIGN_EPI = true>
; __device__ __forceinline__ void gemm_phase(LAS unsigned char* lds, const Gemm g, const Sched& S, const Epi& E, int wave) {
;     ...
;             PG8_LDA(At, 1, 1); PG8_STAGE(PG8_SB(1, 0), b3, voffB); PG8_STAGE(PG8_SB(1, 1), b3 + hstepB, voffB); PG8_STAGE(PG8_SA(1, 0), a3, voffA);
;             PG8_WAIT_V(8); PG8_WAIT_L(0); PG8_BAR; PG8_MMA(1, 0, At, B0); PG8_MMA(1, 1, At, B1); PG8_BAR; PG8_SCHED;
;         }
;         if constexpr (ALIGN_EPI) { if (wr == 0) PG8_BAR; }
	s_setprio 0
	s_add_i32 s24, s48, s51
	v_lshl_add_u64 v[212:213], v[212:213], 0, s[52:53]
	s_mov_b32 m0, s24
	s_nop 0
	global_load_lds_dwordx4 v[212:213], off
	s_add_i32 m0, s24, 0x2000
	s_add_u32 s18, s18, 0x20080
	v_lshl_add_u64 v[212:213], v[214:215], 0, s[52:53]
	s_addc_u32 s19, s19, 0
	s_add_i32 s24, s49, s51
	global_load_lds_dwordx4 v[212:213], off
	v_lshl_add_u64 v[212:213], s[18:19], 0, v[0:1]
	s_mov_b32 m0, s24
	s_nop 0
	global_load_lds_dwordx4 v[212:213], off
	v_lshl_add_u64 v[212:213], s[18:19], 0, v[142:143]
	s_add_i32 m0, s24, 0x2000
	s_nop 0
	global_load_lds_dwordx4 v[212:213], off
	v_lshl_add_u64 v[212:213], v[216:217], 0, s[52:53]
	s_mov_b32 m0, s35
	s_nop 0
	global_load_lds_dwordx4 v[212:213], off
	v_lshl_add_u64 v[212:213], v[218:219], 0, s[52:53]
	s_mov_b32 m0, s36
	s_nop 0
	global_load_lds_dwordx4 v[212:213], off
	ds_read_b128 v[180:183], v163 offset:49152
	ds_read_b128 v[184:187], v163 offset:50176
	ds_read_b128 v[188:191], v163 offset:51200
	ds_read_b128 v[192:195], v163 offset:52224
	ds_read_b128 v[196:199], v163 offset:53248
	ds_read_b128 v[200:203], v163 offset:54272
	ds_read_b128 v[204:207], v163 offset:55296
	ds_read_b128 v[208:211], v163 offset:56320
	s_waitcnt vmcnt(8)
	s_waitcnt lgkmcnt(0)
	s_setprio 1
	s_barrier
	v_mfma_f32_16x16x32_bf16 v[62:65], v[130:133], v[180:183], v[62:65]
	v_mfma_f32_16x16x32_bf16 v[58:61], v[148:151], v[180:183], v[58:61]
	v_mfma_f32_16x16x32_bf16 v[46:49], v[130:133], v[188:191], v[46:49]
	v_mfma_f32_16x16x32_bf16 v[42:45], v[148:151], v[188:191], v[42:45]
	v_mfma_f32_16x16x32_bf16 v[30:33], v[130:133], v[196:199], v[30:33]
	v_mfma_f32_16x16x32_bf16 v[26:29], v[148:151], v[196:199], v[26:29]
	v_mfma_f32_16x16x32_bf16 v[14:17], v[130:133], v[204:207], v[14:17]
	v_mfma_f32_16x16x32_bf16 v[10:13], v[148:151], v[204:207], v[10:13]
	v_mfma_f32_16x16x32_bf16 v[62:65], v[134:137], v[184:187], v[62:65]
	v_mfma_f32_16x16x32_bf16 v[58:61], v[152:155], v[184:187], v[58:61]
	v_mfma_f32_16x16x32_bf16 v[46:49], v[134:137], v[192:195], v[46:49]
	v_mfma_f32_16x16x32_bf16 v[42:45], v[152:155], v[192:195], v[42:45]
	v_mfma_f32_16x16x32_bf16 v[30:33], v[134:137], v[200:203], v[30:33]
	v_mfma_f32_16x16x32_bf16 v[26:29], v[152:155], v[200:203], v[26:29]
	v_mfma_f32_16x16x32_bf16 v[14:17], v[134:137], v[208:211], v[14:17]
	v_mfma_f32_16x16x32_bf16 v[10:13], v[152:155], v[208:211], v[10:13]
	v_mfma_f32_16x16x32_bf16 v[54:57], v[156:159], v[180:183], v[54:57]
	v_mfma_f32_16x16x32_bf16 v[50:53], v[168:171], v[180:183], v[50:53]
	v_mfma_f32_16x16x32_bf16 v[38:41], v[156:159], v[188:191], v[38:41]
	v_mfma_f32_16x16x32_bf16 v[34:37], v[168:171], v[188:191], v[34:37]
	v_mfma_f32_16x16x32_bf16 v[22:25], v[156:159], v[196:199], v[22:25]
	v_mfma_f32_16x16x32_bf16 v[18:21], v[168:171], v[196:199], v[18:21]
	v_mfma_f32_16x16x32_bf16 v[6:9], v[156:159], v[204:207], v[6:9]
	v_mfma_f32_16x16x32_bf16 v[2:5], v[168:171], v[204:207], v[2:5]
	v_mfma_f32_16x16x32_bf16 v[54:57], v[164:167], v[184:187], v[54:57]
	v_mfma_f32_16x16x32_bf16 v[50:53], v[172:175], v[184:187], v[50:53]
	v_mfma_f32_16x16x32_bf16 v[38:41], v[164:167], v[192:195], v[38:41]
	v_mfma_f32_16x16x32_bf16 v[34:37], v[172:175], v[192:195], v[34:37]
	v_mfma_f32_16x16x32_bf16 v[22:25], v[164:167], v[200:203], v[22:25]
	v_mfma_f32_16x16x32_bf16 v[18:21], v[172:175], v[200:203], v[18:21]
	v_mfma_f32_16x16x32_bf16 v[6:9], v[164:167], v[208:211], v[6:9]
	v_mfma_f32_16x16x32_bf16 v[2:5], v[172:175], v[208:211], v[2:5]
	s_barrier
	s_setprio 0
	s_add_i32 s47, s47, 2
	s_add_u32 s16, s16, 0x100
	s_addc_u32 s17, s17, 0
	s_add_u32 s45, s45, 0x100
	s_addc_u32 s46, s46, 0
	s_cmp_gt_u32 s47, 5
	s_cbranch_scc0 .LBB0_2649
	v_readlane_b32 s16, v252, 14
	v_readlane_b32 s17, v252, 15
	s_and_b64 vcc, exec, s[16:17]
	s_cbranch_vccz .LBB0_2652
	s_barrier

; #define PG8_STAGE(bufoff, gbase, voff) do { _Pragma("unroll") for (int _i = 0; _i < 2; ++_i) \
;         __builtin_amdgcn_global_load_lds((const unsigned*)((const char*)(gbase) + (voff)[_i]), (LAS unsigned*)(lds + (bufoff) + ldsw + _i * 8192), 16, 0, 0); } while (0)
; #define PG8_LDA(dst, b, h) do { _Pragma("unroll") for (int m = 0; m < 4; ++m) _Pragma("unroll") for (int k = 0; k < 2; ++k) dst[m][k] = *(const LAS bf16x8*)(lds + PG8_SA(b, h) + aoff + m * 2048 + k * 1024); } while (0)
; #define PG8_LDB(dst, b, h) do { _Pragma("unroll") for (int n = 0; n < 2; ++n) _Pragma("unroll") for (int k = 0; k < 2; ++k) dst[n][k] = *(const LAS bf16x8*)(lds + PG8_SB(b, h) + boff + n * 2048 + k * 1024); } while (0)
; #define PG8_MMA(ai, bj, At, Bt) do { __builtin_amdgcn_s_setprio(1); _Pragma("unroll") for (int m = 0; m < 4; ++m) _Pragma("unroll") for (int n = 0; n < 2; ++n) _Pragma("unroll") for (int k = 0; k < 2; ++k) \
;         acc[ai][bj][m][n] = __builtin_amdgcn_mfma_f32_16x16x32_bf16(Bt[n][k], At[m][k], acc[ai][bj][m][n], 0, 0, 0); __builtin_amdgcn_s_setprio(0); } while (0)
; #define PG8_WAIT_V(n) asm volatile("s_waitcnt vmcnt(" #n ")" ::: "memory")
; #define PG8_WAIT_L(n) asm volatile("s_waitcnt lgkmcnt(" #n ")" ::: "memory")
; #define PG8_BAR __builtin_amdgcn_s_barrier()
; #define PG8_SCHED __builtin_amdgcn_sched_barrier(0)
; template <class Epi, class Sched, int LDA, int LDB, bool ALIGN_EPI = true>
; __device__ __forceinline__ void gemm_phase(LAS unsigned char* lds, const Gemm g, const Sched& S, const Epi& E, int wave) {
;     ...
;             PG8_LDB(B0, 0, 0); PG8_LDB(B1, 0, 1); PG8_SCHED; PG8_LDA(At, 0, 0); PG8_STAGE(PG8_SA(1, 1), a1 + hstepA, voffA);
;             PG8_WAIT_V(8); PG8_WAIT_L(0); PG8_BAR; PG8_MMA(0, 0, At, B0); PG8_MMA(0, 1, At, B1); PG8_BAR; PG8_SCHED;
;             PG8_LDA(At, 0, 1); PG8_STAGE(PG8_SB(0, 0), b2, voffB); PG8_STAGE(PG8_SB(0, 1), b2 + hstepB, voffB); PG8_STAGE(PG8_SA(0, 0), a2, voffA);
;             PG8_WAIT_V(8); PG8_WAIT_L(0); PG8_BAR; PG8_MMA(1, 0, At, B0); PG8_MMA(1, 1, At, B1); PG8_BAR; PG8_SCHED;
.LBB0_4715:
	s_add_i32 s49, s24, 2
	s_add_u32 s25, s18, 0xfff80080
	s_addc_u32 s28, s19, -1
	s_add_i32 s50, 0, 0x10000
	s_cmp_eq_u32 s17, s24
	s_cselect_b32 s29, s1, s28
	s_cselect_b32 s28, s7, s25
	s_cselect_b32 s25, s3, s45
	s_cselect_b32 s24, s15, s44
	s_add_i32 s52, 0, 0x14000
	v_lshl_add_u64 v[216:217], s[18:19], 0, v[140:141]
	s_add_i32 m0, s27, 0xc000
	s_nop 0
	global_load_lds_dwordx4 v[216:217], off
	v_lshl_add_u64 v[216:217], s[18:19], 0, v[142:143]
	s_add_i32 m0, s27, 0xe000
	s_nop 0
	global_load_lds_dwordx4 v[216:217], off
	v_add_u32_e32 v0, s50, v153
	ds_read_b128 v[144:147], v0
	ds_read_b128 v[148:151], v0 offset:1024
	ds_read_b128 v[156:159], v0 offset:2048
	ds_read_b128 v[160:163], v0 offset:3072
	v_add_u32_e32 v0, s52, v153
	ds_read_b128 v[164:167], v0
	ds_read_b128 v[168:171], v0 offset:1024
	ds_read_b128 v[172:175], v0 offset:2048
	ds_read_b128 v[180:183], v0 offset:3072
	ds_read_b128 v[184:187], v155
	ds_read_b128 v[188:191], v155 offset:1024
	ds_read_b128 v[192:195], v155 offset:2048
	ds_read_b128 v[196:199], v155 offset:3072
	ds_read_b128 v[200:203], v155 offset:4096
	ds_read_b128 v[204:207], v155 offset:5120
	ds_read_b128 v[208:211], v155 offset:6144
	ds_read_b128 v[212:215], v155 offset:7168
	s_waitcnt vmcnt(8)
	s_waitcnt lgkmcnt(0)
	s_setprio 1
	s_barrier
	v_mfma_f32_16x16x32_bf16 v[126:129], v[144:147], v[184:187], v[126:129]
	v_mfma_f32_16x16x32_bf16 v[122:125], v[156:159], v[184:187], v[122:125]
	v_mfma_f32_16x16x32_bf16 v[110:113], v[144:147], v[192:195], v[110:113]
	v_mfma_f32_16x16x32_bf16 v[106:109], v[156:159], v[192:195], v[106:109]
	v_mfma_f32_16x16x32_bf16 v[94:97], v[144:147], v[200:203], v[94:97]
	v_mfma_f32_16x16x32_bf16 v[90:93], v[156:159], v[200:203], v[90:93]
	v_mfma_f32_16x16x32_bf16 v[78:81], v[144:147], v[208:211], v[78:81]
	v_mfma_f32_16x16x32_bf16 v[74:77], v[156:159], v[208:211], v[74:77]
	v_mfma_f32_16x16x32_bf16 v[126:129], v[148:151], v[188:191], v[126:129]
	v_mfma_f32_16x16x32_bf16 v[122:125], v[160:163], v[188:191], v[122:125]
	v_mfma_f32_16x16x32_bf16 v[110:113], v[148:151], v[196:199], v[110:113]
	v_mfma_f32_16x16x32_bf16 v[106:109], v[160:163], v[196:199], v[106:109]
	v_mfma_f32_16x16x32_bf16 v[94:97], v[148:151], v[204:207], v[94:97]
	v_mfma_f32_16x16x32_bf16 v[90:93], v[160:163], v[204:207], v[90:93]
	v_mfma_f32_16x16x32_bf16 v[78:81], v[148:151], v[212:215], v[78:81]
	v_mfma_f32_16x16x32_bf16 v[74:77], v[160:163], v[212:215], v[74:77]
	v_mfma_f32_16x16x32_bf16 v[118:121], v[164:167], v[184:187], v[118:121]
	v_mfma_f32_16x16x32_bf16 v[114:117], v[172:175], v[184:187], v[114:117]
	v_mfma_f32_16x16x32_bf16 v[102:105], v[164:167], v[192:195], v[102:105]
	v_mfma_f32_16x16x32_bf16 v[98:101], v[172:175], v[192:195], v[98:101]
	v_mfma_f32_16x16x32_bf16 v[86:89], v[164:167], v[200:203], v[86:89]
	v_mfma_f32_16x16x32_bf16 v[82:85], v[172:175], v[200:203], v[82:85]
	v_mfma_f32_16x16x32_bf16 v[70:73], v[164:167], v[208:211], v[70:73]
	v_mfma_f32_16x16x32_bf16 v[66:69], v[172:175], v[208:211], v[66:69]
	v_mfma_f32_16x16x32_bf16 v[118:121], v[168:171], v[188:191], v[118:121]
	v_mfma_f32_16x16x32_bf16 v[114:117], v[180:183], v[188:191], v[114:117]
	v_mfma_f32_16x16x32_bf16 v[102:105], v[168:171], v[196:199], v[102:105]
	v_mfma_f32_16x16x32_bf16 v[98:101], v[180:183], v[196:199], v[98:101]
	v_mfma_f32_16x16x32_bf16 v[86:89], v[168:171], v[204:207], v[86:89]
	v_mfma_f32_16x16x32_bf16 v[82:85], v[180:183], v[204:207], v[82:85]
	v_mfma_f32_16x16x32_bf16 v[70:73], v[168:171], v[212:215], v[70:73]
	v_mfma_f32_16x16x32_bf16 v[66:69], v[180:183], v[212:215], v[66:69]
	s_barrier
	s_setprio 0
	s_add_i32 s50, s50, s53
	v_lshl_add_u64 v[216:217], s[24:25], 0, v[132:133]
	s_mov_b32 m0, s50
	s_nop 0
	global_load_lds_dwordx4 v[216:217], off
	s_add_i32 m0, s50, 0x2000
	s_add_u32 s50, s24, 0x80000
	v_lshl_add_u64 v[218:219], s[24:25], 0, v[136:137]
	s_addc_u32 s51, s25, 0
	s_add_i32 s52, s52, s53
	global_load_lds_dwordx4 v[218:219], off
	v_lshl_add_u64 v[220:221], s[50:51], 0, v[132:133]
	s_mov_b32 m0, s52
	v_lshl_add_u64 v[222:223], s[28:29], 0, v[134:135]
	global_load_lds_dwordx4 v[220:221], off
	v_lshl_add_u64 v[220:221], s[50:51], 0, v[136:137]
	s_add_i32 m0, s52, 0x2000
	s_nop 0
	global_load_lds_dwordx4 v[220:221], off
	v_lshl_add_u64 v[220:221], s[28:29], 0, v[130:131]
	s_mov_b32 m0, s27
	s_nop 0
	global_load_lds_dwordx4 v[220:221], off
	s_mov_b32 m0, s34
	s_nop 0
	global_load_lds_dwordx4 v[222:223], off
	ds_read_b128 v[184:187], v155 offset:16384
	ds_read_b128 v[188:191], v155 offset:17408
	ds_read_b128 v[192:195], v155 offset:18432
	ds_read_b128 v[196:199], v155 offset:19456
	ds_read_b128 v[200:203], v155 offset:20480
	ds_read_b128 v[204:207], v155 offset:21504
	ds_read_b128 v[208:211], v155 offset:22528
	ds_read_b128 v[212:215], v155 offset:23552
	s_waitcnt vmcnt(8)
	s_waitcnt lgkmcnt(0)
	s_setprio 1
	s_barrier
; #define PG8_STAGE(bufoff, gbase, voff) do { _Pragma("unroll") for (int _i = 0; _i < 2; ++_i) \
;         __builtin_amdgcn_global_load_lds((const unsigned*)((const char*)(gbase) + (voff)[_i]), (LAS unsigned*)(lds + (bufoff) + ldsw + _i * 8192), 16, 0, 0); } while (0)
; #define PG8_LDA(dst, b, h) do { _Pragma("unroll") for (int m = 0; m < 4; ++m) _Pragma("unroll") for (int k = 0; k < 2; ++k) dst[m][k] = *(const LAS bf16x8*)(lds + PG8_SA(b, h) + aoff + m * 2048 + k * 1024); } while (0)
; #define PG8_LDB(dst, b, h) do { _Pragma("unroll") for (int n = 0; n < 2; ++n) _Pragma("unroll") for (int k = 0; k < 2; ++k) dst[n][k] = *(const LAS bf16x8*)(lds + PG8_SB(b, h) + boff + n * 2048 + k * 1024); } while (0)
; #define PG8_MMA(ai, bj, At, Bt) do { __builtin_amdgcn_s_setprio(1); _Pragma("unroll") for (int m = 0; m < 4; ++m) _Pragma("unroll") for (int n = 0; n < 2; ++n) _Pragma("unroll") for (int k = 0; k < 2; ++k) \
;         acc[ai][bj][m][n] = __builtin_amdgcn_mfma_f32_16x16x32_bf16(Bt[n][k], At[m][k], acc[ai][bj][m][n], 0, 0, 0); __builtin_amdgcn_s_setprio(0); } while (0)
; #define PG8_WAIT_V(n) asm volatile("s_waitcnt vmcnt(" #n ")" ::: "memory")
; #define PG8_WAIT_L(n) asm volatile("s_waitcnt lgkmcnt(" #n ")" ::: "memory")
; #define PG8_BAR __builtin_amdgcn_s_barrier()
; #define PG8_SCHED __builtin_amdgcn_sched_barrier(0)
; template <class Epi, class Sched, int LDA, int LDB, bool ALIGN_EPI = true>
; __device__ __forceinline__ void gemm_phase(LAS unsigned char* lds, const Gemm g, const Sched& S, const Epi& E, int wave) {
;     ...
;             PG8_WAIT_V(8); PG8_WAIT_L(0); PG8_BAR; PG8_MMA(1, 0, At, B0); PG8_MMA(1, 1, At, B1); PG8_BAR; PG8_SCHED;
;             PG8_LDB(B0, 1, 0); PG8_LDB(B1, 1, 1); PG8_SCHED; PG8_LDA(At, 1, 0); PG8_STAGE(PG8_SA(0, 1), a2 + hstepA, voffA);
;             PG8_WAIT_V(8); PG8_WAIT_L(0); PG8_BAR; PG8_MMA(0, 0, At, B0); PG8_MMA(0, 1, At, B1); PG8_BAR; PG8_SCHED;
	v_mfma_f32_16x16x32_bf16 v[62:65], v[144:147], v[184:187], v[62:65]
	v_mfma_f32_16x16x32_bf16 v[58:61], v[156:159], v[184:187], v[58:61]
	v_mfma_f32_16x16x32_bf16 v[46:49], v[144:147], v[192:195], v[46:49]
	v_mfma_f32_16x16x32_bf16 v[42:45], v[156:159], v[192:195], v[42:45]
	v_mfma_f32_16x16x32_bf16 v[30:33], v[144:147], v[200:203], v[30:33]
	v_mfma_f32_16x16x32_bf16 v[26:29], v[156:159], v[200:203], v[26:29]
	v_mfma_f32_16x16x32_bf16 v[14:17], v[144:147], v[208:211], v[14:17]
	v_mfma_f32_16x16x32_bf16 v[10:13], v[156:159], v[208:211], v[10:13]
	v_mfma_f32_16x16x32_bf16 v[62:65], v[148:151], v[188:191], v[62:65]
	v_mfma_f32_16x16x32_bf16 v[58:61], v[160:163], v[188:191], v[58:61]
	v_mfma_f32_16x16x32_bf16 v[46:49], v[148:151], v[196:199], v[46:49]
	v_mfma_f32_16x16x32_bf16 v[42:45], v[160:163], v[196:199], v[42:45]
	v_mfma_f32_16x16x32_bf16 v[30:33], v[148:151], v[204:207], v[30:33]
	v_mfma_f32_16x16x32_bf16 v[26:29], v[160:163], v[204:207], v[26:29]
	v_mfma_f32_16x16x32_bf16 v[14:17], v[148:151], v[212:215], v[14:17]
	v_mfma_f32_16x16x32_bf16 v[10:13], v[160:163], v[212:215], v[10:13]
	v_mfma_f32_16x16x32_bf16 v[54:57], v[164:167], v[184:187], v[54:57]
	v_mfma_f32_16x16x32_bf16 v[50:53], v[172:175], v[184:187], v[50:53]
	v_mfma_f32_16x16x32_bf16 v[38:41], v[164:167], v[192:195], v[38:41]
	v_mfma_f32_16x16x32_bf16 v[34:37], v[172:175], v[192:195], v[34:37]
	v_mfma_f32_16x16x32_bf16 v[22:25], v[164:167], v[200:203], v[22:25]
	v_mfma_f32_16x16x32_bf16 v[18:21], v[172:175], v[200:203], v[18:21]
	v_mfma_f32_16x16x32_bf16 v[6:9], v[164:167], v[208:211], v[6:9]
	v_mfma_f32_16x16x32_bf16 v[2:5], v[172:175], v[208:211], v[2:5]
	v_mfma_f32_16x16x32_bf16 v[54:57], v[168:171], v[188:191], v[54:57]
	v_mfma_f32_16x16x32_bf16 v[50:53], v[180:183], v[188:191], v[50:53]
	v_mfma_f32_16x16x32_bf16 v[38:41], v[168:171], v[196:199], v[38:41]
	v_mfma_f32_16x16x32_bf16 v[34:37], v[180:183], v[196:199], v[34:37]
	v_mfma_f32_16x16x32_bf16 v[22:25], v[168:171], v[204:207], v[22:25]
	v_mfma_f32_16x16x32_bf16 v[18:21], v[180:183], v[204:207], v[18:21]
	v_mfma_f32_16x16x32_bf16 v[6:9], v[168:171], v[212:215], v[6:9]
	v_mfma_f32_16x16x32_bf16 v[2:5], v[180:183], v[212:215], v[2:5]
	s_barrier
	s_setprio 0
	s_add_i32 s50, 0, 0x18000
	s_add_i32 s51, 0, 0x1c000
	s_add_u32 s28, s28, 0x80000
	s_addc_u32 s29, s29, 0
	s_mov_b32 m0, s35
	v_lshl_add_u64 v[224:225], s[28:29], 0, v[130:131]
	global_load_lds_dwordx4 v[224:225], off
	v_lshl_add_u64 v[224:225], s[28:29], 0, v[134:135]
	s_mov_b32 m0, s36
	s_nop 0
	global_load_lds_dwordx4 v[224:225], off
	v_add_u32_e32 v0, s50, v153
	ds_read_b128 v[144:147], v0
	ds_read_b128 v[148:151], v0 offset:1024
	ds_read_b128 v[156:159], v0 offset:2048
	ds_read_b128 v[160:163], v0 offset:3072
	v_add_u32_e32 v0, s51, v153
	ds_read_b128 v[164:167], v0
	ds_read_b128 v[168:171], v0 offset:1024
	ds_read_b128 v[172:175], v0 offset:2048
	ds_read_b128 v[180:183], v0 offset:3072
	ds_read_b128 v[184:187], v155 offset:32768
	ds_read_b128 v[188:191], v155 offset:33792
	ds_read_b128 v[192:195], v155 offset:34816
	ds_read_b128 v[196:199], v155 offset:35840
	ds_read_b128 v[200:203], v155 offset:36864
	ds_read_b128 v[204:207], v155 offset:37888
	ds_read_b128 v[208:211], v155 offset:38912
	ds_read_b128 v[212:215], v155 offset:39936
	s_waitcnt vmcnt(8)
	s_waitcnt lgkmcnt(0)
	s_setprio 1
	s_barrier
	v_mfma_f32_16x16x32_bf16 v[126:129], v[144:147], v[184:187], v[126:129]
	v_mfma_f32_16x16x32_bf16 v[122:125], v[156:159], v[184:187], v[122:125]
	v_mfma_f32_16x16x32_bf16 v[110:113], v[144:147], v[192:195], v[110:113]
	v_mfma_f32_16x16x32_bf16 v[106:109], v[156:159], v[192:195], v[106:109]
	v_mfma_f32_16x16x32_bf16 v[94:97], v[144:147], v[200:203], v[94:97]
	v_mfma_f32_16x16x32_bf16 v[90:93], v[156:159], v[200:203], v[90:93]
	v_mfma_f32_16x16x32_bf16 v[78:81], v[144:147], v[208:211], v[78:81]
	v_mfma_f32_16x16x32_bf16 v[74:77], v[156:159], v[208:211], v[74:77]
	v_mfma_f32_16x16x32_bf16 v[126:129], v[148:151], v[188:191], v[126:129]
	v_mfma_f32_16x16x32_bf16 v[122:125], v[160:163], v[188:191], v[122:125]
	v_mfma_f32_16x16x32_bf16 v[110:113], v[148:151], v[196:199], v[110:113]
	v_mfma_f32_16x16x32_bf16 v[106:109], v[160:163], v[196:199], v[106:109]
	v_mfma_f32_16x16x32_bf16 v[94:97], v[148:151], v[204:207], v[94:97]
	v_mfma_f32_16x16x32_bf16 v[90:93], v[160:163], v[204:207], v[90:93]
	v_mfma_f32_16x16x32_bf16 v[78:81], v[148:151], v[212:215], v[78:81]
	v_mfma_f32_16x16x32_bf16 v[74:77], v[160:163], v[212:215], v[74:77]
	v_mfma_f32_16x16x32_bf16 v[118:121], v[164:167], v[184:187], v[118:121]
	v_mfma_f32_16x16x32_bf16 v[114:117], v[172:175], v[184:187], v[114:117]
	v_mfma_f32_16x16x32_bf16 v[102:105], v[164:167], v[192:195], v[102:105]
	v_mfma_f32_16x16x32_bf16 v[98:101], v[172:175], v[192:195], v[98:101]
	v_mfma_f32_16x16x32_bf16 v[86:89], v[164:167], v[200:203], v[86:89]
	v_mfma_f32_16x16x32_bf16 v[82:85], v[172:175], v[200:203], v[82:85]
	v_mfma_f32_16x16x32_bf16 v[70:73], v[164:167], v[208:211], v[70:73]
	v_mfma_f32_16x16x32_bf16 v[66:69], v[172:175], v[208:211], v[66:69]
	v_mfma_f32_16x16x32_bf16 v[118:121], v[168:171], v[188:191], v[118:121]
	v_mfma_f32_16x16x32_bf16 v[114:117], v[180:183], v[188:191], v[114:117]
	v_mfma_f32_16x16x32_bf16 v[102:105], v[168:171], v[196:199], v[102:105]
	v_mfma_f32_16x16x32_bf16 v[98:101], v[180:183], v[196:199], v[98:101]
	v_mfma_f32_16x16x32_bf16 v[86:89], v[168:171], v[204:207], v[86:89]
	v_mfma_f32_16x16x32_bf16 v[82:85], v[180:183], v[204:207], v[82:85]
	v_mfma_f32_16x16x32_bf16 v[70:73], v[168:171], v[212:215], v[70:73]
	v_mfma_f32_16x16x32_bf16 v[66:69], v[180:183], v[212:215], v[66:69]
	s_barrier
; #define PG8_STAGE(bufoff, gbase, voff) do { _Pragma("unroll") for (int _i = 0; _i < 2; ++_i) \
;         __builtin_amdgcn_global_load_lds((const unsigned*)((const char*)(gbase) + (voff)[_i]), (LAS unsigned*)(lds + (bufoff) + ldsw + _i * 8192), 16, 0, 0); } while (0)
; #define PG8_LDA(dst, b, h) do { _Pragma("unroll") for (int m = 0; m < 4; ++m) _Pragma("unroll") for (int k = 0; k < 2; ++k) dst[m][k] = *(const LAS bf16x8*)(lds + PG8_SA(b, h) + aoff + m * 2048 + k * 1024); } while (0)
; #define PG8_MMA(ai, bj, At, Bt) do { __builtin_amdgcn_s_setprio(1); _Pragma("unroll") for (int m = 0; m < 4; ++m) _Pragma("unroll") for (int n = 0; n < 2; ++n) _Pragma("unroll") for (int k = 0; k < 2; ++k) \
;         acc[ai][bj][m][n] = __builtin_amdgcn_mfma_f32_16x16x32_bf16(Bt[n][k], At[m][k], acc[ai][bj][m][n], 0, 0, 0); __builtin_amdgcn_s_setprio(0); } while (0)
; #define PG8_WAIT_V(n) asm volatile("s_waitcnt vmcnt(" #n ")" ::: "memory")
; #define PG8_WAIT_L(n) asm volatile("s_waitcnt lgkmcnt(" #n ")" ::: "memory")
; #define PG8_BAR __builtin_amdgcn_s_barrier()
; #define PG8_SCHED __builtin_amdgcn_sched_barrier(0)
; template <class Epi, class Sched, int LDA, int LDB, bool ALIGN_EPI = true>
; __device__ __forceinline__ void gemm_phase(LAS unsigned char* lds, const Gemm g, const Sched& S, const Epi& E, int wave) {
;     ...
;             PG8_LDA(At, 1, 1); PG8_STAGE(PG8_SB(1, 0), b3, voffB); PG8_STAGE(PG8_SB(1, 1), b3 + hstepB, voffB); PG8_STAGE(PG8_SA(1, 0), a3, voffA);
;             PG8_WAIT_V(8); PG8_WAIT_L(0); PG8_BAR; PG8_MMA(1, 0, At, B0); PG8_MMA(1, 1, At, B1); PG8_BAR; PG8_SCHED;
;         }
;         if constexpr (ALIGN_EPI) { if (wr == 0) PG8_BAR; }
	s_setprio 0
	s_add_i32 s28, s50, s53
	v_lshl_add_u64 v[216:217], v[216:217], 0, s[54:55]
	s_mov_b32 m0, s28
	s_nop 0
	global_load_lds_dwordx4 v[216:217], off
	s_add_i32 m0, s28, 0x2000
	s_add_u32 s24, s24, 0x80080
	v_lshl_add_u64 v[216:217], v[218:219], 0, s[54:55]
	s_addc_u32 s25, s25, 0
	s_add_i32 s28, s51, s53
	global_load_lds_dwordx4 v[216:217], off
	v_lshl_add_u64 v[216:217], s[24:25], 0, v[132:133]
	s_mov_b32 m0, s28
	s_nop 0
	global_load_lds_dwordx4 v[216:217], off
	v_lshl_add_u64 v[216:217], s[24:25], 0, v[136:137]
	s_add_i32 m0, s28, 0x2000
	s_nop 0
	global_load_lds_dwordx4 v[216:217], off
	v_lshl_add_u64 v[216:217], v[220:221], 0, s[54:55]
	s_mov_b32 m0, s37
	s_nop 0
	global_load_lds_dwordx4 v[216:217], off
	v_lshl_add_u64 v[216:217], v[222:223], 0, s[54:55]
	s_mov_b32 m0, s38
	s_nop 0
	global_load_lds_dwordx4 v[216:217], off
	ds_read_b128 v[184:187], v155 offset:49152
	ds_read_b128 v[188:191], v155 offset:50176
	ds_read_b128 v[192:195], v155 offset:51200
	ds_read_b128 v[196:199], v155 offset:52224
	ds_read_b128 v[200:203], v155 offset:53248
	ds_read_b128 v[204:207], v155 offset:54272
	ds_read_b128 v[208:211], v155 offset:55296
	ds_read_b128 v[212:215], v155 offset:56320
	s_waitcnt vmcnt(8)
	s_waitcnt lgkmcnt(0)
	s_setprio 1
	s_barrier
	v_mfma_f32_16x16x32_bf16 v[62:65], v[144:147], v[184:187], v[62:65]
	v_mfma_f32_16x16x32_bf16 v[58:61], v[156:159], v[184:187], v[58:61]
	v_mfma_f32_16x16x32_bf16 v[46:49], v[144:147], v[192:195], v[46:49]
	v_mfma_f32_16x16x32_bf16 v[42:45], v[156:159], v[192:195], v[42:45]
	v_mfma_f32_16x16x32_bf16 v[30:33], v[144:147], v[200:203], v[30:33]
	v_mfma_f32_16x16x32_bf16 v[26:29], v[156:159], v[200:203], v[26:29]
	v_mfma_f32_16x16x32_bf16 v[14:17], v[144:147], v[208:211], v[14:17]
	v_mfma_f32_16x16x32_bf16 v[10:13], v[156:159], v[208:211], v[10:13]
	v_mfma_f32_16x16x32_bf16 v[62:65], v[148:151], v[188:191], v[62:65]
	v_mfma_f32_16x16x32_bf16 v[58:61], v[160:163], v[188:191], v[58:61]
	v_mfma_f32_16x16x32_bf16 v[46:49], v[148:151], v[196:199], v[46:49]
	v_mfma_f32_16x16x32_bf16 v[42:45], v[160:163], v[196:199], v[42:45]
	v_mfma_f32_16x16x32_bf16 v[30:33], v[148:151], v[204:207], v[30:33]
	v_mfma_f32_16x16x32_bf16 v[26:29], v[160:163], v[204:207], v[26:29]
	v_mfma_f32_16x16x32_bf16 v[14:17], v[148:151], v[212:215], v[14:17]
	v_mfma_f32_16x16x32_bf16 v[10:13], v[160:163], v[212:215], v[10:13]
	v_mfma_f32_16x16x32_bf16 v[54:57], v[164:167], v[184:187], v[54:57]
	v_mfma_f32_16x16x32_bf16 v[50:53], v[172:175], v[184:187], v[50:53]
	v_mfma_f32_16x16x32_bf16 v[38:41], v[164:167], v[192:195], v[38:41]
	v_mfma_f32_16x16x32_bf16 v[34:37], v[172:175], v[192:195], v[34:37]
	v_mfma_f32_16x16x32_bf16 v[22:25], v[164:167], v[200:203], v[22:25]
	v_mfma_f32_16x16x32_bf16 v[18:21], v[172:175], v[200:203], v[18:21]
	v_mfma_f32_16x16x32_bf16 v[6:9], v[164:167], v[208:211], v[6:9]
	v_mfma_f32_16x16x32_bf16 v[2:5], v[172:175], v[208:211], v[2:5]
	v_mfma_f32_16x16x32_bf16 v[54:57], v[168:171], v[188:191], v[54:57]
	v_mfma_f32_16x16x32_bf16 v[50:53], v[180:183], v[188:191], v[50:53]
	v_mfma_f32_16x16x32_bf16 v[38:41], v[168:171], v[196:199], v[38:41]
	v_mfma_f32_16x16x32_bf16 v[34:37], v[180:183], v[196:199], v[34:37]
	v_mfma_f32_16x16x32_bf16 v[22:25], v[168:171], v[204:207], v[22:25]
	v_mfma_f32_16x16x32_bf16 v[18:21], v[180:183], v[204:207], v[18:21]
	v_mfma_f32_16x16x32_bf16 v[6:9], v[168:171], v[212:215], v[6:9]
	v_mfma_f32_16x16x32_bf16 v[2:5], v[180:183], v[212:215], v[2:5]
	s_barrier
	s_setprio 0
	s_add_u32 s18, s18, 0x100
	s_addc_u32 s19, s19, 0
	s_add_u32 s44, s44, 0x100
	s_addc_u32 s45, s45, 0
	s_cmp_ge_i32 s49, s43
	s_mov_b32 s24, s49
	s_cbranch_scc0 .LBB0_4715
	v_readlane_b32 s18, v252, 14
	v_readlane_b32 s19, v252, 15
	s_and_b64 vcc, exec, s[18:19]
	s_cbranch_vccz .LBB0_4718
	s_barrier

; #define PG8_STAGE(bufoff, gbase, voff) do { _Pragma("unroll") for (int _i = 0; _i < 2; ++_i) \
;         __builtin_amdgcn_global_load_lds((const unsigned*)((const char*)(gbase) + (voff)[_i]), (LAS unsigned*)(lds + (bufoff) + ldsw + _i * 8192), 16, 0, 0); } while (0)
; #define PG8_LDA(dst, b, h) do { _Pragma("unroll") for (int m = 0; m < 4; ++m) _Pragma("unroll") for (int k = 0; k < 2; ++k) dst[m][k] = *(const LAS bf16x8*)(lds + PG8_SA(b, h) + aoff + m * 2048 + k * 1024); } while (0)
; #define PG8_LDB(dst, b, h) do { _Pragma("unroll") for (int n = 0; n < 2; ++n) _Pragma("unroll") for (int k = 0; k < 2; ++k) dst[n][k] = *(const LAS bf16x8*)(lds + PG8_SB(b, h) + boff + n * 2048 + k * 1024); } while (0)
; #define PG8_MMA(ai, bj, At, Bt) do { __builtin_amdgcn_s_setprio(1); _Pragma("unroll") for (int m = 0; m < 4; ++m) _Pragma("unroll") for (int n = 0; n < 2; ++n) _Pragma("unroll") for (int k = 0; k < 2; ++k) \
;         acc[ai][bj][m][n] = __builtin_amdgcn_mfma_f32_16x16x32_bf16(Bt[n][k], At[m][k], acc[ai][bj][m][n], 0, 0, 0); __builtin_amdgcn_s_setprio(0); } while (0)
; #define PG8_WAIT_V(n) asm volatile("s_waitcnt vmcnt(" #n ")" ::: "memory")
; #define PG8_WAIT_L(n) asm volatile("s_waitcnt lgkmcnt(" #n ")" ::: "memory")
; #define PG8_BAR __builtin_amdgcn_s_barrier()
; #define PG8_SCHED __builtin_amdgcn_sched_barrier(0)
; template <class Epi, class Sched, int LDA, int LDB, bool ALIGN_EPI = true>
; __device__ __forceinline__ void gemm_phase(LAS unsigned char* lds, const Gemm g, const Sched& S, const Epi& E, int wave) {
;     ...
;             PG8_LDB(B0, 0, 0); PG8_LDB(B1, 0, 1); PG8_SCHED; PG8_LDA(At, 0, 0); PG8_STAGE(PG8_SA(1, 1), a1 + hstepA, voffA);
;             PG8_WAIT_V(8); PG8_WAIT_L(0); PG8_BAR; PG8_MMA(0, 0, At, B0); PG8_MMA(0, 1, At, B1); PG8_BAR; PG8_SCHED;
;             PG8_LDA(At, 0, 1); PG8_STAGE(PG8_SB(0, 0), b2, voffB); PG8_STAGE(PG8_SB(0, 1), b2 + hstepB, voffB); PG8_STAGE(PG8_SA(0, 0), a2, voffA);
;             PG8_WAIT_V(8); PG8_WAIT_L(0); PG8_BAR; PG8_MMA(1, 0, At, B0); PG8_MMA(1, 1, At, B1); PG8_BAR; PG8_SCHED;
.LBB0_4901:
	s_add_i32 s65, s36, 2
	s_add_u32 s37, s34, 0xfff80080
	s_addc_u32 s38, s35, -1
	s_add_i32 s66, 0, 0x10000
	s_cmp_eq_u32 s29, s36
	s_cselect_b32 s39, s9, s38
	s_cselect_b32 s38, s13, s37
	s_cselect_b32 s37, s11, s64
	s_cselect_b32 s36, s25, s59
	s_add_i32 s72, 0, 0x14000
	v_lshl_add_u64 v[208:209], s[34:35], 0, v[152:153]
	s_add_i32 m0, s27, 0xc000
	s_nop 0
	global_load_lds_dwordx4 v[208:209], off
	v_lshl_add_u64 v[208:209], s[34:35], 0, v[154:155]
	s_add_i32 m0, s27, 0xe000
	s_nop 0
	global_load_lds_dwordx4 v[208:209], off
	v_add_u32_e32 v70, s66, v213
	v_add_u32_e32 v168, s72, v213
	ds_read_b128 v[50:53], v70
	ds_read_b128 v[54:57], v70 offset:1024
	ds_read_b128 v[66:69], v70 offset:2048
	ds_read_b128 v[70:73], v70 offset:3072
	ds_read_b128 v[156:159], v168
	ds_read_b128 v[160:163], v168 offset:1024
	ds_read_b128 v[164:167], v168 offset:2048
	ds_read_b128 v[168:171], v168 offset:3072
	ds_read_b128 v[172:175], v215
	ds_read_b128 v[180:183], v215 offset:1024
	ds_read_b128 v[184:187], v215 offset:2048
	ds_read_b128 v[188:191], v215 offset:3072
	ds_read_b128 v[192:195], v215 offset:4096
	ds_read_b128 v[196:199], v215 offset:5120
	ds_read_b128 v[200:203], v215 offset:6144
	ds_read_b128 v[204:207], v215 offset:7168
	s_waitcnt vmcnt(8)
	s_waitcnt lgkmcnt(0)
	s_setprio 1
	s_barrier
	v_mfma_f32_16x16x32_bf16 v[142:145], v[50:53], v[172:175], v[142:145]
	v_mfma_f32_16x16x32_bf16 v[138:141], v[66:69], v[172:175], v[138:141]
	v_mfma_f32_16x16x32_bf16 v[126:129], v[50:53], v[184:187], v[126:129]
	v_mfma_f32_16x16x32_bf16 v[122:125], v[66:69], v[184:187], v[122:125]
	v_mfma_f32_16x16x32_bf16 v[110:113], v[50:53], v[192:195], v[110:113]
	v_mfma_f32_16x16x32_bf16 v[106:109], v[66:69], v[192:195], v[106:109]
	v_mfma_f32_16x16x32_bf16 v[94:97], v[50:53], v[200:203], v[94:97]
	v_mfma_f32_16x16x32_bf16 v[90:93], v[66:69], v[200:203], v[90:93]
	v_mfma_f32_16x16x32_bf16 v[142:145], v[54:57], v[180:183], v[142:145]
	v_mfma_f32_16x16x32_bf16 v[138:141], v[70:73], v[180:183], v[138:141]
	v_mfma_f32_16x16x32_bf16 v[126:129], v[54:57], v[188:191], v[126:129]
	v_mfma_f32_16x16x32_bf16 v[122:125], v[70:73], v[188:191], v[122:125]
	v_mfma_f32_16x16x32_bf16 v[110:113], v[54:57], v[196:199], v[110:113]
	v_mfma_f32_16x16x32_bf16 v[106:109], v[70:73], v[196:199], v[106:109]
	v_mfma_f32_16x16x32_bf16 v[94:97], v[54:57], v[204:207], v[94:97]
	v_mfma_f32_16x16x32_bf16 v[90:93], v[70:73], v[204:207], v[90:93]
	v_mfma_f32_16x16x32_bf16 v[134:137], v[156:159], v[172:175], v[134:137]
	v_mfma_f32_16x16x32_bf16 v[130:133], v[164:167], v[172:175], v[130:133]
	v_mfma_f32_16x16x32_bf16 v[118:121], v[156:159], v[184:187], v[118:121]
	v_mfma_f32_16x16x32_bf16 v[114:117], v[164:167], v[184:187], v[114:117]
	v_mfma_f32_16x16x32_bf16 v[102:105], v[156:159], v[192:195], v[102:105]
	v_mfma_f32_16x16x32_bf16 v[98:101], v[164:167], v[192:195], v[98:101]
	v_mfma_f32_16x16x32_bf16 v[86:89], v[156:159], v[200:203], v[86:89]
	v_mfma_f32_16x16x32_bf16 v[82:85], v[164:167], v[200:203], v[82:85]
	v_mfma_f32_16x16x32_bf16 v[134:137], v[160:163], v[180:183], v[134:137]
	v_mfma_f32_16x16x32_bf16 v[130:133], v[168:171], v[180:183], v[130:133]
	v_mfma_f32_16x16x32_bf16 v[118:121], v[160:163], v[188:191], v[118:121]
	v_mfma_f32_16x16x32_bf16 v[114:117], v[168:171], v[188:191], v[114:117]
	v_mfma_f32_16x16x32_bf16 v[102:105], v[160:163], v[196:199], v[102:105]
	v_mfma_f32_16x16x32_bf16 v[98:101], v[168:171], v[196:199], v[98:101]
	v_mfma_f32_16x16x32_bf16 v[86:89], v[160:163], v[204:207], v[86:89]
	v_mfma_f32_16x16x32_bf16 v[82:85], v[168:171], v[204:207], v[82:85]
	s_barrier
	s_setprio 0
	s_add_i32 s66, s66, s60
	v_lshl_add_u64 v[208:209], s[36:37], 0, v[0:1]
	s_mov_b32 m0, s66
	s_nop 0
	global_load_lds_dwordx4 v[208:209], off
	s_add_i32 m0, s66, 0x2000
	s_add_u32 s66, s36, 0x80000
	v_lshl_add_u64 v[210:211], s[36:37], 0, v[150:151]
	s_addc_u32 s67, s37, 0
	s_add_i32 s72, s72, s60
	global_load_lds_dwordx4 v[210:211], off
	v_lshl_add_u64 v[216:217], s[66:67], 0, v[0:1]
	s_mov_b32 m0, s72
	v_lshl_add_u64 v[218:219], s[38:39], 0, v[148:149]
	global_load_lds_dwordx4 v[216:217], off
	v_lshl_add_u64 v[216:217], s[66:67], 0, v[150:151]
	s_add_i32 m0, s72, 0x2000
	s_nop 0
	global_load_lds_dwordx4 v[216:217], off
	v_lshl_add_u64 v[216:217], s[38:39], 0, v[146:147]
	s_mov_b32 m0, s27
	s_nop 0
	global_load_lds_dwordx4 v[216:217], off
	s_mov_b32 m0, s44
	s_nop 0
	global_load_lds_dwordx4 v[218:219], off
	ds_read_b128 v[172:175], v215 offset:16384
	ds_read_b128 v[180:183], v215 offset:17408
	ds_read_b128 v[184:187], v215 offset:18432
	ds_read_b128 v[188:191], v215 offset:19456
	ds_read_b128 v[192:195], v215 offset:20480
	ds_read_b128 v[196:199], v215 offset:21504
	ds_read_b128 v[200:203], v215 offset:22528
	ds_read_b128 v[204:207], v215 offset:23552
	s_waitcnt vmcnt(8)
	s_waitcnt lgkmcnt(0)
	s_setprio 1
	s_barrier
; #define PG8_STAGE(bufoff, gbase, voff) do { _Pragma("unroll") for (int _i = 0; _i < 2; ++_i) \
;         __builtin_amdgcn_global_load_lds((const unsigned*)((const char*)(gbase) + (voff)[_i]), (LAS unsigned*)(lds + (bufoff) + ldsw + _i * 8192), 16, 0, 0); } while (0)
; #define PG8_LDA(dst, b, h) do { _Pragma("unroll") for (int m = 0; m < 4; ++m) _Pragma("unroll") for (int k = 0; k < 2; ++k) dst[m][k] = *(const LAS bf16x8*)(lds + PG8_SA(b, h) + aoff + m * 2048 + k * 1024); } while (0)
; #define PG8_LDB(dst, b, h) do { _Pragma("unroll") for (int n = 0; n < 2; ++n) _Pragma("unroll") for (int k = 0; k < 2; ++k) dst[n][k] = *(const LAS bf16x8*)(lds + PG8_SB(b, h) + boff + n * 2048 + k * 1024); } while (0)
; #define PG8_MMA(ai, bj, At, Bt) do { __builtin_amdgcn_s_setprio(1); _Pragma("unroll") for (int m = 0; m < 4; ++m) _Pragma("unroll") for (int n = 0; n < 2; ++n) _Pragma("unroll") for (int k = 0; k < 2; ++k) \
;         acc[ai][bj][m][n] = __builtin_amdgcn_mfma_f32_16x16x32_bf16(Bt[n][k], At[m][k], acc[ai][bj][m][n], 0, 0, 0); __builtin_amdgcn_s_setprio(0); } while (0)
; #define PG8_WAIT_V(n) asm volatile("s_waitcnt vmcnt(" #n ")" ::: "memory")
; #define PG8_WAIT_L(n) asm volatile("s_waitcnt lgkmcnt(" #n ")" ::: "memory")
; #define PG8_BAR __builtin_amdgcn_s_barrier()
; #define PG8_SCHED __builtin_amdgcn_sched_barrier(0)
; template <class Epi, class Sched, int LDA, int LDB, bool ALIGN_EPI = true>
; __device__ __forceinline__ void gemm_phase(LAS unsigned char* lds, const Gemm g, const Sched& S, const Epi& E, int wave) {
;     ...
;             PG8_WAIT_V(8); PG8_WAIT_L(0); PG8_BAR; PG8_MMA(1, 0, At, B0); PG8_MMA(1, 1, At, B1); PG8_BAR; PG8_SCHED;
;             PG8_LDB(B0, 1, 0); PG8_LDB(B1, 1, 1); PG8_SCHED; PG8_LDA(At, 1, 0); PG8_STAGE(PG8_SA(0, 1), a2 + hstepA, voffA);
;             PG8_WAIT_V(8); PG8_WAIT_L(0); PG8_BAR; PG8_MMA(0, 0, At, B0); PG8_MMA(0, 1, At, B1); PG8_BAR; PG8_SCHED;
	v_mfma_f32_16x16x32_bf16 v[78:81], v[50:53], v[172:175], v[78:81]
	v_mfma_f32_16x16x32_bf16 v[74:77], v[66:69], v[172:175], v[74:77]
	v_mfma_f32_16x16x32_bf16 v[46:49], v[50:53], v[184:187], v[46:49]
	v_mfma_f32_16x16x32_bf16 v[42:45], v[66:69], v[184:187], v[42:45]
	v_mfma_f32_16x16x32_bf16 v[30:33], v[50:53], v[192:195], v[30:33]
	v_mfma_f32_16x16x32_bf16 v[26:29], v[66:69], v[192:195], v[26:29]
	v_mfma_f32_16x16x32_bf16 v[14:17], v[50:53], v[200:203], v[14:17]
	v_mfma_f32_16x16x32_bf16 v[10:13], v[66:69], v[200:203], v[10:13]
	v_mfma_f32_16x16x32_bf16 v[78:81], v[54:57], v[180:183], v[78:81]
	v_mfma_f32_16x16x32_bf16 v[74:77], v[70:73], v[180:183], v[74:77]
	v_mfma_f32_16x16x32_bf16 v[46:49], v[54:57], v[188:191], v[46:49]
	v_mfma_f32_16x16x32_bf16 v[42:45], v[70:73], v[188:191], v[42:45]
	v_mfma_f32_16x16x32_bf16 v[30:33], v[54:57], v[196:199], v[30:33]
	v_mfma_f32_16x16x32_bf16 v[26:29], v[70:73], v[196:199], v[26:29]
	v_mfma_f32_16x16x32_bf16 v[14:17], v[54:57], v[204:207], v[14:17]
	v_mfma_f32_16x16x32_bf16 v[10:13], v[70:73], v[204:207], v[10:13]
	v_mfma_f32_16x16x32_bf16 v[38:41], v[156:159], v[184:187], v[38:41]
	v_mfma_f32_16x16x32_bf16 v[34:37], v[164:167], v[184:187], v[34:37]
	v_mfma_f32_16x16x32_bf16 v[22:25], v[156:159], v[192:195], v[22:25]
	v_mfma_f32_16x16x32_bf16 v[18:21], v[164:167], v[192:195], v[18:21]
	v_mfma_f32_16x16x32_bf16 v[6:9], v[156:159], v[200:203], v[6:9]
	v_mfma_f32_16x16x32_bf16 v[2:5], v[164:167], v[200:203], v[2:5]
	v_mfma_f32_16x16x32_bf16 v[50:53], v[156:159], v[172:175], v[62:65]
	v_mfma_f32_16x16x32_bf16 v[54:57], v[164:167], v[172:175], v[58:61]
	v_mfma_f32_16x16x32_bf16 v[38:41], v[160:163], v[188:191], v[38:41]
	v_mfma_f32_16x16x32_bf16 v[34:37], v[168:171], v[188:191], v[34:37]
	v_mfma_f32_16x16x32_bf16 v[22:25], v[160:163], v[196:199], v[22:25]
	v_mfma_f32_16x16x32_bf16 v[18:21], v[168:171], v[196:199], v[18:21]
	v_mfma_f32_16x16x32_bf16 v[6:9], v[160:163], v[204:207], v[6:9]
	v_mfma_f32_16x16x32_bf16 v[2:5], v[168:171], v[204:207], v[2:5]
	v_mfma_f32_16x16x32_bf16 v[50:53], v[160:163], v[180:183], v[50:53]
	v_mfma_f32_16x16x32_bf16 v[54:57], v[168:171], v[180:183], v[54:57]
	s_barrier
	s_setprio 0
	s_add_i32 s66, 0, 0x18000
	s_add_i32 s67, 0, 0x1c000
	s_add_u32 s38, s38, 0x80000
	s_addc_u32 s39, s39, 0
	s_mov_b32 m0, s45
	v_lshl_add_u64 v[220:221], s[38:39], 0, v[146:147]
	global_load_lds_dwordx4 v[220:221], off
	v_lshl_add_u64 v[220:221], s[38:39], 0, v[148:149]
	s_mov_b32 m0, s46
	s_nop 0
	global_load_lds_dwordx4 v[220:221], off
	v_add_u32_e32 v70, s66, v213
	v_add_u32_e32 v168, s67, v213
	ds_read_b128 v[58:61], v70
	ds_read_b128 v[62:65], v70 offset:1024
	ds_read_b128 v[66:69], v70 offset:2048
	ds_read_b128 v[70:73], v70 offset:3072
	ds_read_b128 v[156:159], v168
	ds_read_b128 v[160:163], v168 offset:1024
	ds_read_b128 v[164:167], v168 offset:2048
	ds_read_b128 v[168:171], v168 offset:3072
	ds_read_b128 v[172:175], v215 offset:32768
	ds_read_b128 v[180:183], v215 offset:33792
	ds_read_b128 v[184:187], v215 offset:34816
	ds_read_b128 v[188:191], v215 offset:35840
	ds_read_b128 v[192:195], v215 offset:36864
	ds_read_b128 v[196:199], v215 offset:37888
	ds_read_b128 v[200:203], v215 offset:38912
	ds_read_b128 v[204:207], v215 offset:39936
	s_waitcnt vmcnt(8)
	s_waitcnt lgkmcnt(0)
	s_setprio 1
	s_barrier
	v_mfma_f32_16x16x32_bf16 v[142:145], v[58:61], v[172:175], v[142:145]
	v_mfma_f32_16x16x32_bf16 v[138:141], v[66:69], v[172:175], v[138:141]
	v_mfma_f32_16x16x32_bf16 v[126:129], v[58:61], v[184:187], v[126:129]
	v_mfma_f32_16x16x32_bf16 v[122:125], v[66:69], v[184:187], v[122:125]
	v_mfma_f32_16x16x32_bf16 v[110:113], v[58:61], v[192:195], v[110:113]
	v_mfma_f32_16x16x32_bf16 v[106:109], v[66:69], v[192:195], v[106:109]
	v_mfma_f32_16x16x32_bf16 v[94:97], v[58:61], v[200:203], v[94:97]
	v_mfma_f32_16x16x32_bf16 v[90:93], v[66:69], v[200:203], v[90:93]
	v_mfma_f32_16x16x32_bf16 v[142:145], v[62:65], v[180:183], v[142:145]
	v_mfma_f32_16x16x32_bf16 v[138:141], v[70:73], v[180:183], v[138:141]
	v_mfma_f32_16x16x32_bf16 v[126:129], v[62:65], v[188:191], v[126:129]
	v_mfma_f32_16x16x32_bf16 v[122:125], v[70:73], v[188:191], v[122:125]
	v_mfma_f32_16x16x32_bf16 v[110:113], v[62:65], v[196:199], v[110:113]
	v_mfma_f32_16x16x32_bf16 v[106:109], v[70:73], v[196:199], v[106:109]
	v_mfma_f32_16x16x32_bf16 v[94:97], v[62:65], v[204:207], v[94:97]
	v_mfma_f32_16x16x32_bf16 v[90:93], v[70:73], v[204:207], v[90:93]
	v_mfma_f32_16x16x32_bf16 v[134:137], v[156:159], v[172:175], v[134:137]
	v_mfma_f32_16x16x32_bf16 v[130:133], v[164:167], v[172:175], v[130:133]
	v_mfma_f32_16x16x32_bf16 v[118:121], v[156:159], v[184:187], v[118:121]
	v_mfma_f32_16x16x32_bf16 v[114:117], v[164:167], v[184:187], v[114:117]
	v_mfma_f32_16x16x32_bf16 v[102:105], v[156:159], v[192:195], v[102:105]
	v_mfma_f32_16x16x32_bf16 v[98:101], v[164:167], v[192:195], v[98:101]
	v_mfma_f32_16x16x32_bf16 v[86:89], v[156:159], v[200:203], v[86:89]
	v_mfma_f32_16x16x32_bf16 v[82:85], v[164:167], v[200:203], v[82:85]
	v_mfma_f32_16x16x32_bf16 v[134:137], v[160:163], v[180:183], v[134:137]
	v_mfma_f32_16x16x32_bf16 v[130:133], v[168:171], v[180:183], v[130:133]
	v_mfma_f32_16x16x32_bf16 v[118:121], v[160:163], v[188:191], v[118:121]
	v_mfma_f32_16x16x32_bf16 v[114:117], v[168:171], v[188:191], v[114:117]
	v_mfma_f32_16x16x32_bf16 v[102:105], v[160:163], v[196:199], v[102:105]
	v_mfma_f32_16x16x32_bf16 v[98:101], v[168:171], v[196:199], v[98:101]
	v_mfma_f32_16x16x32_bf16 v[86:89], v[160:163], v[204:207], v[86:89]
	v_mfma_f32_16x16x32_bf16 v[82:85], v[168:171], v[204:207], v[82:85]
	s_barrier
; #define PG8_STAGE(bufoff, gbase, voff) do { _Pragma("unroll") for (int _i = 0; _i < 2; ++_i) \
;         __builtin_amdgcn_global_load_lds((const unsigned*)((const char*)(gbase) + (voff)[_i]), (LAS unsigned*)(lds + (bufoff) + ldsw + _i * 8192), 16, 0, 0); } while (0)
; #define PG8_LDA(dst, b, h) do { _Pragma("unroll") for (int m = 0; m < 4; ++m) _Pragma("unroll") for (int k = 0; k < 2; ++k) dst[m][k] = *(const LAS bf16x8*)(lds + PG8_SA(b, h) + aoff + m * 2048 + k * 1024); } while (0)
; #define PG8_MMA(ai, bj, At, Bt) do { __builtin_amdgcn_s_setprio(1); _Pragma("unroll") for (int m = 0; m < 4; ++m) _Pragma("unroll") for (int n = 0; n < 2; ++n) _Pragma("unroll") for (int k = 0; k < 2; ++k) \
;         acc[ai][bj][m][n] = __builtin_amdgcn_mfma_f32_16x16x32_bf16(Bt[n][k], At[m][k], acc[ai][bj][m][n], 0, 0, 0); __builtin_amdgcn_s_setprio(0); } while (0)
; #define PG8_WAIT_V(n) asm volatile("s_waitcnt vmcnt(" #n ")" ::: "memory")
; #define PG8_WAIT_L(n) asm volatile("s_waitcnt lgkmcnt(" #n ")" ::: "memory")
; #define PG8_BAR __builtin_amdgcn_s_barrier()
; #define PG8_SCHED __builtin_amdgcn_sched_barrier(0)
; template <class Epi, class Sched, int LDA, int LDB, bool ALIGN_EPI = true>
; __device__ __forceinline__ void gemm_phase(LAS unsigned char* lds, const Gemm g, const Sched& S, const Epi& E, int wave) {
;     ...
;             PG8_LDA(At, 1, 1); PG8_STAGE(PG8_SB(1, 0), b3, voffB); PG8_STAGE(PG8_SB(1, 1), b3 + hstepB, voffB); PG8_STAGE(PG8_SA(1, 0), a3, voffA);
;             PG8_WAIT_V(8); PG8_WAIT_L(0); PG8_BAR; PG8_MMA(1, 0, At, B0); PG8_MMA(1, 1, At, B1); PG8_BAR; PG8_SCHED;
;         }
;         if constexpr (ALIGN_EPI) { if (wr == 0) PG8_BAR; }
	s_setprio 0
	s_add_i32 s38, s66, s60
	v_lshl_add_u64 v[208:209], v[208:209], 0, s[70:71]
	s_mov_b32 m0, s38
	s_nop 0
	global_load_lds_dwordx4 v[208:209], off
	s_add_i32 m0, s38, 0x2000
	s_add_u32 s36, s36, 0x80080
	v_lshl_add_u64 v[208:209], v[210:211], 0, s[70:71]
	s_addc_u32 s37, s37, 0
	s_add_i32 s38, s67, s60
	global_load_lds_dwordx4 v[208:209], off
	v_lshl_add_u64 v[208:209], s[36:37], 0, v[0:1]
	s_mov_b32 m0, s38
	s_nop 0
	global_load_lds_dwordx4 v[208:209], off
	v_lshl_add_u64 v[208:209], s[36:37], 0, v[150:151]
	s_add_i32 m0, s38, 0x2000
	s_nop 0
	global_load_lds_dwordx4 v[208:209], off
	v_lshl_add_u64 v[208:209], v[216:217], 0, s[70:71]
	s_mov_b32 m0, s51
	s_nop 0
	global_load_lds_dwordx4 v[208:209], off
	v_lshl_add_u64 v[208:209], v[218:219], 0, s[70:71]
	s_mov_b32 m0, s52
	s_nop 0
	global_load_lds_dwordx4 v[208:209], off
	ds_read_b128 v[172:175], v215 offset:49152
	ds_read_b128 v[180:183], v215 offset:50176
	ds_read_b128 v[184:187], v215 offset:51200
	ds_read_b128 v[188:191], v215 offset:52224
	ds_read_b128 v[192:195], v215 offset:53248
	ds_read_b128 v[196:199], v215 offset:54272
	ds_read_b128 v[200:203], v215 offset:55296
	ds_read_b128 v[204:207], v215 offset:56320
	s_waitcnt vmcnt(8)
	s_waitcnt lgkmcnt(0)
	s_setprio 1
	s_barrier
	v_mfma_f32_16x16x32_bf16 v[78:81], v[58:61], v[172:175], v[78:81]
	v_mfma_f32_16x16x32_bf16 v[74:77], v[66:69], v[172:175], v[74:77]
	v_mfma_f32_16x16x32_bf16 v[46:49], v[58:61], v[184:187], v[46:49]
	v_mfma_f32_16x16x32_bf16 v[42:45], v[66:69], v[184:187], v[42:45]
	v_mfma_f32_16x16x32_bf16 v[30:33], v[58:61], v[192:195], v[30:33]
	v_mfma_f32_16x16x32_bf16 v[26:29], v[66:69], v[192:195], v[26:29]
	v_mfma_f32_16x16x32_bf16 v[14:17], v[58:61], v[200:203], v[14:17]
	v_mfma_f32_16x16x32_bf16 v[10:13], v[66:69], v[200:203], v[10:13]
	v_mfma_f32_16x16x32_bf16 v[78:81], v[62:65], v[180:183], v[78:81]
	v_mfma_f32_16x16x32_bf16 v[74:77], v[70:73], v[180:183], v[74:77]
	v_mfma_f32_16x16x32_bf16 v[46:49], v[62:65], v[188:191], v[46:49]
	v_mfma_f32_16x16x32_bf16 v[42:45], v[70:73], v[188:191], v[42:45]
	v_mfma_f32_16x16x32_bf16 v[30:33], v[62:65], v[196:199], v[30:33]
	v_mfma_f32_16x16x32_bf16 v[26:29], v[70:73], v[196:199], v[26:29]
	v_mfma_f32_16x16x32_bf16 v[14:17], v[62:65], v[204:207], v[14:17]
	v_mfma_f32_16x16x32_bf16 v[10:13], v[70:73], v[204:207], v[10:13]
	v_mfma_f32_16x16x32_bf16 v[50:53], v[156:159], v[172:175], v[50:53]
	v_mfma_f32_16x16x32_bf16 v[62:65], v[160:163], v[180:183], v[50:53]
	v_mfma_f32_16x16x32_bf16 v[50:53], v[164:167], v[172:175], v[54:57]
	v_mfma_f32_16x16x32_bf16 v[38:41], v[156:159], v[184:187], v[38:41]
	v_mfma_f32_16x16x32_bf16 v[34:37], v[164:167], v[184:187], v[34:37]
	v_mfma_f32_16x16x32_bf16 v[22:25], v[156:159], v[192:195], v[22:25]
	v_mfma_f32_16x16x32_bf16 v[18:21], v[164:167], v[192:195], v[18:21]
	v_mfma_f32_16x16x32_bf16 v[6:9], v[156:159], v[200:203], v[6:9]
	v_mfma_f32_16x16x32_bf16 v[2:5], v[164:167], v[200:203], v[2:5]
	v_mfma_f32_16x16x32_bf16 v[58:61], v[168:171], v[180:183], v[50:53]
	v_mfma_f32_16x16x32_bf16 v[38:41], v[160:163], v[188:191], v[38:41]
	v_mfma_f32_16x16x32_bf16 v[34:37], v[168:171], v[188:191], v[34:37]
	v_mfma_f32_16x16x32_bf16 v[22:25], v[160:163], v[196:199], v[22:25]
	v_mfma_f32_16x16x32_bf16 v[18:21], v[168:171], v[196:199], v[18:21]
	v_mfma_f32_16x16x32_bf16 v[6:9], v[160:163], v[204:207], v[6:9]
	v_mfma_f32_16x16x32_bf16 v[2:5], v[168:171], v[204:207], v[2:5]
	s_barrier
	s_setprio 0
	s_add_u32 s34, s34, 0x100
	s_addc_u32 s35, s35, 0
	s_add_u32 s59, s59, 0x100
	s_addc_u32 s64, s64, 0
	s_cmp_ge_i32 s65, s43
	s_mov_b32 s36, s65
	s_cbranch_scc0 .LBB0_4901
	v_readlane_b32 s34, v252, 14
	v_readlane_b32 s35, v252, 15
	s_and_b64 vcc, exec, s[34:35]
	s_cbranch_vccz .LBB0_4904
	s_barrier
